# speedup vs baseline: 1.0180x; 1.0027x over previous
; #define GM_LOAD(KOFF) GM_LOAD2(KOFF, 0)
;     ...
;   const u16* bp0 = Bt + (size_t)lr * ldb + kc * 8;
;   const size_t bstep = 32 * ldb;
;   const int so = lr * LSTR + kc * 16;
;   uint4 ra0, ra1, ra2, ra3, rb0, rb1, rb2, rb3;
;     ...
;   GM_LOAD(0)
;   GM_STORE(smem)
;   __syncthreads();
;   const int nk = K >> 6;
;   const int aoff = (wm * 64 + (lane & 31)) * LSTR + (lane >> 5) * 16;
;   const int boff = (wn * 64 + (lane & 31)) * LSTR + (lane >> 5) * 16;
;   for (int kt = 0; kt < nk; ++kt) {
;     const int kn = (kt + 1 < nk) ? kt + 1 : kt;
;     GM_LOAD2(kn * 64, kn * bkstep)
; __device__ __forceinline__ void zero_acc(f32x16 (&acc)[2][2]) {
; #pragma unroll
;   for (int i = 0; i < 2; ++i)
; #pragma unroll
;     for (int j = 0; j < 2; ++j)
; #pragma unroll
;       for (int r = 0; r < 16; ++r) acc[i][j][r] = 0.f;
; }
.LBB0_359:
	s_lshl_b32 s6, s6, s21
	s_xor_b64 s[12:13], s[12:13], -1
	s_lshl_b64 s[14:15], s[6:7], 1
	s_add_u32 s26, s22, s14
	s_addc_u32 s27, s23, s15
	v_lshl_add_u64 v[2:3], s[26:27], 0, v[132:133]
	v_lshl_add_u64 v[158:159], v[2:3], 0, v[142:143]
	v_lshl_add_u64 v[2:3], s[26:27], 0, v[152:153]
	v_lshl_add_u64 v[166:167], v[146:147], 0, s[14:15]
	v_lshl_add_u64 v[160:161], v[2:3], 0, v[142:143]
	v_lshl_add_u64 v[2:3], s[26:27], 0, v[154:155]
	v_lshl_add_u64 v[168:169], v[166:167], 0, s[10:11]
	v_lshl_add_u64 v[162:163], v[2:3], 0, v[142:143]
	v_lshl_add_u64 v[2:3], s[26:27], 0, v[156:157]
	v_lshl_add_u64 v[170:171], v[168:169], 0, s[10:11]
	v_lshl_add_u64 v[164:165], v[2:3], 0, v[142:143]
	global_load_dwordx4 v[34:37], v[166:167], off
	global_load_dwordx4 v[38:41], v[168:169], off
	v_lshl_add_u64 v[172:173], v[166:167], 0, s[8:9]
	global_load_dwordx4 v[42:45], v[170:171], off
	global_load_dwordx4 v[46:49], v[172:173], off
	global_load_dwordx4 v[174:177], v[158:159], off
	global_load_dwordx4 v[178:181], v[160:161], off
	global_load_dwordx4 v[182:185], v[162:163], off
	global_load_dwordx4 v[186:189], v[164:165], off
	v_mov_b32_e32 v2, 0
	s_mov_b32 s14, 0
	s_mov_b32 s15, s24
	s_add_i32 s15, s15, -1
	s_mov_b32 s6, 64
	v_mov_b32_e32 v3, v2
	v_mov_b32_e32 v4, v2
	v_mov_b32_e32 v5, v2
	v_mov_b32_e32 v6, v2
	v_mov_b32_e32 v7, v2
	v_mov_b32_e32 v8, v2
	v_mov_b32_e32 v9, v2
	v_mov_b32_e32 v10, v2
	v_mov_b32_e32 v11, v2
	v_mov_b32_e32 v12, v2
	v_mov_b32_e32 v13, v2
	v_mov_b32_e32 v14, v2
	v_mov_b32_e32 v15, v2
	v_mov_b32_e32 v16, v2
	v_mov_b32_e32 v17, v2
	v_mov_b32_e32 v18, v2
	v_mov_b32_e32 v19, v2
	v_mov_b32_e32 v20, v2
	v_mov_b32_e32 v21, v2
	v_mov_b32_e32 v22, v2
	v_mov_b32_e32 v23, v2
	v_mov_b32_e32 v24, v2
	v_mov_b32_e32 v25, v2
	v_mov_b32_e32 v26, v2
	v_mov_b32_e32 v27, v2
	v_mov_b32_e32 v28, v2
	v_mov_b32_e32 v29, v2
	v_mov_b32_e32 v30, v2
	v_mov_b32_e32 v31, v2
	v_mov_b32_e32 v32, v2
	v_mov_b32_e32 v33, v2
	v_mov_b32_e32 v50, v2
	v_mov_b32_e32 v51, v2
	v_mov_b32_e32 v52, v2
	v_mov_b32_e32 v53, v2
	v_mov_b32_e32 v54, v2
	v_mov_b32_e32 v55, v2
	v_mov_b32_e32 v56, v2
	v_mov_b32_e32 v57, v2
	v_mov_b32_e32 v58, v2
	v_mov_b32_e32 v59, v2
	v_mov_b32_e32 v60, v2
	v_mov_b32_e32 v61, v2
	v_mov_b32_e32 v62, v2
	v_mov_b32_e32 v63, v2
	v_mov_b32_e32 v64, v2
	v_mov_b32_e32 v65, v2
	s_waitcnt vmcnt(7)
	ds_write_b128 v190, v[34:37] offset:18432
	s_waitcnt vmcnt(6)
	ds_write_b128 v190, v[38:41] offset:23040
	s_waitcnt vmcnt(5)
	ds_write_b128 v190, v[42:45] offset:27648
	s_waitcnt vmcnt(4)
	ds_write_b128 v190, v[46:49] offset:32256
	s_waitcnt vmcnt(3)
	ds_write_b128 v190, v[174:177]
	s_waitcnt vmcnt(2)
	ds_write_b128 v190, v[178:181] offset:4608
	s_waitcnt vmcnt(1)
	ds_write_b128 v190, v[182:185] offset:9216
	s_waitcnt vmcnt(0)
	ds_write_b128 v190, v[186:189] offset:13824
	v_mov_b32_e32 v34, v2
	v_mov_b32_e32 v35, v2
	v_mov_b32_e32 v36, v2
	v_mov_b32_e32 v37, v2
	v_mov_b32_e32 v38, v2
	v_mov_b32_e32 v39, v2
	v_mov_b32_e32 v40, v2
	v_mov_b32_e32 v41, v2
	v_mov_b32_e32 v42, v2
	v_mov_b32_e32 v43, v2
	v_mov_b32_e32 v44, v2
	v_mov_b32_e32 v45, v2
	v_mov_b32_e32 v46, v2
	v_mov_b32_e32 v47, v2
	v_mov_b32_e32 v48, v2
	v_mov_b32_e32 v49, v2
	s_waitcnt lgkmcnt(0)
	s_barrier
	s_lshl_b64 s[26:27], s[6:7], 1
	v_lshl_add_u64 v[174:175], v[158:159], 0, s[26:27]
	v_lshl_add_u64 v[178:179], v[162:163], 0, s[26:27]
	v_lshl_add_u64 v[182:183], v[166:167], 0, s[26:27]
	v_lshl_add_u64 v[186:187], v[170:171], 0, s[26:27]
	v_lshl_add_u64 v[176:177], v[160:161], 0, s[26:27]
	global_load_dwordx4 v[198:201], v[174:175], off
	global_load_dwordx4 v[202:205], v[176:177], off
	v_lshl_add_u64 v[180:181], v[164:165], 0, s[26:27]
	global_load_dwordx4 v[206:209], v[178:179], off
	global_load_dwordx4 v[210:213], v[180:181], off
	v_lshl_add_u64 v[184:185], v[168:169], 0, s[26:27]
	global_load_dwordx4 v[214:217], v[182:183], off
	global_load_dwordx4 v[218:221], v[184:185], off
	v_lshl_add_u64 v[188:189], v[172:173], 0, s[26:27]
	global_load_dwordx4 v[224:227], v[186:187], off
	global_load_dwordx4 v[228:231], v[188:189], off
.LBB0_360:
	s_and_b32 s25, s14, 2
	s_mulk_i32 s25, 0x4800
	v_add3_u32 v197, s25, v191, v192
	v_add3_u32 v223, s25, v193, v192
	ds_read_b128 v[232:235], v197 offset:0
	ds_read_b128 v[236:239], v223 offset:18432
	ds_read_b128 v[244:247], v197 offset:4608
	ds_read_b128 v[240:243], v223 offset:23040
	s_waitcnt lgkmcnt(2)
	v_mfma_f32_32x32x16_bf16 v[50:65], v[232:235], v[236:239], v[50:65]
	ds_read_b128 v[248:251], v197 offset:32
	s_waitcnt lgkmcnt(2)
	v_mfma_f32_32x32x16_bf16 v[2:17], v[244:247], v[236:239], v[2:17]
	ds_read_b128 v[236:239], v223 offset:18464
	s_waitcnt lgkmcnt(2)
	v_mfma_f32_32x32x16_bf16 v[18:33], v[232:235], v[240:243], v[18:33]
	ds_read_b128 v[232:235], v197 offset:4640
	v_mfma_f32_32x32x16_bf16 v[34:49], v[244:247], v[240:243], v[34:49]
	ds_read_b128 v[240:243], v223 offset:23072
	s_waitcnt lgkmcnt(2)
	v_mfma_f32_32x32x16_bf16 v[50:65], v[248:251], v[236:239], v[50:65]
	ds_read_b128 v[244:247], v197 offset:64
	s_waitcnt lgkmcnt(2)
	v_mfma_f32_32x32x16_bf16 v[2:17], v[232:235], v[236:239], v[2:17]
	ds_read_b128 v[236:239], v223 offset:18496
	s_waitcnt lgkmcnt(2)
	v_mfma_f32_32x32x16_bf16 v[18:33], v[248:251], v[240:243], v[18:33]
	ds_read_b128 v[248:251], v197 offset:4672
	v_mfma_f32_32x32x16_bf16 v[34:49], v[232:235], v[240:243], v[34:49]
	ds_read_b128 v[240:243], v223 offset:23104
	s_waitcnt lgkmcnt(2)
	v_mfma_f32_32x32x16_bf16 v[50:65], v[244:247], v[236:239], v[50:65]
	ds_read_b128 v[232:235], v197 offset:96
	s_waitcnt lgkmcnt(2)
	v_mfma_f32_32x32x16_bf16 v[2:17], v[248:251], v[236:239], v[2:17]
	ds_read_b128 v[236:239], v223 offset:18528
	s_waitcnt lgkmcnt(2)
;     ...
;   for (int kt = 0; kt < nk; ++kt) {
;     const int kn = (kt + 1 < nk) ? kt + 1 : kt;
;     GM_LOAD2(kn * 64, kn * bkstep)
;     __builtin_amdgcn_sched_barrier(0);
;     const char* As = smem + (kt & 1) * 2 * TILE_B;
;     const char* Bs = As + TILE_B;
;     if constexpr (HOIST) {
;       bf16x8 fa0[4], fa1[4], fb0[4], fb1[4];
; #pragma unroll
;       for (int st = 0; st < 4; ++st) {
;         fa0[st] = *(const bf16x8*)(As + aoff + st * 32);
;         fb0[st] = *(const bf16x8*)(Bs + boff + st * 32);
;         fa1[st] = *(const bf16x8*)(As + aoff + 32 * LSTR + st * 32);
;         fb1[st] = *(const bf16x8*)(Bs + boff + 32 * LSTR + st * 32);
;       }
;       __builtin_amdgcn_sched_barrier(0);
; #pragma unroll
;       for (int st = 0; st < 4; ++st) {
;         acc[0][0] = mfma32(fa0[st], fb0[st], acc[0][0]);
;         acc[0][1] = mfma32(fa0[st], fb1[st], acc[0][1]);
;         acc[1][0] = mfma32(fa1[st], fb0[st], acc[1][0]);
;         acc[1][1] = mfma32(fa1[st], fb1[st], acc[1][1]);
;       }
;     } else {
; #pragma unroll
;       for (int st = 0; st < 4; ++st) {
;         bf16x8 a0 = *(const bf16x8*)(As + aoff + st * 32);
;         bf16x8 a1 = *(const bf16x8*)(As + aoff + 32 * LSTR + st * 32);
;         bf16x8 b0 = *(const bf16x8*)(Bs + boff + st * 32);
;         bf16x8 b1 = *(const bf16x8*)(Bs + boff + 32 * LSTR + st * 32);
;         acc[0][0] = mfma32(a0, b0, acc[0][0]);
;         acc[0][1] = mfma32(a0, b1, acc[0][1]);
;         acc[1][0] = mfma32(a1, b0, acc[1][0]);
;         acc[1][1] = mfma32(a1, b1, acc[1][1]);
;       }
;     }
;     __builtin_amdgcn_sched_barrier(0);
;     {
;       char* Ad = smem + ((kt + 1) & 1) * 2 * TILE_B;
;       GM_STORE(Ad)
;     }
;     __syncthreads();
	v_mfma_f32_32x32x16_bf16 v[18:33], v[244:247], v[240:243], v[18:33]
	ds_read_b128 v[244:247], v197 offset:4704
	v_mfma_f32_32x32x16_bf16 v[34:49], v[248:251], v[240:243], v[34:49]
	ds_read_b128 v[240:243], v223 offset:23136
	s_waitcnt lgkmcnt(2)
	v_mfma_f32_32x32x16_bf16 v[50:65], v[232:235], v[236:239], v[50:65]
	s_waitcnt lgkmcnt(1)
	v_mfma_f32_32x32x16_bf16 v[2:17], v[244:247], v[236:239], v[2:17]
	s_waitcnt lgkmcnt(0)
	v_mfma_f32_32x32x16_bf16 v[18:33], v[232:235], v[240:243], v[18:33]
	v_mfma_f32_32x32x16_bf16 v[34:49], v[244:247], v[240:243], v[34:49]
	s_add_i32 s14, s14, 2
	s_and_b32 s25, s14, 2
	s_mulk_i32 s25, 0x4800
	s_add_i32 s15, s15, -1
	s_add_i32 s6, s6, 64
	v_add_u32_e32 v197, s25, v190
	s_lshl_b64 s[26:27], s[6:7], 1
	s_cmp_lg_u32 s15, 0
	s_waitcnt vmcnt(7)
	ds_write_b128 v197, v[198:201]
	v_lshl_add_u64 v[198:199], v[158:159], 0, s[26:27]
	global_load_dwordx4 v[198:201], v[198:199], off
	s_waitcnt vmcnt(7)
	ds_write_b128 v197, v[202:205] offset:4608
	v_lshl_add_u64 v[202:203], v[160:161], 0, s[26:27]
	global_load_dwordx4 v[202:205], v[202:203], off
	s_waitcnt vmcnt(7)
	ds_write_b128 v197, v[206:209] offset:9216
	v_lshl_add_u64 v[206:207], v[162:163], 0, s[26:27]
	global_load_dwordx4 v[206:209], v[206:207], off
	s_waitcnt vmcnt(7)
	ds_write_b128 v197, v[210:213] offset:13824
	v_lshl_add_u64 v[210:211], v[164:165], 0, s[26:27]
	global_load_dwordx4 v[210:213], v[210:211], off
	s_waitcnt vmcnt(7)
	ds_write_b128 v197, v[214:217] offset:18432
	v_lshl_add_u64 v[214:215], v[166:167], 0, s[26:27]
	global_load_dwordx4 v[214:217], v[214:215], off
	s_waitcnt vmcnt(7)
	ds_write_b128 v197, v[218:221] offset:23040
	v_lshl_add_u64 v[218:219], v[168:169], 0, s[26:27]
	global_load_dwordx4 v[218:221], v[218:219], off
	s_waitcnt vmcnt(7)
	ds_write_b128 v197, v[224:227] offset:27648
	v_lshl_add_u64 v[224:225], v[170:171], 0, s[26:27]
	global_load_dwordx4 v[224:227], v[224:225], off
	s_waitcnt vmcnt(7)
	ds_write_b128 v197, v[228:231] offset:32256
	v_lshl_add_u64 v[228:229], v[172:173], 0, s[26:27]
	global_load_dwordx4 v[228:231], v[228:229], off
	s_waitcnt lgkmcnt(0)
	s_barrier
	s_cbranch_scc1 .LBB0_360
	s_and_b32 s25, s14, 2
	s_mulk_i32 s25, 0x4800
	v_add3_u32 v197, s25, v191, v192
	v_add3_u32 v223, s25, v193, v192
	ds_read_b128 v[232:235], v197 offset:0
	ds_read_b128 v[236:239], v223 offset:18432
	ds_read_b128 v[244:247], v197 offset:4608
	ds_read_b128 v[240:243], v223 offset:23040
	s_waitcnt lgkmcnt(2)
	v_mfma_f32_32x32x16_bf16 v[50:65], v[232:235], v[236:239], v[50:65]
	ds_read_b128 v[248:251], v197 offset:32
	s_waitcnt lgkmcnt(2)
	v_mfma_f32_32x32x16_bf16 v[2:17], v[244:247], v[236:239], v[2:17]
	ds_read_b128 v[236:239], v223 offset:18464
	s_waitcnt lgkmcnt(2)
	v_mfma_f32_32x32x16_bf16 v[18:33], v[232:235], v[240:243], v[18:33]
	ds_read_b128 v[232:235], v197 offset:4640
	v_mfma_f32_32x32x16_bf16 v[34:49], v[244:247], v[240:243], v[34:49]
	ds_read_b128 v[240:243], v223 offset:23072
	s_waitcnt lgkmcnt(2)
	v_mfma_f32_32x32x16_bf16 v[50:65], v[248:251], v[236:239], v[50:65]
	ds_read_b128 v[244:247], v197 offset:64
	s_waitcnt lgkmcnt(2)
	v_mfma_f32_32x32x16_bf16 v[2:17], v[232:235], v[236:239], v[2:17]
	ds_read_b128 v[236:239], v223 offset:18496
	s_waitcnt lgkmcnt(2)
	v_mfma_f32_32x32x16_bf16 v[18:33], v[248:251], v[240:243], v[18:33]
	ds_read_b128 v[248:251], v197 offset:4672
	v_mfma_f32_32x32x16_bf16 v[34:49], v[232:235], v[240:243], v[34:49]
	ds_read_b128 v[240:243], v223 offset:23104
	s_waitcnt lgkmcnt(2)
	v_mfma_f32_32x32x16_bf16 v[50:65], v[244:247], v[236:239], v[50:65]
	ds_read_b128 v[232:235], v197 offset:96
	s_waitcnt lgkmcnt(2)
	v_mfma_f32_32x32x16_bf16 v[2:17], v[248:251], v[236:239], v[2:17]
	ds_read_b128 v[236:239], v223 offset:18528
	s_waitcnt lgkmcnt(2)
	v_mfma_f32_32x32x16_bf16 v[18:33], v[244:247], v[240:243], v[18:33]
	ds_read_b128 v[244:247], v197 offset:4704
	v_mfma_f32_32x32x16_bf16 v[34:49], v[248:251], v[240:243], v[34:49]
	ds_read_b128 v[240:243], v223 offset:23136
	s_waitcnt lgkmcnt(2)
	v_mfma_f32_32x32x16_bf16 v[50:65], v[232:235], v[236:239], v[50:65]
	s_waitcnt lgkmcnt(1)
	v_mfma_f32_32x32x16_bf16 v[2:17], v[244:247], v[236:239], v[2:17]
	s_waitcnt lgkmcnt(0)
	v_mfma_f32_32x32x16_bf16 v[18:33], v[232:235], v[240:243], v[18:33]
	v_mfma_f32_32x32x16_bf16 v[34:49], v[244:247], v[240:243], v[34:49]
	s_add_i32 s14, s14, 2
	s_and_b32 s25, s14, 2
	s_mulk_i32 s25, 0x4800
	s_add_i32 s6, s6, 64
	v_add_u32_e32 v197, s25, v190
	s_waitcnt vmcnt(7)
	ds_write_b128 v197, v[198:201]
	s_waitcnt vmcnt(6)
	ds_write_b128 v197, v[202:205] offset:4608
	s_waitcnt vmcnt(5)
	ds_write_b128 v197, v[206:209] offset:9216
	s_waitcnt vmcnt(4)
	ds_write_b128 v197, v[210:213] offset:13824
	s_waitcnt vmcnt(3)
	ds_write_b128 v197, v[214:217] offset:18432
	s_waitcnt vmcnt(2)
	ds_write_b128 v197, v[218:221] offset:23040
	s_waitcnt vmcnt(1)
	ds_write_b128 v197, v[224:227] offset:27648
	s_waitcnt vmcnt(0)
	ds_write_b128 v197, v[228:231] offset:32256
	s_waitcnt lgkmcnt(0)
	s_barrier
; __device__ __forceinline__ void acc_to_lds(const f32x16 (&acc)[2][2], float* cs) {
;   const int tid = threadIdx.x, lane = tid & 63, wave = tid >> 6;
;   const int wm = wave >> 1, wn = wave & 1;
; #pragma unroll
;   for (int i = 0; i < 2; ++i)
; #pragma unroll
;     for (int j = 0; j < 2; ++j)
; #pragma unroll
;       for (int r = 0; r < 16; ++r) {
;         int row = wm * 64 + i * 32 + (r & 3) + 8 * (r >> 2) + 4 * (lane >> 5);
;         int col = wn * 64 + j * 32 + (lane & 31);
;         cs[row * CSTR + col] = acc[i][j][r];
;       }
;   __syncthreads();
; __device__ __forceinline__ void fourier_half_tile(const Params& P, bool isctx, int b, int mt, int nt, char* smem) {
;     ...
;     } else {
;       u16* d1 = WSP(u16, OFF_FTO) + (rowbase + k) * 256 + nt * 128 + half * 64;
;       u16* d2 = WSP(u16, OFF_FTO) + (rowbase + (k > 0 ? N - k : 0)) * 256 + nt * 128 + half * 64;
; #pragma unroll
;       for (int q = 0; q < 8; ++q) {
;         float4 a = *(const float4*)(cs + r * CSTR + half * 64 + q * 8);
;         float4 c = *(const float4*)(cs + r * CSTR + half * 64 + q * 8 + 4);
;         uint4 o1, o2;
;         o1.x = pack2(pacc[q * 8 + 0] + a.x, pacc[q * 8 + 1] + a.y); o1.y = pack2(pacc[q * 8 + 2] + a.z, pacc[q * 8 + 3] + a.w);
;         o1.z = pack2(pacc[q * 8 + 4] + c.x, pacc[q * 8 + 5] + c.y); o1.w = pack2(pacc[q * 8 + 6] + c.z, pacc[q * 8 + 7] + c.w);
;         o2.x = pack2(pacc[q * 8 + 0] - a.x, pacc[q * 8 + 1] - a.y); o2.y = pack2(pacc[q * 8 + 2] - a.z, pacc[q * 8 + 3] - a.w);
;         o2.z = pack2(pacc[q * 8 + 4] - c.x, pacc[q * 8 + 5] - c.y); o2.w = pack2(pacc[q * 8 + 6] - c.z, pacc[q * 8 + 7] - c.w);
;         *(uint4*)(d1 + q * 8) = o1;
;         if (k > 0) *(uint4*)(d2 + q * 8) = o2;
	s_nop 0
	s_nop 0
	s_nop 0
	v_add3_u32 v197, s25, v191, v192
	v_add3_u32 v223, s25, v193, v192
	ds_read_b128 v[198:201], v197 offset:0
	ds_read_b128 v[202:205], v223 offset:18432
	ds_read_b128 v[210:213], v197 offset:4608
	ds_read_b128 v[206:209], v223 offset:23040
	s_waitcnt lgkmcnt(2)
	v_mfma_f32_32x32x16_bf16 v[50:65], v[198:201], v[202:205], v[50:65]
	ds_read_b128 v[214:217], v197 offset:32
	s_waitcnt lgkmcnt(2)
	v_mfma_f32_32x32x16_bf16 v[2:17], v[210:213], v[202:205], v[2:17]
	ds_read_b128 v[202:205], v223 offset:18464
	s_waitcnt lgkmcnt(2)
	v_mfma_f32_32x32x16_bf16 v[18:33], v[198:201], v[206:209], v[18:33]
	ds_read_b128 v[198:201], v197 offset:4640
	v_mfma_f32_32x32x16_bf16 v[34:49], v[210:213], v[206:209], v[34:49]
	ds_read_b128 v[206:209], v223 offset:23072
	s_waitcnt lgkmcnt(2)
	v_mfma_f32_32x32x16_bf16 v[50:65], v[214:217], v[202:205], v[50:65]
	ds_read_b128 v[210:213], v197 offset:64
	s_waitcnt lgkmcnt(2)
	v_mfma_f32_32x32x16_bf16 v[2:17], v[198:201], v[202:205], v[2:17]
	ds_read_b128 v[202:205], v223 offset:18496
	s_waitcnt lgkmcnt(2)
	v_mfma_f32_32x32x16_bf16 v[18:33], v[214:217], v[206:209], v[18:33]
	ds_read_b128 v[214:217], v197 offset:4672
	v_mfma_f32_32x32x16_bf16 v[34:49], v[198:201], v[206:209], v[34:49]
	ds_read_b128 v[206:209], v223 offset:23104
	s_waitcnt lgkmcnt(2)
	v_mfma_f32_32x32x16_bf16 v[50:65], v[210:213], v[202:205], v[50:65]
	ds_read_b128 v[198:201], v197 offset:96
	s_waitcnt lgkmcnt(2)
	v_mfma_f32_32x32x16_bf16 v[2:17], v[214:217], v[202:205], v[2:17]
	ds_read_b128 v[202:205], v223 offset:18528
	s_waitcnt lgkmcnt(2)
	v_mfma_f32_32x32x16_bf16 v[18:33], v[210:213], v[206:209], v[18:33]
	ds_read_b128 v[210:213], v197 offset:4704
	v_mfma_f32_32x32x16_bf16 v[34:49], v[214:217], v[206:209], v[34:49]
	ds_read_b128 v[206:209], v223 offset:23136
	s_waitcnt lgkmcnt(2)
	v_mfma_f32_32x32x16_bf16 v[50:65], v[198:201], v[202:205], v[50:65]
	s_waitcnt lgkmcnt(1)
	v_mfma_f32_32x32x16_bf16 v[2:17], v[210:213], v[202:205], v[2:17]
	s_waitcnt lgkmcnt(0)
	v_mfma_f32_32x32x16_bf16 v[18:33], v[198:201], v[206:209], v[18:33]
	v_mfma_f32_32x32x16_bf16 v[34:49], v[210:213], v[206:209], v[34:49]
	s_waitcnt lgkmcnt(0)
	s_barrier
	ds_write2_b32 v194, v50, v18 offset1:32
	ds_write2_b32 v194, v51, v19 offset0:132 offset1:164
	v_add_u32_e32 v18, 0x400, v194
	ds_write2_b32 v18, v52, v20 offset0:8 offset1:40
	ds_write2_b32 v18, v53, v21 offset0:140 offset1:172
	v_add_u32_e32 v18, 0x1000, v194
	ds_write2_b32 v18, v54, v22 offset0:32 offset1:64
	ds_write2_b32 v18, v55, v23 offset0:164 offset1:196
	v_add_u32_e32 v18, 0x1400, v194
	ds_write2_b32 v18, v56, v24 offset0:40 offset1:72
	ds_write2_b32 v18, v57, v25 offset0:172 offset1:204
	v_add_u32_e32 v18, 0x2000, v194
	ds_write2_b32 v18, v58, v26 offset0:64 offset1:96
	ds_write2_b32 v18, v59, v27 offset0:196 offset1:228
	v_add_u32_e32 v18, 0x2400, v194
	ds_write2_b32 v18, v60, v28 offset0:72 offset1:104
	ds_write2_b32 v18, v61, v29 offset0:204 offset1:236
	v_add_u32_e32 v18, 0x3000, v194
	ds_write2_b32 v18, v62, v30 offset0:96 offset1:128
	v_add_u32_e32 v18, 0x3200, v194
	ds_write2_b32 v18, v63, v31 offset0:100 offset1:132
	v_add_u32_e32 v18, 0x3400, v194
	ds_write2_b32 v18, v64, v32 offset0:104 offset1:136
	v_add_u32_e32 v18, 0x3600, v194
	ds_write2_b32 v18, v65, v33 offset0:108 offset1:140
	v_add_u32_e32 v18, 0x4000, v194
	ds_write2_b32 v18, v2, v34 offset0:128 offset1:160
	v_add_u32_e32 v2, 0x4400, v194
	ds_write2_b32 v2, v3, v35 offset0:4 offset1:36
	ds_write2_b32 v2, v4, v36 offset0:136 offset1:168
	v_add_u32_e32 v2, 0x4800, v194
	ds_write2_b32 v2, v5, v37 offset0:12 offset1:44
	v_add_u32_e32 v2, 0x5000, v194
	ds_write2_b32 v2, v6, v38 offset0:160 offset1:192
	v_add_u32_e32 v2, 0x5400, v194
	ds_write2_b32 v2, v7, v39 offset0:36 offset1:68
	ds_write2_b32 v2, v8, v40 offset0:168 offset1:200
	v_add_u32_e32 v2, 0x5800, v194
	ds_write2_b32 v2, v9, v41 offset0:44 offset1:76
	v_add_u32_e32 v2, 0x6000, v194
	ds_write2_b32 v2, v10, v42 offset0:192 offset1:224
	v_add_u32_e32 v2, 0x6400, v194
	ds_write2_b32 v2, v11, v43 offset0:68 offset1:100
	ds_write2_b32 v2, v12, v44 offset0:200 offset1:232
	v_add_u32_e32 v2, 0x6800, v194
	ds_write2_b32 v2, v13, v45 offset0:76 offset1:108
	v_add_u32_e32 v2, 0x7200, v194
	ds_write2_b32 v2, v14, v46 offset0:96 offset1:128
	v_add_u32_e32 v2, 0x7400, v194
	ds_write2_b32 v2, v15, v47 offset0:100 offset1:132
	v_add_u32_e32 v2, 0x7600, v194
	ds_write2_b32 v2, v16, v48 offset0:104 offset1:136
	v_add_u32_e32 v2, 0x7800, v194
	s_mov_b64 s[14:15], -1
	s_and_b64 vcc, exec, s[12:13]
	ds_write2_b32 v2, v17, v49 offset0:108 offset1:140
	s_waitcnt lgkmcnt(0)
	s_barrier
	s_cbranch_vccz .LBB0_379
	ds_read_b128 v[2:5], v195
	ds_read_b128 v[6:9], v195 offset:16
	s_waitcnt lgkmcnt(1)
	v_add_f32_e32 v10, v78, v2
	v_add_f32_e32 v11, v79, v3
	v_sub_f32_e32 v2, v78, v2
	v_sub_f32_e32 v3, v79, v3
	v_add_f32_e32 v12, v80, v4
	v_add_f32_e32 v13, v81, v5
	v_cvt_pk_bf16_f32 v2, v2, v3
	v_sub_f32_e32 v3, v80, v4
	v_sub_f32_e32 v4, v81, v5
	v_cvt_pk_bf16_f32 v10, v10, v11
	v_cvt_pk_bf16_f32 v11, v12, v13
	s_waitcnt lgkmcnt(0)
	v_add_f32_e32 v12, v74, v6
	v_add_f32_e32 v13, v75, v7
	v_cvt_pk_bf16_f32 v3, v3, v4
	v_sub_f32_e32 v4, v74, v6
	v_sub_f32_e32 v5, v75, v7
	v_cvt_pk_bf16_f32 v12, v12, v13
	v_add_f32_e32 v13, v76, v8
	v_cvt_pk_bf16_f32 v4, v4, v5
	v_sub_f32_e32 v5, v76, v8
	v_add_f32_e32 v14, v77, v9
	v_cvt_pk_bf16_f32 v13, v13, v14
	v_sub_f32_e32 v6, v77, v9
	v_cvt_pk_bf16_f32 v5, v5, v6
	global_store_dwordx4 v[148:149], v[10:13], off
	s_and_saveexec_b64 s[14:15], s[2:3]
	s_cbranch_execz .LBB0_364
	global_store_dwordx4 v[150:151], v[2:5], off

; #define GM_LOAD(KOFF) GM_LOAD2(KOFF, 0)
;     ...
;   const int lr = tid >> 3, kc = tid & 7;
;   const u16* ap0 = arow(lr) + kc * 8;
;   const u16* ap1 = arow(lr + 32) + kc * 8;
;   const u16* ap2 = arow(lr + 64) + kc * 8;
;   const u16* ap3 = arow(lr + 96) + kc * 8;
;   const u16* bp0 = Bt + (size_t)lr * ldb + kc * 8;
;   const size_t bstep = 32 * ldb;
;   const int so = lr * LSTR + kc * 16;
;   uint4 ra0, ra1, ra2, ra3, rb0, rb1, rb2, rb3;
;     ...
;   GM_LOAD(0)
;   GM_STORE(smem)
;   __syncthreads();
;   const int nk = K >> 6;
;   const int aoff = (wm * 64 + (lane & 31)) * LSTR + (lane >> 5) * 16;
;   const int boff = (wn * 64 + (lane & 31)) * LSTR + (lane >> 5) * 16;
;   for (int kt = 0; kt < nk; ++kt) {
;     const int kn = (kt + 1 < nk) ? kt + 1 : kt;
;     GM_LOAD2(kn * 64, kn * bkstep)
; __device__ __forceinline__ void merge_tile(const Params& P, int l, int mt, int nt, char* smem) {
;     ...
;   for (int br = 0; br < 3; ++br) {
;     f32x16 acc[2][2];
;     zero_acc(acc);
;     const int K = (br == 0) ? 256 : 384;
;     const u16* A = WSP(u16, br == 0 ? OFF_FTO : (br == 1 ? OFF_ONA : OFF_ODF)) + (size_t)mt * 128 * K;
;     const u16* Bt = WSP(u16, br == 0 ? OFF_WFT : (br == 1 ? OFF_WNA : OFF_WDF)) + ((size_t)l * DM + nt * 128) * K;
;     gemm_main<false>([&](int rr) { return A + (size_t)rr * K; }, Bt, K, K, smem, acc);
.LBB0_631:
	s_cmp_eq_u32 s36, 1
	s_cselect_b32 s6, s19, 0x1cdb1100
	s_cselect_b32 s37, s20, 0x1980000
	s_cmp_eq_u32 s36, 0
	s_cselect_b32 s42, s21, 0x180
	s_cselect_b32 s43, 0x1e731100, s6
	s_mul_hi_u32 s6, s10, s42
	s_mul_i32 s38, s11, s42
	s_cselect_b32 s37, 0x1700000, s37
	s_add_u32 s40, s90, s43
	s_addc_u32 s41, s91, 0
	s_add_i32 s39, s6, s38
	s_mul_i32 s38, s10, s42
	s_lshl_b64 s[38:39], s[38:39], 1
	s_add_u32 s38, s40, s38
	s_addc_u32 s39, s41, s39
	s_add_u32 s6, s90, s37
	s_mul_hi_i32 s41, s42, s12
	s_mul_i32 s40, s42, s12
	s_addc_u32 s44, s91, 0
	s_lshl_b64 s[40:41], s[40:41], 1
	v_mul_u32_u24_e32 v2, s42, v1
	s_add_u32 s40, s6, s40
	v_lshlrev_b32_e32 v68, 1, v2
	s_addc_u32 s41, s44, s41
	v_lshl_add_u64 v[2:3], s[38:39], 0, v[68:69]
	s_lshl_b32 s6, s42, 6
	v_lshl_add_u64 v[4:5], v[2:3], 0, v[72:73]
	v_lshl_add_u64 v[2:3], v[2:3], 0, s[6:7]
	v_lshl_add_u64 v[6:7], v[2:3], 0, v[72:73]
	v_lshl_add_u64 v[2:3], v[2:3], 0, s[6:7]
	v_lshl_add_u64 v[10:11], v[2:3], 0, v[72:73]
	v_lshl_add_u64 v[2:3], v[2:3], 0, s[6:7]
	v_lshl_add_u64 v[14:15], v[2:3], 0, v[72:73]
	v_lshl_add_u64 v[2:3], s[40:41], 0, v[68:69]
	v_lshl_add_u64 v[18:19], v[2:3], 0, v[72:73]
	v_lshl_add_u64 v[26:27], v[18:19], 0, s[6:7]
	global_load_dwordx4 v[2:5], v[4:5], off
	s_nop 0
	global_load_dwordx4 v[6:9], v[6:7], off
	s_nop 0
	global_load_dwordx4 v[10:13], v[10:11], off
	s_nop 0
	global_load_dwordx4 v[14:17], v[14:15], off
	s_nop 0
	global_load_dwordx4 v[18:21], v[18:19], off
	s_nop 0
	global_load_dwordx4 v[22:25], v[26:27], off
	v_lshl_add_u64 v[26:27], v[26:27], 0, s[6:7]
	v_lshl_add_u64 v[30:31], v[26:27], 0, s[6:7]
	global_load_dwordx4 v[26:29], v[26:27], off
	s_nop 0
	global_load_dwordx4 v[30:33], v[30:31], off
	s_mul_i32 s6, s17, s42
	s_mul_hi_u32 s38, s16, s42
	s_lshr_b32 s56, s42, 6
	s_mul_i32 s39, s16, s42
	s_add_i32 s57, s38, s6
	s_add_i32 s6, s56, -2
	s_mul_i32 s40, s24, s42
	s_mul_hi_u32 s41, s23, s42
	s_add_u32 s38, s43, s39
	s_mul_i32 s44, s23, s42
	s_addc_u32 s39, 0, s57
	s_add_i32 s41, s41, s40
	s_mul_i32 s45, s26, s42
	s_mul_hi_u32 s46, s25, s42
	v_lshl_add_u64 v[146:147], v[70:71], 0, s[38:39]
	s_add_u32 s38, s43, s44
	s_mul_i32 s47, s25, s42
	s_addc_u32 s39, 0, s41
	s_add_i32 s46, s46, s45
	s_mul_i32 s48, s28, s42
	s_mul_hi_u32 s49, s27, s42
	v_lshl_add_u64 v[148:149], v[70:71], 0, s[38:39]
	s_add_u32 s38, s43, s47
	s_mul_i32 s50, s27, s42
	s_addc_u32 s39, 0, s46
	s_add_i32 s49, s49, s48
	s_mul_i32 s51, s15, s42
	s_mul_hi_u32 s52, s14, s42
	v_lshl_add_u64 v[150:151], v[70:71], 0, s[38:39]
	s_add_u32 s38, s43, s50
	s_mul_i32 s53, s14, s42
	s_addc_u32 s39, 0, s49
	s_add_i32 s52, s52, s51
	v_lshl_add_u64 v[152:153], v[70:71], 0, s[38:39]
	s_add_u32 s38, s37, s53
	s_mul_i32 s54, s30, s42
	s_mul_hi_u32 s55, s29, s42
	s_addc_u32 s39, 0, s52
	s_add_i32 s55, s55, s54
	v_lshl_add_u64 v[154:155], v[70:71], 0, s[38:39]
	s_mul_i32 s38, s29, s42
	s_add_u32 s38, s37, s38
	s_addc_u32 s39, 0, s55
	v_lshl_add_u64 v[156:157], v[70:71], 0, s[38:39]
	s_mul_i32 s38, s33, s42
	s_mul_hi_u32 s39, s31, s42
	s_add_i32 s39, s39, s38
	s_mul_i32 s38, s31, s42
	s_add_u32 s38, s37, s38
	s_addc_u32 s39, 0, s39
	v_lshl_add_u64 v[158:159], v[70:71], 0, s[38:39]
	s_mul_i32 s38, s35, s42
	s_mul_hi_u32 s39, s34, s42
	s_add_i32 s39, s39, s38
	s_mul_i32 s38, s34, s42
	s_add_u32 s38, s37, s38
	s_addc_u32 s39, 0, s39
	v_lshl_add_u64 v[160:161], v[70:71], 0, s[38:39]
	s_waitcnt vmcnt(7)
	ds_write_b128 v135, v[2:5]
	s_waitcnt vmcnt(6)
	ds_write_b128 v135, v[6:9] offset:4608
	s_waitcnt vmcnt(3)
	ds_write_b128 v135, v[18:21] offset:18432
	ds_write_b128 v135, v[10:13] offset:9216
	s_waitcnt vmcnt(2)
	ds_write_b128 v135, v[22:25] offset:23040
	ds_write_b128 v135, v[14:17] offset:13824
	s_waitcnt vmcnt(1)
	ds_write_b128 v135, v[26:29] offset:27648
	s_waitcnt vmcnt(0)
	ds_write_b128 v135, v[30:33] offset:32256
	s_mov_b32 s37, 0
	v_mov_b32_e32 v2, 0
	v_mov_b32_e32 v3, v75
	v_mov_b32_e32 v4, v75
	v_mov_b32_e32 v5, v75
	v_mov_b32_e32 v6, v75
	v_mov_b32_e32 v7, v75
	v_mov_b32_e32 v8, v75
	v_mov_b32_e32 v9, v75
	v_mov_b32_e32 v10, v75
	v_mov_b32_e32 v11, v75
	v_mov_b32_e32 v12, v75
	v_mov_b32_e32 v13, v75
	v_mov_b32_e32 v14, v75
	v_mov_b32_e32 v15, v75
	v_mov_b32_e32 v16, v75
	v_mov_b32_e32 v17, v75
	v_mov_b32_e32 v34, 0
	v_mov_b32_e32 v35, v75
	v_mov_b32_e32 v36, v75
	v_mov_b32_e32 v37, v75
	v_mov_b32_e32 v38, v75
	v_mov_b32_e32 v39, v75
	v_mov_b32_e32 v40, v75
	v_mov_b32_e32 v41, v75
	v_mov_b32_e32 v42, v75
	v_mov_b32_e32 v43, v75
	v_mov_b32_e32 v44, v75
	v_mov_b32_e32 v45, v75
	v_mov_b32_e32 v46, v75
	v_mov_b32_e32 v47, v75
	v_mov_b32_e32 v48, v75
	v_mov_b32_e32 v49, v75
	v_mov_b32_e32 v18, 0
	v_mov_b32_e32 v19, v75
	v_mov_b32_e32 v20, v75
	v_mov_b32_e32 v21, v75
	v_mov_b32_e32 v22, v75
	v_mov_b32_e32 v23, v75
	v_mov_b32_e32 v24, v75
	v_mov_b32_e32 v25, v75
	v_mov_b32_e32 v26, v75
	v_mov_b32_e32 v27, v75
	v_mov_b32_e32 v28, v75
	v_mov_b32_e32 v29, v75
	v_mov_b32_e32 v30, v75
	v_mov_b32_e32 v31, v75
	v_mov_b32_e32 v32, v75
	v_mov_b32_e32 v33, v75
	v_mov_b32_e32 v50, 0
	v_mov_b32_e32 v51, v75
	v_mov_b32_e32 v52, v75
	v_mov_b32_e32 v53, v75
	v_mov_b32_e32 v54, v75
	v_mov_b32_e32 v55, v75
	v_mov_b32_e32 v56, v75
	v_mov_b32_e32 v57, v75
	v_mov_b32_e32 v58, v75
	v_mov_b32_e32 v59, v75
	v_mov_b32_e32 v60, v75
	v_mov_b32_e32 v61, v75
	v_mov_b32_e32 v62, v75
	v_mov_b32_e32 v63, v75
	v_mov_b32_e32 v64, v75
	v_mov_b32_e32 v65, v75
	s_waitcnt lgkmcnt(0)
	s_barrier
	v_lshl_add_u64 v[168:169], v[146:147], 0, v[68:69]
	v_lshl_add_u64 v[172:173], v[148:149], 0, v[68:69]
	v_lshl_add_u64 v[176:177], v[150:151], 0, v[68:69]
	v_lshl_add_u64 v[180:181], v[152:153], 0, v[68:69]
	v_lshl_add_u64 v[184:185], v[154:155], 0, v[68:69]
	v_lshl_add_u64 v[188:189], v[156:157], 0, v[68:69]
	v_lshl_add_u64 v[192:193], v[158:159], 0, v[68:69]
	v_lshl_add_u64 v[196:197], v[160:161], 0, v[68:69]
	global_load_dwordx4 v[168:171], v[168:169], off offset:128
	s_nop 0
	global_load_dwordx4 v[172:175], v[172:173], off offset:128
	s_nop 0
	global_load_dwordx4 v[176:179], v[176:177], off offset:128
	s_nop 0
	global_load_dwordx4 v[180:183], v[180:181], off offset:128
	s_nop 0
	global_load_dwordx4 v[184:187], v[184:185], off offset:128
	s_nop 0
	global_load_dwordx4 v[188:191], v[188:189], off offset:128
	s_nop 0
	global_load_dwordx4 v[192:195], v[192:193], off offset:128
	s_nop 0
	global_load_dwordx4 v[196:199], v[196:197], off offset:128
;     ...
;   for (int kt = 0; kt < nk; ++kt) {
;     const int kn = (kt + 1 < nk) ? kt + 1 : kt;
;     GM_LOAD2(kn * 64, kn * bkstep)
;     __builtin_amdgcn_sched_barrier(0);
;     const char* As = smem + (kt & 1) * 2 * TILE_B;
;     const char* Bs = As + TILE_B;
;     if constexpr (HOIST) {
;       bf16x8 fa0[4], fa1[4], fb0[4], fb1[4];
; #pragma unroll
;       for (int st = 0; st < 4; ++st) {
;         fa0[st] = *(const bf16x8*)(As + aoff + st * 32);
;         fb0[st] = *(const bf16x8*)(Bs + boff + st * 32);
;         fa1[st] = *(const bf16x8*)(As + aoff + 32 * LSTR + st * 32);
;         fb1[st] = *(const bf16x8*)(Bs + boff + 32 * LSTR + st * 32);
;       }
;       __builtin_amdgcn_sched_barrier(0);
; #pragma unroll
;       for (int st = 0; st < 4; ++st) {
;         acc[0][0] = mfma32(fa0[st], fb0[st], acc[0][0]);
;         acc[0][1] = mfma32(fa0[st], fb1[st], acc[0][1]);
;         acc[1][0] = mfma32(fa1[st], fb0[st], acc[1][0]);
;         acc[1][1] = mfma32(fa1[st], fb1[st], acc[1][1]);
;       }
;     } else {
; #pragma unroll
;       for (int st = 0; st < 4; ++st) {
;         bf16x8 a0 = *(const bf16x8*)(As + aoff + st * 32);
;         bf16x8 a1 = *(const bf16x8*)(As + aoff + 32 * LSTR + st * 32);
;         bf16x8 b0 = *(const bf16x8*)(Bs + boff + st * 32);
;         bf16x8 b1 = *(const bf16x8*)(Bs + boff + 32 * LSTR + st * 32);
;         acc[0][0] = mfma32(a0, b0, acc[0][0]);
;         acc[0][1] = mfma32(a0, b1, acc[0][1]);
;         acc[1][0] = mfma32(a1, b0, acc[1][0]);
;         acc[1][1] = mfma32(a1, b1, acc[1][1]);
;       }
;     }
;     __builtin_amdgcn_sched_barrier(0);
;     {
;       char* Ad = smem + ((kt + 1) & 1) * 2 * TILE_B;
;       GM_STORE(Ad)
;     }
;     __syncthreads();
.LBB0_632:
	s_and_b32 s38, s37, 2
	s_mulk_i32 s38, 0x4800
	v_add3_u32 v167, s38, v162, v163
	v_add3_u32 v220, s38, v164, v163
	ds_read_b128 v[200:203], v167 offset:0
	ds_read_b128 v[204:207], v220 offset:18432
	ds_read_b128 v[212:215], v167 offset:4608
	ds_read_b128 v[208:211], v220 offset:23040
	s_waitcnt lgkmcnt(2)
	v_mfma_f32_32x32x16_bf16 v[34:49], v[200:203], v[204:207], v[34:49]
	ds_read_b128 v[216:219], v167 offset:32
	s_waitcnt lgkmcnt(2)
	v_mfma_f32_32x32x16_bf16 v[18:33], v[212:215], v[204:207], v[18:33]
	ds_read_b128 v[204:207], v220 offset:18464
	s_waitcnt lgkmcnt(2)
	v_mfma_f32_32x32x16_bf16 v[2:17], v[200:203], v[208:211], v[2:17]
	ds_read_b128 v[200:203], v167 offset:4640
	v_mfma_f32_32x32x16_bf16 v[50:65], v[212:215], v[208:211], v[50:65]
	ds_read_b128 v[208:211], v220 offset:23072
	s_waitcnt lgkmcnt(2)
	v_mfma_f32_32x32x16_bf16 v[34:49], v[216:219], v[204:207], v[34:49]
	ds_read_b128 v[212:215], v167 offset:64
	s_waitcnt lgkmcnt(2)
	v_mfma_f32_32x32x16_bf16 v[18:33], v[200:203], v[204:207], v[18:33]
	ds_read_b128 v[204:207], v220 offset:18496
	s_waitcnt lgkmcnt(2)
	v_mfma_f32_32x32x16_bf16 v[2:17], v[216:219], v[208:211], v[2:17]
	ds_read_b128 v[216:219], v167 offset:4672
	v_mfma_f32_32x32x16_bf16 v[50:65], v[200:203], v[208:211], v[50:65]
	ds_read_b128 v[208:211], v220 offset:23104
	s_waitcnt lgkmcnt(2)
	v_mfma_f32_32x32x16_bf16 v[34:49], v[212:215], v[204:207], v[34:49]
	ds_read_b128 v[200:203], v167 offset:96
	s_waitcnt lgkmcnt(2)
	v_mfma_f32_32x32x16_bf16 v[18:33], v[216:219], v[204:207], v[18:33]
	ds_read_b128 v[204:207], v220 offset:18528
	s_waitcnt lgkmcnt(2)
	v_mfma_f32_32x32x16_bf16 v[2:17], v[212:215], v[208:211], v[2:17]
	ds_read_b128 v[212:215], v167 offset:4704
	v_mfma_f32_32x32x16_bf16 v[50:65], v[216:219], v[208:211], v[50:65]
	ds_read_b128 v[208:211], v220 offset:23136
	s_waitcnt lgkmcnt(2)
	v_mfma_f32_32x32x16_bf16 v[34:49], v[200:203], v[204:207], v[34:49]
	s_waitcnt lgkmcnt(1)
	v_mfma_f32_32x32x16_bf16 v[18:33], v[212:215], v[204:207], v[18:33]
	s_waitcnt lgkmcnt(0)
	v_mfma_f32_32x32x16_bf16 v[2:17], v[200:203], v[208:211], v[2:17]
	v_mfma_f32_32x32x16_bf16 v[50:65], v[212:215], v[208:211], v[50:65]
	s_add_i32 s37, s37, 2
	s_and_b32 s38, s37, 2
	s_mulk_i32 s38, 0x4800
	s_add_i32 s6, s6, -1
	v_add_u32_e32 v167, s38, v135
	v_lshl_add_u64 v[146:147], v[146:147], 0, s[8:9]
	v_lshl_add_u64 v[148:149], v[148:149], 0, s[8:9]
	v_lshl_add_u64 v[150:151], v[150:151], 0, s[8:9]
	v_lshl_add_u64 v[152:153], v[152:153], 0, s[8:9]
	v_lshl_add_u64 v[154:155], v[154:155], 0, s[8:9]
	v_lshl_add_u64 v[156:157], v[156:157], 0, s[8:9]
	v_lshl_add_u64 v[158:159], v[158:159], 0, s[8:9]
	v_lshl_add_u64 v[160:161], v[160:161], 0, s[8:9]
	s_cmp_lg_u32 s6, 0
	s_waitcnt vmcnt(7)
	ds_write_b128 v167, v[168:171]
	v_lshl_add_u64 v[168:169], v[146:147], 0, v[68:69]
	global_load_dwordx4 v[168:171], v[168:169], off offset:128
	s_waitcnt vmcnt(7)
	ds_write_b128 v167, v[172:175] offset:4608
	v_lshl_add_u64 v[172:173], v[148:149], 0, v[68:69]
	global_load_dwordx4 v[172:175], v[172:173], off offset:128
	s_waitcnt vmcnt(7)
	ds_write_b128 v167, v[176:179] offset:9216
	v_lshl_add_u64 v[176:177], v[150:151], 0, v[68:69]
	global_load_dwordx4 v[176:179], v[176:177], off offset:128
	s_waitcnt vmcnt(7)
	ds_write_b128 v167, v[180:183] offset:13824
	v_lshl_add_u64 v[180:181], v[152:153], 0, v[68:69]
	global_load_dwordx4 v[180:183], v[180:181], off offset:128
	s_waitcnt vmcnt(7)
	ds_write_b128 v167, v[184:187] offset:18432
	v_lshl_add_u64 v[184:185], v[154:155], 0, v[68:69]
	global_load_dwordx4 v[184:187], v[184:185], off offset:128
	s_waitcnt vmcnt(7)
	ds_write_b128 v167, v[188:191] offset:23040
	v_lshl_add_u64 v[188:189], v[156:157], 0, v[68:69]
	global_load_dwordx4 v[188:191], v[188:189], off offset:128
	s_waitcnt vmcnt(7)
	ds_write_b128 v167, v[192:195] offset:27648
	v_lshl_add_u64 v[192:193], v[158:159], 0, v[68:69]
	global_load_dwordx4 v[192:195], v[192:193], off offset:128
	s_waitcnt vmcnt(7)
	ds_write_b128 v167, v[196:199] offset:32256
	v_lshl_add_u64 v[196:197], v[160:161], 0, v[68:69]
	global_load_dwordx4 v[196:199], v[196:197], off offset:128
	s_waitcnt lgkmcnt(0)
	s_barrier
	s_cbranch_scc1 .LBB0_632
	s_and_b32 s38, s37, 2
	s_mulk_i32 s38, 0x4800
	v_add3_u32 v167, s38, v162, v163
	v_add3_u32 v220, s38, v164, v163
	ds_read_b128 v[200:203], v167 offset:0
	ds_read_b128 v[204:207], v220 offset:18432
	ds_read_b128 v[212:215], v167 offset:4608
	ds_read_b128 v[208:211], v220 offset:23040
	s_waitcnt lgkmcnt(2)
	v_mfma_f32_32x32x16_bf16 v[34:49], v[200:203], v[204:207], v[34:49]
	ds_read_b128 v[216:219], v167 offset:32
	s_waitcnt lgkmcnt(2)
	v_mfma_f32_32x32x16_bf16 v[18:33], v[212:215], v[204:207], v[18:33]
	ds_read_b128 v[204:207], v220 offset:18464
	s_waitcnt lgkmcnt(2)
	v_mfma_f32_32x32x16_bf16 v[2:17], v[200:203], v[208:211], v[2:17]
	ds_read_b128 v[200:203], v167 offset:4640
	v_mfma_f32_32x32x16_bf16 v[50:65], v[212:215], v[208:211], v[50:65]
	ds_read_b128 v[208:211], v220 offset:23072
	s_waitcnt lgkmcnt(2)
	v_mfma_f32_32x32x16_bf16 v[34:49], v[216:219], v[204:207], v[34:49]
	ds_read_b128 v[212:215], v167 offset:64
	s_waitcnt lgkmcnt(2)
	v_mfma_f32_32x32x16_bf16 v[18:33], v[200:203], v[204:207], v[18:33]
	ds_read_b128 v[204:207], v220 offset:18496
	s_waitcnt lgkmcnt(2)
	v_mfma_f32_32x32x16_bf16 v[2:17], v[216:219], v[208:211], v[2:17]
	ds_read_b128 v[216:219], v167 offset:4672
	v_mfma_f32_32x32x16_bf16 v[50:65], v[200:203], v[208:211], v[50:65]
	ds_read_b128 v[208:211], v220 offset:23104
	s_waitcnt lgkmcnt(2)
	v_mfma_f32_32x32x16_bf16 v[34:49], v[212:215], v[204:207], v[34:49]
	ds_read_b128 v[200:203], v167 offset:96
	s_waitcnt lgkmcnt(2)
;     ...
;   for (int kt = 0; kt < nk; ++kt) {
;     const int kn = (kt + 1 < nk) ? kt + 1 : kt;
;     GM_LOAD2(kn * 64, kn * bkstep)
;     __builtin_amdgcn_sched_barrier(0);
;     const char* As = smem + (kt & 1) * 2 * TILE_B;
;     const char* Bs = As + TILE_B;
;     if constexpr (HOIST) {
;       bf16x8 fa0[4], fa1[4], fb0[4], fb1[4];
; #pragma unroll
;       for (int st = 0; st < 4; ++st) {
;         fa0[st] = *(const bf16x8*)(As + aoff + st * 32);
;         fb0[st] = *(const bf16x8*)(Bs + boff + st * 32);
;         fa1[st] = *(const bf16x8*)(As + aoff + 32 * LSTR + st * 32);
;         fb1[st] = *(const bf16x8*)(Bs + boff + 32 * LSTR + st * 32);
;       }
;       __builtin_amdgcn_sched_barrier(0);
; #pragma unroll
;       for (int st = 0; st < 4; ++st) {
;         acc[0][0] = mfma32(fa0[st], fb0[st], acc[0][0]);
;         acc[0][1] = mfma32(fa0[st], fb1[st], acc[0][1]);
;         acc[1][0] = mfma32(fa1[st], fb0[st], acc[1][0]);
;         acc[1][1] = mfma32(fa1[st], fb1[st], acc[1][1]);
;       }
;     } else {
; #pragma unroll
;       for (int st = 0; st < 4; ++st) {
;         bf16x8 a0 = *(const bf16x8*)(As + aoff + st * 32);
;         bf16x8 a1 = *(const bf16x8*)(As + aoff + 32 * LSTR + st * 32);
;         bf16x8 b0 = *(const bf16x8*)(Bs + boff + st * 32);
;         bf16x8 b1 = *(const bf16x8*)(Bs + boff + 32 * LSTR + st * 32);
;         acc[0][0] = mfma32(a0, b0, acc[0][0]);
;         acc[0][1] = mfma32(a0, b1, acc[0][1]);
;         acc[1][0] = mfma32(a1, b0, acc[1][0]);
;         acc[1][1] = mfma32(a1, b1, acc[1][1]);
;       }
;     }
;     __builtin_amdgcn_sched_barrier(0);
;     {
;       char* Ad = smem + ((kt + 1) & 1) * 2 * TILE_B;
;       GM_STORE(Ad)
;     }
;     __syncthreads();
; __device__ __forceinline__ void acc_to_lds(const f32x16 (&acc)[2][2], float* cs) {
;   const int tid = threadIdx.x, lane = tid & 63, wave = tid >> 6;
;   const int wm = wave >> 1, wn = wave & 1;
; #pragma unroll
;   for (int i = 0; i < 2; ++i)
; #pragma unroll
;     for (int j = 0; j < 2; ++j)
; #pragma unroll
;       for (int r = 0; r < 16; ++r) {
;         int row = wm * 64 + i * 32 + (r & 3) + 8 * (r >> 2) + 4 * (lane >> 5);
;         int col = wn * 64 + j * 32 + (lane & 31);
;         cs[row * CSTR + col] = acc[i][j][r];
;       }
;   __syncthreads();
	v_mfma_f32_32x32x16_bf16 v[18:33], v[216:219], v[204:207], v[18:33]
	ds_read_b128 v[204:207], v220 offset:18528
	s_waitcnt lgkmcnt(2)
	v_mfma_f32_32x32x16_bf16 v[2:17], v[212:215], v[208:211], v[2:17]
	ds_read_b128 v[212:215], v167 offset:4704
	v_mfma_f32_32x32x16_bf16 v[50:65], v[216:219], v[208:211], v[50:65]
	ds_read_b128 v[208:211], v220 offset:23136
	s_waitcnt lgkmcnt(2)
	v_mfma_f32_32x32x16_bf16 v[34:49], v[200:203], v[204:207], v[34:49]
	s_waitcnt lgkmcnt(1)
	v_mfma_f32_32x32x16_bf16 v[18:33], v[212:215], v[204:207], v[18:33]
	s_waitcnt lgkmcnt(0)
	v_mfma_f32_32x32x16_bf16 v[2:17], v[200:203], v[208:211], v[2:17]
	v_mfma_f32_32x32x16_bf16 v[50:65], v[212:215], v[208:211], v[50:65]
	s_add_i32 s37, s37, 2
	s_and_b32 s38, s37, 2
	s_mulk_i32 s38, 0x4800
	v_add_u32_e32 v167, s38, v135
	v_lshl_add_u64 v[146:147], v[146:147], 0, s[8:9]
	v_lshl_add_u64 v[148:149], v[148:149], 0, s[8:9]
	v_lshl_add_u64 v[150:151], v[150:151], 0, s[8:9]
	v_lshl_add_u64 v[152:153], v[152:153], 0, s[8:9]
	v_lshl_add_u64 v[154:155], v[154:155], 0, s[8:9]
	v_lshl_add_u64 v[156:157], v[156:157], 0, s[8:9]
	v_lshl_add_u64 v[158:159], v[158:159], 0, s[8:9]
	v_lshl_add_u64 v[160:161], v[160:161], 0, s[8:9]
	s_waitcnt vmcnt(7)
	ds_write_b128 v167, v[168:171]
	s_waitcnt vmcnt(6)
	ds_write_b128 v167, v[172:175] offset:4608
	s_waitcnt vmcnt(5)
	ds_write_b128 v167, v[176:179] offset:9216
	s_waitcnt vmcnt(4)
	ds_write_b128 v167, v[180:183] offset:13824
	s_waitcnt vmcnt(3)
	ds_write_b128 v167, v[184:187] offset:18432
	s_waitcnt vmcnt(2)
	ds_write_b128 v167, v[188:191] offset:23040
	s_waitcnt vmcnt(1)
	ds_write_b128 v167, v[192:195] offset:27648
	s_waitcnt vmcnt(0)
	ds_write_b128 v167, v[196:199] offset:32256
	s_waitcnt lgkmcnt(0)
	s_barrier
	v_lshl_add_u64 v[180:181], v[160:161], 0, v[68:69]
	v_lshl_add_u64 v[176:177], v[158:159], 0, v[68:69]
	v_lshl_add_u64 v[172:173], v[156:157], 0, v[68:69]
	v_lshl_add_u64 v[168:169], v[154:155], 0, v[68:69]
	v_lshl_add_u64 v[158:159], v[152:153], 0, v[68:69]
	v_lshl_add_u64 v[154:155], v[150:151], 0, v[68:69]
	v_lshl_add_u64 v[150:151], v[148:149], 0, v[68:69]
	v_lshl_add_u64 v[146:147], v[146:147], 0, v[68:69]
	s_nop 0
	s_nop 0
	s_nop 0
	s_nop 0
	s_nop 0
	s_nop 0
	s_nop 0
	v_add3_u32 v68, s38, v162, v163
	v_add3_u32 v167, s38, v164, v163
	ds_read_b128 v[184:187], v68 offset:0
	ds_read_b128 v[188:191], v167 offset:18432
	ds_read_b128 v[196:199], v68 offset:4608
	ds_read_b128 v[192:195], v167 offset:23040
	s_waitcnt lgkmcnt(2)
	v_mfma_f32_32x32x16_bf16 v[34:49], v[184:187], v[188:191], v[34:49]
	ds_read_b128 v[200:203], v68 offset:32
	s_waitcnt lgkmcnt(2)
	v_mfma_f32_32x32x16_bf16 v[18:33], v[196:199], v[188:191], v[18:33]
	ds_read_b128 v[188:191], v167 offset:18464
	s_waitcnt lgkmcnt(2)
	v_mfma_f32_32x32x16_bf16 v[2:17], v[184:187], v[192:195], v[2:17]
	ds_read_b128 v[184:187], v68 offset:4640
	v_mfma_f32_32x32x16_bf16 v[50:65], v[196:199], v[192:195], v[50:65]
	ds_read_b128 v[192:195], v167 offset:23072
	s_waitcnt lgkmcnt(2)
	v_mfma_f32_32x32x16_bf16 v[34:49], v[200:203], v[188:191], v[34:49]
	ds_read_b128 v[196:199], v68 offset:64
	s_waitcnt lgkmcnt(2)
	v_mfma_f32_32x32x16_bf16 v[18:33], v[184:187], v[188:191], v[18:33]
	ds_read_b128 v[188:191], v167 offset:18496
	s_waitcnt lgkmcnt(2)
	v_mfma_f32_32x32x16_bf16 v[2:17], v[200:203], v[192:195], v[2:17]
	ds_read_b128 v[200:203], v68 offset:4672
	v_mfma_f32_32x32x16_bf16 v[50:65], v[184:187], v[192:195], v[50:65]
	ds_read_b128 v[192:195], v167 offset:23104
	s_waitcnt lgkmcnt(2)
	v_mfma_f32_32x32x16_bf16 v[34:49], v[196:199], v[188:191], v[34:49]
	ds_read_b128 v[184:187], v68 offset:96
	s_waitcnt lgkmcnt(2)
	v_mfma_f32_32x32x16_bf16 v[18:33], v[200:203], v[188:191], v[18:33]
	ds_read_b128 v[188:191], v167 offset:18528
	s_waitcnt lgkmcnt(2)
	v_mfma_f32_32x32x16_bf16 v[2:17], v[196:199], v[192:195], v[2:17]
	ds_read_b128 v[196:199], v68 offset:4704
	v_mfma_f32_32x32x16_bf16 v[50:65], v[200:203], v[192:195], v[50:65]
	ds_read_b128 v[192:195], v167 offset:23136
	s_waitcnt lgkmcnt(2)
	v_mfma_f32_32x32x16_bf16 v[34:49], v[184:187], v[188:191], v[34:49]
	s_waitcnt lgkmcnt(1)
	v_mfma_f32_32x32x16_bf16 v[18:33], v[196:199], v[188:191], v[18:33]
	s_waitcnt lgkmcnt(0)
	v_mfma_f32_32x32x16_bf16 v[2:17], v[184:187], v[192:195], v[2:17]
	v_mfma_f32_32x32x16_bf16 v[50:65], v[196:199], v[192:195], v[50:65]
	s_waitcnt lgkmcnt(0)
	s_barrier
	ds_write2_b32 v165, v34, v2 offset1:32
	ds_write2_b32 v165, v35, v3 offset0:132 offset1:164
	v_add_u32_e32 v2, 0x400, v165
	ds_write2_b32 v2, v36, v4 offset0:8 offset1:40
	ds_write2_b32 v2, v37, v5 offset0:140 offset1:172
	v_add_u32_e32 v2, 0x1000, v165
	ds_write2_b32 v2, v38, v6 offset0:32 offset1:64
	ds_write2_b32 v2, v39, v7 offset0:164 offset1:196
	v_add_u32_e32 v2, 0x1400, v165
	ds_write2_b32 v2, v40, v8 offset0:40 offset1:72
	ds_write2_b32 v2, v41, v9 offset0:172 offset1:204
	v_add_u32_e32 v2, 0x2000, v165
	ds_write2_b32 v2, v42, v10 offset0:64 offset1:96
	ds_write2_b32 v2, v43, v11 offset0:196 offset1:228
	v_add_u32_e32 v2, 0x2400, v165
	ds_write2_b32 v2, v44, v12 offset0:72 offset1:104
	ds_write2_b32 v2, v45, v13 offset0:204 offset1:236
	v_add_u32_e32 v2, 0x3000, v165
	ds_write2_b32 v2, v46, v14 offset0:96 offset1:128
	v_add_u32_e32 v2, 0x3200, v165
	ds_write2_b32 v2, v47, v15 offset0:100 offset1:132
	v_add_u32_e32 v2, 0x3400, v165
	ds_write2_b32 v2, v48, v16 offset0:104 offset1:136
	v_add_u32_e32 v2, 0x3600, v165
	ds_write2_b32 v2, v49, v17 offset0:108 offset1:140
	v_add_u32_e32 v2, 0x4000, v165
	ds_write2_b32 v2, v18, v50 offset0:128 offset1:160
	v_add_u32_e32 v2, 0x4400, v165
	ds_write2_b32 v2, v19, v51 offset0:4 offset1:36
	ds_write2_b32 v2, v20, v52 offset0:136 offset1:168
	v_add_u32_e32 v2, 0x4800, v165
	ds_write2_b32 v2, v21, v53 offset0:12 offset1:44
	v_add_u32_e32 v2, 0x5000, v165
	ds_write2_b32 v2, v22, v54 offset0:160 offset1:192
	v_add_u32_e32 v2, 0x5400, v165
	ds_write2_b32 v2, v23, v55 offset0:36 offset1:68
	ds_write2_b32 v2, v24, v56 offset0:168 offset1:200
	v_add_u32_e32 v2, 0x5800, v165
	ds_write2_b32 v2, v25, v57 offset0:44 offset1:76
	v_add_u32_e32 v2, 0x6000, v165
	ds_write2_b32 v2, v26, v58 offset0:192 offset1:224
	v_add_u32_e32 v2, 0x6400, v165
	ds_write2_b32 v2, v27, v59 offset0:68 offset1:100
	ds_write2_b32 v2, v28, v60 offset0:200 offset1:232
	v_add_u32_e32 v2, 0x6800, v165
	ds_write2_b32 v2, v29, v61 offset0:76 offset1:108
	v_add_u32_e32 v2, 0x7200, v165
	ds_write2_b32 v2, v30, v62 offset0:96 offset1:128
	v_add_u32_e32 v2, 0x7400, v165
	ds_write2_b32 v2, v31, v63 offset0:100 offset1:132
	v_add_u32_e32 v2, 0x7600, v165
	s_lshl_b32 s6, s36, 11
	ds_write2_b32 v2, v32, v64 offset0:104 offset1:136
	v_add_u32_e32 v2, 0x7800, v165
	v_lshl_add_u64 v[46:47], v[116:117], 0, s[6:7]
	ds_write2_b32 v2, v33, v65 offset0:108 offset1:140
	s_waitcnt lgkmcnt(0)
	s_barrier
; __device__ __forceinline__ void merge_tile(const Params& P, int l, int mt, int nt, char* smem) {
;     ...
;     const u16* gp = WSP(u16, OFF_G) + grow * 3072 + br * 1024 + nt * 128 + half * 64;
; #pragma unroll
;     for (int q = 0; q < 8; ++q) {
;       uint4 gq = *(const uint4*)(gp + q * 8);
;       float4 a = *(const float4*)(cs + r * CSTR + half * 64 + q * 8);
;       float4 c = *(const float4*)(cs + r * CSTR + half * 64 + q * 8 + 4);
;       macc[q * 8 + 0] += __uint_as_float(gq.x << 16) * a.x;
;       macc[q * 8 + 1] += __uint_as_float(gq.x & 0xffff0000u) * a.y;
;       macc[q * 8 + 2] += __uint_as_float(gq.y << 16) * a.z;
;       macc[q * 8 + 3] += __uint_as_float(gq.y & 0xffff0000u) * a.w;
;       macc[q * 8 + 4] += __uint_as_float(gq.z << 16) * c.x;
;       macc[q * 8 + 5] += __uint_as_float(gq.z & 0xffff0000u) * c.y;
;       macc[q * 8 + 6] += __uint_as_float(gq.w << 16) * c.z;
;       macc[q * 8 + 7] += __uint_as_float(gq.w & 0xffff0000u) * c.w;
;     }
	global_load_dwordx4 v[2:5], v[46:47], off
	global_load_dwordx4 v[6:9], v[46:47], off offset:16
	global_load_dwordx4 v[10:13], v[46:47], off offset:32
	global_load_dwordx4 v[14:17], v[46:47], off offset:48
	global_load_dwordx4 v[18:21], v[46:47], off offset:64
	global_load_dwordx4 v[22:25], v[46:47], off offset:80
	ds_read_b128 v[26:29], v166
	ds_read_b128 v[30:33], v166 offset:16
	ds_read_b128 v[34:37], v166 offset:32
	ds_read_b128 v[38:41], v166 offset:48
	global_load_dwordx4 v[42:45], v[46:47], off offset:112
	s_nop 0
	global_load_dwordx4 v[46:49], v[46:47], off offset:96
	s_add_i32 s36, s36, 1
	s_cmp_lg_u32 s36, 3
	s_waitcnt vmcnt(7)
	v_lshlrev_b32_e32 v50, 16, v2
	v_and_b32_e32 v51, 0xffff0000, v2
	v_lshlrev_b32_e32 v2, 16, v3
	v_and_b32_e32 v3, 0xffff0000, v3
	s_waitcnt lgkmcnt(3)
	v_pk_fma_f32 v[142:143], v[28:29], v[2:3], v[142:143]
	v_lshlrev_b32_e32 v2, 16, v4
	v_and_b32_e32 v3, 0xffff0000, v4
	s_waitcnt lgkmcnt(2)
	v_pk_fma_f32 v[140:141], v[30:31], v[2:3], v[140:141]
	v_lshlrev_b32_e32 v2, 16, v5
	v_and_b32_e32 v3, 0xffff0000, v5
	v_pk_fma_f32 v[138:139], v[32:33], v[2:3], v[138:139]
	s_waitcnt vmcnt(6)
	v_lshlrev_b32_e32 v2, 16, v6
	v_and_b32_e32 v3, 0xffff0000, v6
	s_waitcnt lgkmcnt(1)
	v_pk_fma_f32 v[136:137], v[34:35], v[2:3], v[136:137]
	v_lshlrev_b32_e32 v2, 16, v7
	v_and_b32_e32 v3, 0xffff0000, v7
	v_pk_fma_f32 v[132:133], v[36:37], v[2:3], v[132:133]
	v_lshlrev_b32_e32 v2, 16, v8
	v_and_b32_e32 v3, 0xffff0000, v8
	s_waitcnt lgkmcnt(0)
	v_pk_fma_f32 v[130:131], v[38:39], v[2:3], v[130:131]
	ds_read_b128 v[2:5], v166 offset:64
	v_lshlrev_b32_e32 v6, 16, v9
	v_and_b32_e32 v7, 0xffff0000, v9
	v_pk_fma_f32 v[128:129], v[40:41], v[6:7], v[128:129]
	ds_read_b128 v[6:9], v166 offset:80
	v_pk_fma_f32 v[144:145], v[26:27], v[50:51], v[144:145]
	s_waitcnt vmcnt(5)
	v_lshlrev_b32_e32 v26, 16, v10
	v_and_b32_e32 v27, 0xffff0000, v10
	s_waitcnt lgkmcnt(1)
	v_pk_fma_f32 v[126:127], v[2:3], v[26:27], v[126:127]
	v_lshlrev_b32_e32 v2, 16, v11
	v_and_b32_e32 v3, 0xffff0000, v11
	v_pk_fma_f32 v[124:125], v[4:5], v[2:3], v[124:125]
	v_lshlrev_b32_e32 v2, 16, v12
	v_and_b32_e32 v3, 0xffff0000, v12
	s_waitcnt lgkmcnt(0)
	v_pk_fma_f32 v[122:123], v[6:7], v[2:3], v[122:123]
	ds_read_b128 v[2:5], v166 offset:96
	v_lshlrev_b32_e32 v6, 16, v13
	v_and_b32_e32 v7, 0xffff0000, v13
	v_pk_fma_f32 v[120:121], v[8:9], v[6:7], v[120:121]
	ds_read_b128 v[6:9], v166 offset:112
	s_waitcnt vmcnt(4)
	v_lshlrev_b32_e32 v10, 16, v14
	v_and_b32_e32 v11, 0xffff0000, v14
	s_waitcnt lgkmcnt(1)
	v_pk_fma_f32 v[118:119], v[2:3], v[10:11], v[118:119]
	v_lshlrev_b32_e32 v2, 16, v15
	v_and_b32_e32 v3, 0xffff0000, v15
	v_pk_fma_f32 v[114:115], v[4:5], v[2:3], v[114:115]
	v_lshlrev_b32_e32 v2, 16, v16
	v_and_b32_e32 v3, 0xffff0000, v16
	s_waitcnt lgkmcnt(0)
	v_pk_fma_f32 v[112:113], v[6:7], v[2:3], v[112:113]
	ds_read_b128 v[2:5], v166 offset:128
	v_lshlrev_b32_e32 v6, 16, v17
	v_and_b32_e32 v7, 0xffff0000, v17
	v_pk_fma_f32 v[110:111], v[8:9], v[6:7], v[110:111]
	ds_read_b128 v[6:9], v166 offset:144
	s_waitcnt vmcnt(3)
	v_lshlrev_b32_e32 v10, 16, v18
	v_and_b32_e32 v11, 0xffff0000, v18
	s_waitcnt lgkmcnt(1)
	v_pk_fma_f32 v[106:107], v[2:3], v[10:11], v[106:107]
	v_lshlrev_b32_e32 v2, 16, v19
	v_and_b32_e32 v3, 0xffff0000, v19
	v_pk_fma_f32 v[104:105], v[4:5], v[2:3], v[104:105]
	v_lshlrev_b32_e32 v2, 16, v20
	v_and_b32_e32 v3, 0xffff0000, v20
	s_waitcnt lgkmcnt(0)
	v_pk_fma_f32 v[102:103], v[6:7], v[2:3], v[102:103]
	ds_read_b128 v[2:5], v166 offset:160
	v_lshlrev_b32_e32 v6, 16, v21
	v_and_b32_e32 v7, 0xffff0000, v21
	v_pk_fma_f32 v[100:101], v[8:9], v[6:7], v[100:101]
	ds_read_b128 v[6:9], v166 offset:176
	s_waitcnt vmcnt(2)
	v_lshlrev_b32_e32 v10, 16, v22
	v_and_b32_e32 v11, 0xffff0000, v22
	s_waitcnt lgkmcnt(1)
	v_pk_fma_f32 v[98:99], v[2:3], v[10:11], v[98:99]
	v_lshlrev_b32_e32 v2, 16, v23
	v_and_b32_e32 v3, 0xffff0000, v23
	v_pk_fma_f32 v[96:97], v[4:5], v[2:3], v[96:97]
	v_lshlrev_b32_e32 v2, 16, v24
	v_and_b32_e32 v3, 0xffff0000, v24
	s_waitcnt lgkmcnt(0)
	v_pk_fma_f32 v[94:95], v[6:7], v[2:3], v[94:95]
	ds_read_b128 v[2:5], v166 offset:192
	v_lshlrev_b32_e32 v6, 16, v25
	v_and_b32_e32 v7, 0xffff0000, v25
	v_pk_fma_f32 v[92:93], v[8:9], v[6:7], v[92:93]
	ds_read_b128 v[6:9], v166 offset:208
	s_waitcnt vmcnt(0)
	v_lshlrev_b32_e32 v10, 16, v46
	v_and_b32_e32 v11, 0xffff0000, v46
	s_waitcnt lgkmcnt(1)
	v_pk_fma_f32 v[90:91], v[2:3], v[10:11], v[90:91]
	v_lshlrev_b32_e32 v2, 16, v47
	v_and_b32_e32 v3, 0xffff0000, v47
	v_pk_fma_f32 v[88:89], v[4:5], v[2:3], v[88:89]
	v_lshlrev_b32_e32 v2, 16, v48
	v_and_b32_e32 v3, 0xffff0000, v48
	s_waitcnt lgkmcnt(0)
	v_pk_fma_f32 v[86:87], v[6:7], v[2:3], v[86:87]
	ds_read_b128 v[2:5], v166 offset:224
	v_lshlrev_b32_e32 v6, 16, v49
	v_and_b32_e32 v7, 0xffff0000, v49
	v_pk_fma_f32 v[84:85], v[8:9], v[6:7], v[84:85]
	ds_read_b128 v[6:9], v166 offset:240
	v_lshlrev_b32_e32 v10, 16, v42
	v_and_b32_e32 v11, 0xffff0000, v42
	s_waitcnt lgkmcnt(1)
	v_pk_fma_f32 v[82:83], v[2:3], v[10:11], v[82:83]
	v_lshlrev_b32_e32 v2, 16, v43
	v_and_b32_e32 v3, 0xffff0000, v43
	v_pk_fma_f32 v[80:81], v[4:5], v[2:3], v[80:81]
	v_lshlrev_b32_e32 v2, 16, v44
	v_and_b32_e32 v3, 0xffff0000, v44
	s_waitcnt lgkmcnt(0)
	v_pk_fma_f32 v[78:79], v[6:7], v[2:3], v[78:79]
	v_lshlrev_b32_e32 v2, 16, v45
	v_and_b32_e32 v3, 0xffff0000, v45
	v_pk_fma_f32 v[76:77], v[8:9], v[2:3], v[76:77]
	s_barrier
; __device__ __forceinline__ void store_row64_bf16(const float* v, u16* dst) {
; #pragma unroll
;   for (int q = 0; q < 8; ++q) {
;     uint4 o;
;     o.x = pack2(v[q * 8 + 0], v[q * 8 + 1]);
;     o.y = pack2(v[q * 8 + 2], v[q * 8 + 3]);
;     o.z = pack2(v[q * 8 + 4], v[q * 8 + 5]);
;     o.w = pack2(v[q * 8 + 6], v[q * 8 + 7]);
;     *(uint4*)(dst + q * 8) = o;
;   }
; }
; __device__ __forceinline__ void merge_tile(const Params& P, int l, int mt, int nt, char* smem) {
;     ...
;   }
;   store_row64_bf16(macc, WSP(u16, OFF_M) + grow * DM + nt * 128 + half * 64);
	s_cbranch_scc1 .LBB0_631
	v_lshlrev_b64 v[2:3], 11, v[108:109]
	v_lshl_add_u64 v[2:3], s[4:5], 0, v[2:3]
	v_lshl_add_u64 v[2:3], s[12:13], 1, v[2:3]
	v_mov_b32_e32 v75, v69
	v_lshl_add_u64 v[6:7], v[2:3], 0, v[74:75]
	v_cvt_pk_bf16_f32 v2, v144, v145
	v_cvt_pk_bf16_f32 v3, v142, v143
	v_cvt_pk_bf16_f32 v4, v140, v141
	v_cvt_pk_bf16_f32 v5, v138, v139
	global_store_dwordx4 v[6:7], v[2:5], off
	v_readlane_b32 s40, v253, 37
	v_readlane_b32 s48, v253, 45
	v_cvt_pk_bf16_f32 v2, v136, v137
	v_cvt_pk_bf16_f32 v3, v132, v133
	v_cvt_pk_bf16_f32 v4, v130, v131
	v_cvt_pk_bf16_f32 v5, v128, v129
	global_store_dwordx4 v[6:7], v[2:5], off offset:16
	v_readlane_b32 s49, v253, 46
	v_readlane_b32 s50, v253, 47
	v_cvt_pk_bf16_f32 v2, v126, v127
	v_cvt_pk_bf16_f32 v3, v124, v125
	v_cvt_pk_bf16_f32 v4, v122, v123
	v_cvt_pk_bf16_f32 v5, v120, v121
	global_store_dwordx4 v[6:7], v[2:5], off offset:32
	v_readlane_b32 s51, v253, 48
	v_readlane_b32 s52, v253, 49
	v_cvt_pk_bf16_f32 v2, v118, v119
	v_cvt_pk_bf16_f32 v3, v114, v115
	v_cvt_pk_bf16_f32 v4, v112, v113
	v_cvt_pk_bf16_f32 v5, v110, v111
	global_store_dwordx4 v[6:7], v[2:5], off offset:48
	v_readlane_b32 s53, v253, 50
	v_readlane_b32 s54, v253, 51
	v_cvt_pk_bf16_f32 v2, v106, v107
	v_cvt_pk_bf16_f32 v3, v104, v105
	v_cvt_pk_bf16_f32 v4, v102, v103
	v_cvt_pk_bf16_f32 v5, v100, v101
	global_store_dwordx4 v[6:7], v[2:5], off offset:64
	v_readlane_b32 s55, v253, 52
	v_readlane_b32 s41, v253, 38
	v_cvt_pk_bf16_f32 v2, v98, v99
	v_cvt_pk_bf16_f32 v3, v96, v97
	v_cvt_pk_bf16_f32 v4, v94, v95
	v_cvt_pk_bf16_f32 v5, v92, v93
	global_store_dwordx4 v[6:7], v[2:5], off offset:80
	v_readlane_b32 s42, v253, 39
	v_readlane_b32 s43, v253, 40
	v_cvt_pk_bf16_f32 v2, v90, v91
	v_cvt_pk_bf16_f32 v3, v88, v89
	v_cvt_pk_bf16_f32 v4, v86, v87
	v_cvt_pk_bf16_f32 v5, v84, v85
	global_store_dwordx4 v[6:7], v[2:5], off offset:96
	v_readlane_b32 s44, v253, 41
	v_readlane_b32 s45, v253, 42
	v_cvt_pk_bf16_f32 v2, v82, v83
	v_cvt_pk_bf16_f32 v3, v80, v81
	v_cvt_pk_bf16_f32 v4, v78, v79
	v_cvt_pk_bf16_f32 v5, v76, v77
	global_store_dwordx4 v[6:7], v[2:5], off offset:112
	v_readlane_b32 s46, v253, 43
	v_readlane_b32 s47, v253, 44
	s_branch .LBB0_628

; #define GM_LOAD(KOFF) GM_LOAD2(KOFF, 0)
;     ...
;   const u16* ap0 = arow(lr) + kc * 8;
;   const u16* ap1 = arow(lr + 32) + kc * 8;
;   const u16* ap2 = arow(lr + 64) + kc * 8;
;   const u16* ap3 = arow(lr + 96) + kc * 8;
;   const u16* bp0 = Bt + (size_t)lr * ldb + kc * 8;
;   const size_t bstep = 32 * ldb;
;   const int so = lr * LSTR + kc * 16;
;   uint4 ra0, ra1, ra2, ra3, rb0, rb1, rb2, rb3;
;     ...
;   GM_LOAD(0)
;   GM_STORE(smem)
;   __syncthreads();
; template <bool WIDE>
; __device__ __forceinline__ void outproj_tile(const Params& P, int l, int mt, int nt, char* smem) {
;   float* cs = (float*)smem;
;   const u16* A = WSP(u16, OFF_M) + (size_t)mt * 128 * DM;
;   const u16* Bt = WSP(u16, OFF_WOUT) + ((size_t)l * DM + nt * 128) * DM;
;   f32x16 accw[2][4];
;   f32x16 accn[2][2];
;   if constexpr (WIDE) {
; #pragma unroll
;     for (int i = 0; i < 2; ++i)
; #pragma unroll
;       for (int j = 0; j < 4; ++j)
; #pragma unroll
;         for (int r = 0; r < 16; ++r) accw[i][j][r] = 0.f;
;     gemm_wide([&](int rr) { return A + (size_t)rr * DM; }, Bt, DM, DM, smem, accw);
;   } else {
;     zero_acc(accn);
;     gemm_main([&](int rr) { return A + (size_t)rr * DM; }, Bt, DM, DM, smem, accn);
.LBB0_721:
	s_ashr_i32 s18, s35, 3
	s_add_i32 s14, s18, 0x100
	s_ashr_i32 s15, s14, 31
	s_lshl_b64 s[16:17], s[14:15], 18
	v_lshl_add_u64 v[2:3], v[68:69], 0, s[16:17]
	v_lshl_add_u64 v[80:81], v[2:3], 0, v[74:75]
	v_add_co_u32_e32 v2, vcc, s21, v80
	s_and_b32 s36, s34, 7
	s_nop 0
	v_addc_co_u32_e32 v3, vcc, 0, v81, vcc
	s_lshl_b32 s2, s36, 18
	v_add_co_u32_e32 v4, vcc, s22, v80
	v_lshl_add_u64 v[78:79], v[72:73], 0, s[2:3]
	s_and_b32 s2, s35, 7
	v_addc_co_u32_e32 v5, vcc, 0, v81, vcc
	s_lshl_b32 s2, s2, 18
	global_load_dwordx4 v[28:31], v[2:3], off
	global_load_dwordx4 v[32:35], v[4:5], off
	v_add_co_u32_e32 v2, vcc, s23, v80
	v_lshl_add_u64 v[76:77], v[70:71], 0, s[2:3]
	s_nop 0
	v_addc_co_u32_e32 v3, vcc, 0, v81, vcc
	v_add_co_u32_e32 v4, vcc, s22, v76
	global_load_dwordx4 v[36:39], v[80:81], off
	global_load_dwordx4 v[40:43], v[76:77], off
	v_addc_co_u32_e32 v5, vcc, 0, v77, vcc
	v_add_co_u32_e32 v6, vcc, s23, v76
	s_ashr_i32 s19, s18, 31
	s_nop 0
	v_addc_co_u32_e32 v7, vcc, 0, v77, vcc
	global_load_dwordx4 v[44:47], v[4:5], off
	global_load_dwordx4 v[48:51], v[6:7], off
	v_add_co_u32_e32 v4, vcc, s21, v76
	s_lshl_b64 s[18:19], s[18:19], 18
	s_nop 0
	v_addc_co_u32_e32 v5, vcc, 0, v77, vcc
	global_load_dwordx4 v[52:55], v[2:3], off
	global_load_dwordx4 v[56:59], v[4:5], off
	s_mov_b64 s[16:17], 0
	s_mov_b32 s2, 0
	v_mov_b32_e32 v2, 0
	v_mov_b32_e32 v3, v67
	v_mov_b32_e32 v4, v67
	v_mov_b32_e32 v5, v67
	v_mov_b32_e32 v6, v67
	v_mov_b32_e32 v7, v67
	v_mov_b32_e32 v8, v67
	v_mov_b32_e32 v9, v67
	v_mov_b32_e32 v10, v67
	v_mov_b32_e32 v11, v67
	v_mov_b32_e32 v12, v67
	v_mov_b32_e32 v13, v67
	v_mov_b32_e32 v14, v67
	v_mov_b32_e32 v15, v67
	v_mov_b32_e32 v16, v67
	v_mov_b32_e32 v17, v67
	v_mov_b32_e32 v18, 0
	v_mov_b32_e32 v19, v67
	v_mov_b32_e32 v20, v67
	v_mov_b32_e32 v21, v67
	v_mov_b32_e32 v22, v67
	v_mov_b32_e32 v23, v67
	v_mov_b32_e32 v24, v67
	v_mov_b32_e32 v25, v67
	v_mov_b32_e32 v26, v67
	v_lshl_add_u64 v[88:89], v[72:73], 0, s[18:19]
	v_lshl_add_u64 v[82:83], v[80:81], 0, s[4:5]
	v_lshl_add_u64 v[84:85], v[80:81], 0, s[6:7]
	v_lshl_add_u64 v[86:87], v[80:81], 0, s[8:9]
	v_mov_b32_e32 v27, v67
	v_mov_b32_e32 v60, v67
	v_mov_b32_e32 v61, v67
	v_mov_b32_e32 v62, v67
	v_mov_b32_e32 v63, v67
	v_mov_b32_e32 v64, v67
	v_mov_b32_e32 v65, v67
	s_waitcnt vmcnt(3)
	ds_write_b128 v1, v[44:47] offset:27648
	s_waitcnt vmcnt(2)
	ds_write_b128 v1, v[48:51] offset:32256
	ds_write_b128 v1, v[36:39]
	ds_write_b128 v1, v[40:43] offset:18432
	ds_write_b128 v1, v[28:31] offset:4608
	ds_write_b128 v1, v[32:35] offset:9216
	s_waitcnt vmcnt(1)
	ds_write_b128 v1, v[52:55] offset:13824
	s_waitcnt vmcnt(0)
	ds_write_b128 v1, v[56:59] offset:23040
	v_mov_b32_e32 v28, v67
	v_mov_b32_e32 v29, v67
	v_mov_b32_e32 v30, v67
	v_mov_b32_e32 v31, v67
	v_mov_b32_e32 v32, v67
	v_mov_b32_e32 v33, v67
	v_mov_b32_e32 v34, 0
	v_mov_b32_e32 v35, v67
	v_mov_b32_e32 v36, v67
	v_mov_b32_e32 v37, v67
	v_mov_b32_e32 v38, v67
	v_mov_b32_e32 v39, v67
	v_mov_b32_e32 v40, v67
	v_mov_b32_e32 v41, v67
	v_mov_b32_e32 v42, v67
	v_mov_b32_e32 v43, v67
	v_mov_b32_e32 v44, v67
	v_mov_b32_e32 v45, v67
	v_mov_b32_e32 v46, v67
	v_mov_b32_e32 v47, v67
	v_mov_b32_e32 v48, v67
	v_mov_b32_e32 v49, v67
	v_mov_b32_e32 v50, 0
	v_mov_b32_e32 v51, v67
	v_mov_b32_e32 v52, v67
	v_mov_b32_e32 v53, v67
	v_mov_b32_e32 v54, v67
	v_mov_b32_e32 v55, v67
	v_mov_b32_e32 v56, v67
	v_mov_b32_e32 v57, v67
	v_mov_b32_e32 v58, v67
	v_mov_b32_e32 v59, v67
	s_waitcnt lgkmcnt(0)
	s_barrier
	v_lshl_add_u64 v[104:105], v[88:89], 0, s[16:17]
	v_add_co_u32_e32 v96, vcc, s24, v104
	v_lshl_add_u64 v[120:121], v[78:79], 0, s[16:17]
	s_nop 0
	v_addc_co_u32_e32 v97, vcc, 0, v105, vcc
	v_add_co_u32_e32 v100, vcc, s25, v104
	s_nop 1
	v_addc_co_u32_e32 v101, vcc, 0, v105, vcc
	v_add_co_u32_e32 v106, vcc, s26, v104
	global_load_dwordx4 v[96:99], v[96:97], off offset:384
	s_nop 0
	global_load_dwordx4 v[100:103], v[100:101], off offset:384
	v_addc_co_u32_e32 v107, vcc, 0, v105, vcc
	v_add_co_u32_e32 v108, vcc, s27, v104
	s_nop 1
	v_addc_co_u32_e32 v109, vcc, 0, v105, vcc
	v_add_co_u32_e32 v112, vcc, s28, v120
	global_load_dwordx4 v[104:107], v[106:107], off offset:384
	s_nop 0
	global_load_dwordx4 v[108:111], v[108:109], off offset:384
	v_addc_co_u32_e32 v113, vcc, 0, v121, vcc
	v_add_co_u32_e32 v116, vcc, s29, v120
	s_nop 1
	v_addc_co_u32_e32 v117, vcc, 0, v121, vcc
	v_add_co_u32_e32 v122, vcc, s30, v120
	global_load_dwordx4 v[112:115], v[112:113], off offset:128
	s_nop 0
	global_load_dwordx4 v[116:119], v[116:117], off offset:128
	v_addc_co_u32_e32 v123, vcc, 0, v121, vcc
	v_add_co_u32_e32 v124, vcc, s31, v120
	s_nop 1
	v_addc_co_u32_e32 v125, vcc, 0, v121, vcc
	global_load_dwordx4 v[120:123], v[122:123], off offset:128
	s_nop 0
	global_load_dwordx4 v[124:127], v[124:125], off offset:128
;     ...
;   for (int kt = 0; kt < nk; ++kt) {
;     const int kn = (kt + 1 < nk) ? kt + 1 : kt;
;     GM_LOAD2(kn * 64, kn * bkstep)
;     __builtin_amdgcn_sched_barrier(0);
;     const char* As = smem + (kt & 1) * 2 * TILE_B;
;     const char* Bs = As + TILE_B;
;     if constexpr (HOIST) {
;       bf16x8 fa0[4], fa1[4], fb0[4], fb1[4];
; #pragma unroll
;       for (int st = 0; st < 4; ++st) {
;         fa0[st] = *(const bf16x8*)(As + aoff + st * 32);
;         fb0[st] = *(const bf16x8*)(Bs + boff + st * 32);
;         fa1[st] = *(const bf16x8*)(As + aoff + 32 * LSTR + st * 32);
;         fb1[st] = *(const bf16x8*)(Bs + boff + 32 * LSTR + st * 32);
;       }
;       __builtin_amdgcn_sched_barrier(0);
; #pragma unroll
;       for (int st = 0; st < 4; ++st) {
;         acc[0][0] = mfma32(fa0[st], fb0[st], acc[0][0]);
;         acc[0][1] = mfma32(fa0[st], fb1[st], acc[0][1]);
;         acc[1][0] = mfma32(fa1[st], fb0[st], acc[1][0]);
;         acc[1][1] = mfma32(fa1[st], fb1[st], acc[1][1]);
;       }
;     } else {
; #pragma unroll
;       for (int st = 0; st < 4; ++st) {
;         bf16x8 a0 = *(const bf16x8*)(As + aoff + st * 32);
;         bf16x8 a1 = *(const bf16x8*)(As + aoff + 32 * LSTR + st * 32);
;         bf16x8 b0 = *(const bf16x8*)(Bs + boff + st * 32);
;         bf16x8 b1 = *(const bf16x8*)(Bs + boff + 32 * LSTR + st * 32);
;         acc[0][0] = mfma32(a0, b0, acc[0][0]);
;         acc[0][1] = mfma32(a0, b1, acc[0][1]);
;         acc[1][0] = mfma32(a1, b0, acc[1][0]);
;         acc[1][1] = mfma32(a1, b1, acc[1][1]);
;       }
;     }
;     __builtin_amdgcn_sched_barrier(0);
;     {
;       char* Ad = smem + ((kt + 1) & 1) * 2 * TILE_B;
;       GM_STORE(Ad)
;     }
;     __syncthreads();
.LBB0_722:
	s_and_b32 s18, s2, 2
	s_mulk_i32 s18, 0x4800
	v_add3_u32 v66, s18, v90, v91
	v_add3_u32 v95, s18, v92, v91
	ds_read_b128 v[128:131], v66 offset:0
	ds_read_b128 v[136:139], v95 offset:18432
	ds_read_b128 v[144:147], v66 offset:4608
	ds_read_b128 v[140:143], v95 offset:23040
	s_waitcnt lgkmcnt(2)
	v_mfma_f32_32x32x16_bf16 v[50:65], v[128:131], v[136:139], v[50:65]
	ds_read_b128 v[148:151], v66 offset:32
	s_waitcnt lgkmcnt(2)
	v_mfma_f32_32x32x16_bf16 v[18:33], v[144:147], v[136:139], v[18:33]
	ds_read_b128 v[136:139], v95 offset:18464
	s_waitcnt lgkmcnt(2)
	v_mfma_f32_32x32x16_bf16 v[34:49], v[128:131], v[140:143], v[34:49]
	ds_read_b128 v[128:131], v66 offset:4640
	v_mfma_f32_32x32x16_bf16 v[2:17], v[144:147], v[140:143], v[2:17]
	ds_read_b128 v[140:143], v95 offset:23072
	s_waitcnt lgkmcnt(2)
	v_mfma_f32_32x32x16_bf16 v[50:65], v[148:151], v[136:139], v[50:65]
	ds_read_b128 v[144:147], v66 offset:64
	s_waitcnt lgkmcnt(2)
	v_mfma_f32_32x32x16_bf16 v[18:33], v[128:131], v[136:139], v[18:33]
	ds_read_b128 v[136:139], v95 offset:18496
	s_waitcnt lgkmcnt(2)
	v_mfma_f32_32x32x16_bf16 v[34:49], v[148:151], v[140:143], v[34:49]
	ds_read_b128 v[148:151], v66 offset:4672
	v_mfma_f32_32x32x16_bf16 v[2:17], v[128:131], v[140:143], v[2:17]
	ds_read_b128 v[140:143], v95 offset:23104
	s_waitcnt lgkmcnt(2)
	v_mfma_f32_32x32x16_bf16 v[50:65], v[144:147], v[136:139], v[50:65]
	ds_read_b128 v[128:131], v66 offset:96
	s_waitcnt lgkmcnt(2)
	v_mfma_f32_32x32x16_bf16 v[18:33], v[148:151], v[136:139], v[18:33]
	ds_read_b128 v[136:139], v95 offset:18528
	s_waitcnt lgkmcnt(2)
	v_mfma_f32_32x32x16_bf16 v[34:49], v[144:147], v[140:143], v[34:49]
	ds_read_b128 v[144:147], v66 offset:4704
	v_mfma_f32_32x32x16_bf16 v[2:17], v[148:151], v[140:143], v[2:17]
	ds_read_b128 v[140:143], v95 offset:23136
	s_waitcnt lgkmcnt(2)
	v_mfma_f32_32x32x16_bf16 v[50:65], v[128:131], v[136:139], v[50:65]
	s_waitcnt lgkmcnt(1)
	v_mfma_f32_32x32x16_bf16 v[18:33], v[144:147], v[136:139], v[18:33]
	s_waitcnt lgkmcnt(0)
	v_mfma_f32_32x32x16_bf16 v[34:49], v[128:131], v[140:143], v[34:49]
	v_mfma_f32_32x32x16_bf16 v[2:17], v[144:147], v[140:143], v[2:17]
	s_add_i32 s2, s2, 2
	s_and_b32 s18, s2, 2
	s_add_u32 s16, s16, 0x80
	s_mulk_i32 s18, 0x4800
	s_addc_u32 s17, s17, 0
	v_add_u32_e32 v66, s18, v1
	s_cmpk_lg_i32 s16, 0x700
	s_waitcnt vmcnt(7)
	ds_write_b128 v66, v[96:99]
	v_lshl_add_u64 v[96:97], v[88:89], 0, s[16:17]
	v_add_co_u32_e32 v96, vcc, s24, v96
	s_nop 1
	v_addc_co_u32_e32 v97, vcc, 0, v97, vcc
	global_load_dwordx4 v[96:99], v[96:97], off offset:384
	s_waitcnt vmcnt(7)
	ds_write_b128 v66, v[100:103] offset:4608
	v_lshl_add_u64 v[100:101], v[88:89], 0, s[16:17]
	v_add_co_u32_e32 v100, vcc, s25, v100
	s_nop 1
	v_addc_co_u32_e32 v101, vcc, 0, v101, vcc
	global_load_dwordx4 v[100:103], v[100:101], off offset:384
	s_waitcnt vmcnt(7)
	ds_write_b128 v66, v[104:107] offset:9216
	v_lshl_add_u64 v[104:105], v[88:89], 0, s[16:17]
	v_add_co_u32_e32 v104, vcc, s26, v104
	s_nop 1
	v_addc_co_u32_e32 v105, vcc, 0, v105, vcc
	global_load_dwordx4 v[104:107], v[104:105], off offset:384
	s_waitcnt vmcnt(7)
	ds_write_b128 v66, v[108:111] offset:13824
	v_lshl_add_u64 v[108:109], v[88:89], 0, s[16:17]
	v_add_co_u32_e32 v108, vcc, s27, v108
	s_nop 1
	v_addc_co_u32_e32 v109, vcc, 0, v109, vcc
	global_load_dwordx4 v[108:111], v[108:109], off offset:384
	s_waitcnt vmcnt(7)
	ds_write_b128 v66, v[112:115] offset:18432
	v_lshl_add_u64 v[112:113], v[78:79], 0, s[16:17]
	v_add_co_u32_e32 v112, vcc, s28, v112
	s_nop 1
	v_addc_co_u32_e32 v113, vcc, 0, v113, vcc
	global_load_dwordx4 v[112:115], v[112:113], off offset:128
	s_waitcnt vmcnt(7)
	ds_write_b128 v66, v[116:119] offset:23040
	v_lshl_add_u64 v[116:117], v[78:79], 0, s[16:17]
	v_add_co_u32_e32 v116, vcc, s29, v116
	s_nop 1
	v_addc_co_u32_e32 v117, vcc, 0, v117, vcc
	global_load_dwordx4 v[116:119], v[116:117], off offset:128
	s_waitcnt vmcnt(7)
	ds_write_b128 v66, v[120:123] offset:27648
	v_lshl_add_u64 v[120:121], v[78:79], 0, s[16:17]
	v_add_co_u32_e32 v120, vcc, s30, v120
	s_nop 1
	v_addc_co_u32_e32 v121, vcc, 0, v121, vcc
	global_load_dwordx4 v[120:123], v[120:121], off offset:128
	s_waitcnt vmcnt(7)
	ds_write_b128 v66, v[124:127] offset:32256
	v_lshl_add_u64 v[124:125], v[78:79], 0, s[16:17]
	v_add_co_u32_e32 v124, vcc, s31, v124
	s_nop 1
	v_addc_co_u32_e32 v125, vcc, 0, v125, vcc
	global_load_dwordx4 v[124:127], v[124:125], off offset:128
	s_waitcnt lgkmcnt(0)
	s_barrier
	s_cbranch_scc1 .LBB0_722
;     ...
;   for (int kt = 0; kt < nk; ++kt) {
;     const int kn = (kt + 1 < nk) ? kt + 1 : kt;
;     GM_LOAD2(kn * 64, kn * bkstep)
;     __builtin_amdgcn_sched_barrier(0);
;     const char* As = smem + (kt & 1) * 2 * TILE_B;
;     const char* Bs = As + TILE_B;
;     if constexpr (HOIST) {
;       bf16x8 fa0[4], fa1[4], fb0[4], fb1[4];
; #pragma unroll
;       for (int st = 0; st < 4; ++st) {
;         fa0[st] = *(const bf16x8*)(As + aoff + st * 32);
;         fb0[st] = *(const bf16x8*)(Bs + boff + st * 32);
;         fa1[st] = *(const bf16x8*)(As + aoff + 32 * LSTR + st * 32);
;         fb1[st] = *(const bf16x8*)(Bs + boff + 32 * LSTR + st * 32);
;       }
;       __builtin_amdgcn_sched_barrier(0);
; #pragma unroll
;       for (int st = 0; st < 4; ++st) {
;         acc[0][0] = mfma32(fa0[st], fb0[st], acc[0][0]);
;         acc[0][1] = mfma32(fa0[st], fb1[st], acc[0][1]);
;         acc[1][0] = mfma32(fa1[st], fb0[st], acc[1][0]);
;         acc[1][1] = mfma32(fa1[st], fb1[st], acc[1][1]);
;       }
;     } else {
; #pragma unroll
;       for (int st = 0; st < 4; ++st) {
;         bf16x8 a0 = *(const bf16x8*)(As + aoff + st * 32);
;         bf16x8 a1 = *(const bf16x8*)(As + aoff + 32 * LSTR + st * 32);
;         bf16x8 b0 = *(const bf16x8*)(Bs + boff + st * 32);
;         bf16x8 b1 = *(const bf16x8*)(Bs + boff + 32 * LSTR + st * 32);
;         acc[0][0] = mfma32(a0, b0, acc[0][0]);
;         acc[0][1] = mfma32(a0, b1, acc[0][1]);
;         acc[1][0] = mfma32(a1, b0, acc[1][0]);
;         acc[1][1] = mfma32(a1, b1, acc[1][1]);
;       }
;     }
;     __builtin_amdgcn_sched_barrier(0);
;     {
;       char* Ad = smem + ((kt + 1) & 1) * 2 * TILE_B;
;       GM_STORE(Ad)
;     }
;     __syncthreads();
	s_and_b32 s18, s2, 2
	s_mulk_i32 s18, 0x4800
	v_add3_u32 v66, s18, v90, v91
	v_add3_u32 v95, s18, v92, v91
	ds_read_b128 v[128:131], v66 offset:0
	ds_read_b128 v[136:139], v95 offset:18432
	ds_read_b128 v[144:147], v66 offset:4608
	ds_read_b128 v[140:143], v95 offset:23040
	s_waitcnt lgkmcnt(2)
	v_mfma_f32_32x32x16_bf16 v[50:65], v[128:131], v[136:139], v[50:65]
	ds_read_b128 v[148:151], v66 offset:32
	s_waitcnt lgkmcnt(2)
	v_mfma_f32_32x32x16_bf16 v[18:33], v[144:147], v[136:139], v[18:33]
	ds_read_b128 v[136:139], v95 offset:18464
	s_waitcnt lgkmcnt(2)
	v_mfma_f32_32x32x16_bf16 v[34:49], v[128:131], v[140:143], v[34:49]
	ds_read_b128 v[128:131], v66 offset:4640
	v_mfma_f32_32x32x16_bf16 v[2:17], v[144:147], v[140:143], v[2:17]
	ds_read_b128 v[140:143], v95 offset:23072
	s_waitcnt lgkmcnt(2)
	v_mfma_f32_32x32x16_bf16 v[50:65], v[148:151], v[136:139], v[50:65]
	ds_read_b128 v[144:147], v66 offset:64
	s_waitcnt lgkmcnt(2)
	v_mfma_f32_32x32x16_bf16 v[18:33], v[128:131], v[136:139], v[18:33]
	ds_read_b128 v[136:139], v95 offset:18496
	s_waitcnt lgkmcnt(2)
	v_mfma_f32_32x32x16_bf16 v[34:49], v[148:151], v[140:143], v[34:49]
	ds_read_b128 v[148:151], v66 offset:4672
	v_mfma_f32_32x32x16_bf16 v[2:17], v[128:131], v[140:143], v[2:17]
	ds_read_b128 v[140:143], v95 offset:23104
	s_waitcnt lgkmcnt(2)
	v_mfma_f32_32x32x16_bf16 v[50:65], v[144:147], v[136:139], v[50:65]
	ds_read_b128 v[128:131], v66 offset:96
	s_waitcnt lgkmcnt(2)
	v_mfma_f32_32x32x16_bf16 v[18:33], v[148:151], v[136:139], v[18:33]
	ds_read_b128 v[136:139], v95 offset:18528
	s_waitcnt lgkmcnt(2)
	v_mfma_f32_32x32x16_bf16 v[34:49], v[144:147], v[140:143], v[34:49]
	ds_read_b128 v[144:147], v66 offset:4704
	v_mfma_f32_32x32x16_bf16 v[2:17], v[148:151], v[140:143], v[2:17]
	ds_read_b128 v[140:143], v95 offset:23136
	s_waitcnt lgkmcnt(2)
	v_mfma_f32_32x32x16_bf16 v[50:65], v[128:131], v[136:139], v[50:65]
	s_waitcnt lgkmcnt(1)
	v_mfma_f32_32x32x16_bf16 v[18:33], v[144:147], v[136:139], v[18:33]
	s_waitcnt lgkmcnt(0)
	v_mfma_f32_32x32x16_bf16 v[34:49], v[128:131], v[140:143], v[34:49]
	v_mfma_f32_32x32x16_bf16 v[2:17], v[144:147], v[140:143], v[2:17]
	s_add_i32 s2, s2, 2
	s_and_b32 s18, s2, 2
	s_add_u32 s16, s16, 0x80
	s_mulk_i32 s18, 0x4800
	s_addc_u32 s17, s17, 0
	v_add_u32_e32 v66, s18, v1
	s_waitcnt vmcnt(7)
	ds_write_b128 v66, v[96:99]
	s_waitcnt vmcnt(6)
	ds_write_b128 v66, v[100:103] offset:4608
	s_waitcnt vmcnt(5)
	ds_write_b128 v66, v[104:107] offset:9216
	s_waitcnt vmcnt(4)
	ds_write_b128 v66, v[108:111] offset:13824
	s_waitcnt vmcnt(3)
	ds_write_b128 v66, v[112:115] offset:18432
	s_waitcnt vmcnt(2)
	ds_write_b128 v66, v[116:119] offset:23040
	s_waitcnt vmcnt(1)
	ds_write_b128 v66, v[120:123] offset:27648
	s_waitcnt vmcnt(0)
	ds_write_b128 v66, v[124:127] offset:32256
	s_waitcnt lgkmcnt(0)
	s_barrier
	v_add_co_u32_e32 v104, vcc, 0x10000, v76
	s_nop 0
	s_nop 0
	s_nop 0
	v_addc_co_u32_e32 v105, vcc, 0, v77, vcc
	v_add_co_u32_e32 v108, vcc, 0x20000, v76
	s_nop 0
	v_addc_co_u32_e32 v109, vcc, 0, v77, vcc
	v_add_co_u32_e32 v76, vcc, 0x30000, v76
	s_lshl_b64 s[14:15], s[14:15], 7
	s_nop 0
	v_addc_co_u32_e32 v77, vcc, 0, v77, vcc
	s_nop 0
	v_add_u32_e32 v66, v90, v91
	v_add_u32_e32 v76, v92, v91
	ds_read_b128 v[116:119], v66 offset:36864
	ds_read_b128 v[120:123], v76 offset:55296
	ds_read_b128 v[128:131], v66 offset:41472
	ds_read_b128 v[124:127], v76 offset:59904
	s_waitcnt lgkmcnt(2)
	v_mfma_f32_32x32x16_bf16 v[50:65], v[116:119], v[120:123], v[50:65]
	ds_read_b128 v[136:139], v66 offset:36896
	s_waitcnt lgkmcnt(2)
	v_mfma_f32_32x32x16_bf16 v[18:33], v[128:131], v[120:123], v[18:33]
	ds_read_b128 v[120:123], v76 offset:55328
	s_waitcnt lgkmcnt(2)
	v_mfma_f32_32x32x16_bf16 v[34:49], v[116:119], v[124:127], v[34:49]
	ds_read_b128 v[116:119], v66 offset:41504
	v_mfma_f32_32x32x16_bf16 v[2:17], v[128:131], v[124:127], v[2:17]
	ds_read_b128 v[124:127], v76 offset:59936
	s_waitcnt lgkmcnt(2)
	v_mfma_f32_32x32x16_bf16 v[50:65], v[136:139], v[120:123], v[50:65]
	ds_read_b128 v[128:131], v66 offset:36928
	s_waitcnt lgkmcnt(2)
	v_mfma_f32_32x32x16_bf16 v[18:33], v[116:119], v[120:123], v[18:33]
	ds_read_b128 v[120:123], v76 offset:55360
	s_waitcnt lgkmcnt(2)
	v_mfma_f32_32x32x16_bf16 v[34:49], v[136:139], v[124:127], v[34:49]
	ds_read_b128 v[136:139], v66 offset:41536
	v_mfma_f32_32x32x16_bf16 v[2:17], v[116:119], v[124:127], v[2:17]
	ds_read_b128 v[124:127], v76 offset:59968
	s_waitcnt lgkmcnt(2)
	v_mfma_f32_32x32x16_bf16 v[50:65], v[128:131], v[120:123], v[50:65]
	ds_read_b128 v[116:119], v66 offset:36960
	s_waitcnt lgkmcnt(2)
	v_mfma_f32_32x32x16_bf16 v[18:33], v[136:139], v[120:123], v[18:33]
	ds_read_b128 v[120:123], v76 offset:55392
	s_waitcnt lgkmcnt(2)
	v_mfma_f32_32x32x16_bf16 v[34:49], v[128:131], v[124:127], v[34:49]
	ds_read_b128 v[128:131], v66 offset:41568
	v_mfma_f32_32x32x16_bf16 v[2:17], v[136:139], v[124:127], v[2:17]
	ds_read_b128 v[124:127], v76 offset:60000
	s_waitcnt lgkmcnt(2)
	v_mfma_f32_32x32x16_bf16 v[50:65], v[116:119], v[120:123], v[50:65]
	s_waitcnt lgkmcnt(1)
	v_mfma_f32_32x32x16_bf16 v[18:33], v[128:131], v[120:123], v[18:33]
	s_waitcnt lgkmcnt(0)
	v_mfma_f32_32x32x16_bf16 v[34:49], v[116:119], v[124:127], v[34:49]
	v_mfma_f32_32x32x16_bf16 v[2:17], v[128:131], v[124:127], v[2:17]
	s_waitcnt lgkmcnt(0)
	s_barrier
; __device__ __forceinline__ void acc_to_lds(const f32x16 (&acc)[2][2], float* cs) {
;   const int tid = threadIdx.x, lane = tid & 63, wave = tid >> 6;
;   const int wm = wave >> 1, wn = wave & 1;
; #pragma unroll
;   for (int i = 0; i < 2; ++i)
; #pragma unroll
;     for (int j = 0; j < 2; ++j)
; #pragma unroll
;       for (int r = 0; r < 16; ++r) {
;         int row = wm * 64 + i * 32 + (r & 3) + 8 * (r >> 2) + 4 * (lane >> 5);
;         int col = wn * 64 + j * 32 + (lane & 31);
;         cs[row * CSTR + col] = acc[i][j][r];
;       }
;   __syncthreads();
; template <bool WIDE>
; __device__ __forceinline__ void outproj_tile(const Params& P, int l, int mt, int nt, char* smem) {
;     ...
;   for (int hsel = 0; hsel < (WIDE ? 2 : 1); ++hsel) {
;     if constexpr (WIDE) wide_acc_to_lds(accw, cs, hsel); else acc_to_lds(accn, cs);
;     int tid_ = threadIdx.x;
;     asm volatile("" : "+v"(tid_));
;     const int lane = tid_ & 63, wave = tid_ >> 6;
;     const int r = 32 * wave + (lane & 31), half = lane >> 5;
;     const size_t grow = (size_t)mt * 128 + r;
;     const bool isctx = grow >= NLAT;
;     const int modrow = isctx ? 8 : (int)(grow >> 12);
;     const int col = (nt + hsel) * 128 + half * 64;
;     const float* g1 = WSP(float, OFF_MOD) + ((size_t)l * 9 + modrow) * 6144 + 2048 + col;
;     const float* xin;
;     float* xo;
;     if (!isctx) { xin = (l == 0 ? P.x : P.out) + grow * DM + col; xo = P.out + grow * DM + col; }
;     else { xin = (l == 0 ? P.ctx : WSP(float, OFF_XC)) + (grow - NLAT) * DM + col; xo = WSP(float, OFF_XC) + (grow - NLAT) * DM + col; }
	ds_write2_b32 v93, v50, v34 offset1:32
	ds_write2_b32 v93, v51, v35 offset0:132 offset1:164
	v_add_u32_e32 v34, 0x400, v93
	ds_write2_b32 v34, v52, v36 offset0:8 offset1:40
	ds_write2_b32 v34, v53, v37 offset0:140 offset1:172
	v_add_u32_e32 v34, 0x1000, v93
	ds_write2_b32 v34, v54, v38 offset0:32 offset1:64
	ds_write2_b32 v34, v55, v39 offset0:164 offset1:196
	v_add_u32_e32 v34, 0x1400, v93
	ds_write2_b32 v34, v56, v40 offset0:40 offset1:72
	ds_write2_b32 v34, v57, v41 offset0:172 offset1:204
	v_add_u32_e32 v34, 0x2000, v93
	ds_write2_b32 v34, v58, v42 offset0:64 offset1:96
	ds_write2_b32 v34, v59, v43 offset0:196 offset1:228
	v_add_u32_e32 v34, 0x2400, v93
	ds_write2_b32 v34, v60, v44 offset0:72 offset1:104
	ds_write2_b32 v34, v61, v45 offset0:204 offset1:236
	v_add_u32_e32 v34, 0x3000, v93
	ds_write2_b32 v34, v62, v46 offset0:96 offset1:128
	v_add_u32_e32 v34, 0x3200, v93
	ds_write2_b32 v34, v63, v47 offset0:100 offset1:132
	v_add_u32_e32 v34, 0x3400, v93
	ds_write2_b32 v34, v64, v48 offset0:104 offset1:136
	v_add_u32_e32 v34, 0x3600, v93
	ds_write2_b32 v34, v65, v49 offset0:108 offset1:140
	v_add_u32_e32 v34, 0x4000, v93
	ds_write2_b32 v34, v18, v2 offset0:128 offset1:160
	v_add_u32_e32 v2, 0x4400, v93
	ds_write2_b32 v2, v19, v3 offset0:4 offset1:36
	ds_write2_b32 v2, v20, v4 offset0:136 offset1:168
	v_add_u32_e32 v2, 0x4800, v93
	ds_write2_b32 v2, v21, v5 offset0:12 offset1:44
	v_add_u32_e32 v2, 0x5000, v93
	ds_write2_b32 v2, v22, v6 offset0:160 offset1:192
	v_add_u32_e32 v2, 0x5400, v93
	ds_write2_b32 v2, v23, v7 offset0:36 offset1:68
	ds_write2_b32 v2, v24, v8 offset0:168 offset1:200
	v_add_u32_e32 v2, 0x5800, v93
	ds_write2_b32 v2, v25, v9 offset0:44 offset1:76
	v_add_u32_e32 v2, 0x6000, v93
	ds_write2_b32 v2, v26, v10 offset0:192 offset1:224
	v_add_u32_e32 v2, 0x6400, v93
	ds_write2_b32 v2, v27, v11 offset0:68 offset1:100
	ds_write2_b32 v2, v28, v12 offset0:200 offset1:232
	v_add_u32_e32 v2, 0x6800, v93
	ds_write2_b32 v2, v29, v13 offset0:76 offset1:108
	v_add_u32_e32 v2, 0x7200, v93
	ds_write2_b32 v2, v30, v14 offset0:96 offset1:128
	v_add_u32_e32 v2, 0x7400, v93
	ds_write2_b32 v2, v31, v15 offset0:100 offset1:132
	v_add_u32_e32 v2, 0x7600, v93
	ds_write2_b32 v2, v32, v16 offset0:104 offset1:136
	v_add_u32_e32 v2, 0x7800, v93
	v_mov_b32_e32 v12, v134
	ds_write2_b32 v2, v33, v17 offset0:108 offset1:140
	s_waitcnt lgkmcnt(0)
	s_barrier
	s_nop 0
	v_ashrrev_i32_e32 v2, 1, v12
	v_bfi_b32 v2, s33, v2, v12
	v_ashrrev_i32_e32 v3, 31, v2
	v_lshl_add_u64 v[4:5], s[14:15], 0, v[2:3]
	v_cmp_gt_u64_e32 vcc, s[10:11], v[4:5]
	v_lshlrev_b64 v[10:11], 10, v[4:5]
	s_and_saveexec_b64 s[14:15], vcc
	s_xor_b64 s[14:15], exec, s[14:15]
	s_cbranch_execz .LBB0_725
	v_readlane_b32 s56, v253, 21
	v_lshlrev_b64 v[8:9], 2, v[10:11]
	v_readlane_b32 s57, v253, 22
	v_readlane_b32 s58, v253, 23
	v_readlane_b32 s59, v253, 24
	v_lshl_add_u64 v[6:7], s[56:57], 0, v[8:9]
	v_lshl_add_u64 v[8:9], s[88:89], 0, v[8:9]
	v_readlane_b32 s60, v253, 25
	v_readlane_b32 s61, v253, 26
	v_readlane_b32 s62, v253, 27
	v_readlane_b32 s63, v253, 28
	v_readlane_b32 s64, v253, 29
	v_readlane_b32 s65, v253, 30
	v_readlane_b32 s66, v253, 31
	v_readlane_b32 s67, v253, 32
	v_readlane_b32 s68, v253, 33
	v_readlane_b32 s69, v253, 34
	v_readlane_b32 s70, v253, 35
	v_readlane_b32 s71, v253, 36

; #define GM_LOAD(KOFF) GM_LOAD2(KOFF, 0)
;     ...
;   const u16* ap0 = arow(lr) + kc * 8;
;   const u16* ap1 = arow(lr + 32) + kc * 8;
;   const u16* ap2 = arow(lr + 64) + kc * 8;
;   const u16* ap3 = arow(lr + 96) + kc * 8;
;   const u16* bp0 = Bt + (size_t)lr * ldb + kc * 8;
;   const size_t bstep = 32 * ldb;
;   const int so = lr * LSTR + kc * 16;
;   uint4 ra0, ra1, ra2, ra3, rb0, rb1, rb2, rb3;
;     ...
;   GM_LOAD(0)
;   GM_STORE(smem)
;   __syncthreads();
; __device__ __forceinline__ void expert2_tile_narrow(const Params& P, int e, int mt, int nt, char* smem) {
;   f32x16 acc[2][2];
;   zero_acc(acc);
;   const u16* A = WSP(u16, OFF_HID) + ((size_t)e * EROWS + mt * 128) * 2048;
;   const u16* Bt = WSP(u16, OFF_WDN) + (size_t)e * DM * 2048 + (size_t)nt * 128 * 64;
;   gemm_main([&](int rr) { return A + (size_t)rr * 2048; }, Bt, 64, 2048, smem, acc, 1024 * 64);
.LBB0_1120:
	s_and_b32 s2, s34, 7
	s_lshl_b32 s36, s35, 4
	s_lshl_b32 s42, s2, 14
	s_lshl_b32 s2, s19, 12
	s_ashr_i32 s14, s35, 4
	s_and_b32 s36, s36, 0x80
	s_and_b32 s43, s2, 0x80000
	s_and_b32 s2, s35, 7
	s_ashr_i32 s15, s14, 31
	s_mul_i32 s12, s14, 0x1100
	s_bitset1_b32 s36, 12
	s_mul_hi_i32 s13, s14, 0x1100
	s_add_u32 s12, s12, s36
	s_addc_u32 s13, s13, 0
	s_lshl_b64 s[36:37], s[12:13], 12
	s_lshl_b64 s[38:39], s[14:15], 22
	s_add_u32 s15, s17, s38
	s_addc_u32 s41, s18, s39
	s_lshl_b32 s40, s2, 14
	s_add_u32 s40, s15, s40
	s_addc_u32 s41, s41, 0
	v_lshl_add_u64 v[2:3], v[72:73], 0, s[36:37]
	v_lshl_add_u64 v[82:83], v[2:3], 0, v[76:77]
	v_lshl_add_u64 v[2:3], s[40:41], 0, v[78:79]
	v_lshl_add_u64 v[80:81], v[2:3], 0, v[76:77]
	v_add_co_u32_e32 v2, vcc, s21, v82
	s_mul_hi_i32 s37, s14, 0x1100000
	s_nop 0
	v_addc_co_u32_e32 v3, vcc, 0, v83, vcc
	v_add_co_u32_e32 v4, vcc, s22, v82
	s_mul_i32 s14, s14, 0x1100000
	s_nop 0
	v_addc_co_u32_e32 v5, vcc, 0, v83, vcc
	global_load_dwordx4 v[22:25], v[2:3], off
	global_load_dwordx4 v[26:29], v[4:5], off
	v_add_co_u32_e32 v2, vcc, s23, v82
	s_or_b32 s38, s38, s42
	s_nop 0
	v_addc_co_u32_e32 v3, vcc, 0, v83, vcc
	global_load_dwordx4 v[30:33], v[2:3], off
	global_load_dwordx4 v[34:37], v[82:83], off
	global_load_dwordx4 v[38:41], v[80:81], off
	v_add_co_u32_e32 v2, vcc, s24, v80
	s_or_b32 s36, s14, s43
	s_nop 0
	v_addc_co_u32_e32 v3, vcc, 0, v81, vcc
	global_load_dwordx4 v[42:45], v[2:3], off offset:-4096
	global_load_dwordx4 v[46:49], v[2:3], off
	v_add_co_u32_e32 v2, vcc, s25, v80
	s_mov_b32 s15, 0
	s_nop 0
	v_addc_co_u32_e32 v3, vcc, 0, v81, vcc
	global_load_dwordx4 v[50:53], v[2:3], off
	v_mov_b32_e32 v2, 0
	v_mov_b32_e32 v3, v67
	v_mov_b32_e32 v4, v67
	v_mov_b32_e32 v5, v67
	v_mov_b32_e32 v6, v67
	v_mov_b32_e32 v7, v67
	v_mov_b32_e32 v8, v67
	v_mov_b32_e32 v9, v67
	v_mov_b32_e32 v10, v67
	v_mov_b32_e32 v11, v67
	v_mov_b32_e32 v12, v67
	v_mov_b32_e32 v13, v67
	v_mov_b32_e32 v14, v67
	v_mov_b32_e32 v15, v67
	v_mov_b32_e32 v16, v67
	v_mov_b32_e32 v17, v67
	v_mov_b32_e32 v18, 0
	v_mov_b32_e32 v19, v67
	v_mov_b32_e32 v20, v67
	v_mov_b32_e32 v21, v67
	v_lshl_add_u64 v[84:85], v[82:83], 0, s[4:5]
	v_lshl_add_u64 v[86:87], v[82:83], 0, s[6:7]
	v_lshl_add_u64 v[88:89], v[82:83], 0, s[8:9]
	v_lshl_add_u64 v[90:91], v[74:75], 0, s[38:39]
	v_lshl_add_u64 v[92:93], v[70:71], 0, s[36:37]
	v_mov_b32_e32 v54, v67
	v_mov_b32_e32 v55, v67
	v_mov_b32_e32 v56, v67
	v_mov_b32_e32 v57, v67
	v_mov_b32_e32 v58, v67
	v_mov_b32_e32 v59, v67
	v_mov_b32_e32 v60, v67
	v_mov_b32_e32 v61, v67
	v_mov_b32_e32 v62, v67
	v_mov_b32_e32 v63, v67
	v_mov_b32_e32 v64, v67
	v_mov_b32_e32 v65, v67
	s_waitcnt vmcnt(4)
	ds_write_b128 v1, v[34:37]
	ds_write_b128 v1, v[22:25] offset:4608
	ds_write_b128 v1, v[26:29] offset:9216
	ds_write_b128 v1, v[30:33] offset:13824
	s_waitcnt vmcnt(3)
	ds_write_b128 v1, v[38:41] offset:18432
	s_waitcnt vmcnt(2)
	ds_write_b128 v1, v[42:45] offset:23040
	s_waitcnt vmcnt(1)
	ds_write_b128 v1, v[46:49] offset:27648
	s_waitcnt vmcnt(0)
	ds_write_b128 v1, v[50:53] offset:32256
	v_mov_b32_e32 v22, v67
	v_mov_b32_e32 v23, v67
	v_mov_b32_e32 v24, v67
	v_mov_b32_e32 v25, v67
	v_mov_b32_e32 v26, v67
	v_mov_b32_e32 v27, v67
	v_mov_b32_e32 v28, v67
	v_mov_b32_e32 v29, v67
	v_mov_b32_e32 v30, v67
	v_mov_b32_e32 v31, v67
	v_mov_b32_e32 v32, v67
	v_mov_b32_e32 v33, v67
	v_mov_b32_e32 v50, 0
	v_mov_b32_e32 v51, v67
	v_mov_b32_e32 v52, v67
	v_mov_b32_e32 v53, v67
	v_mov_b32_e32 v34, 0
	v_mov_b32_e32 v35, v67
	v_mov_b32_e32 v36, v67
	v_mov_b32_e32 v37, v67
	v_mov_b32_e32 v38, v67
	v_mov_b32_e32 v39, v67
	v_mov_b32_e32 v40, v67
	v_mov_b32_e32 v41, v67
	v_mov_b32_e32 v42, v67
	v_mov_b32_e32 v43, v67
	v_mov_b32_e32 v44, v67
	v_mov_b32_e32 v45, v67
	v_mov_b32_e32 v46, v67
	v_mov_b32_e32 v47, v67
	v_mov_b32_e32 v48, v67
	v_mov_b32_e32 v49, v67
	s_waitcnt lgkmcnt(0)
	s_barrier
	v_lshl_add_u64 v[106:107], v[92:93], 0, v[68:69]
	v_add_co_u32_e32 v98, vcc, s26, v106
	v_lshl_add_u64 v[122:123], v[90:91], 0, v[68:69]
	s_nop 0
	v_addc_co_u32_e32 v99, vcc, 0, v107, vcc
	v_add_co_u32_e32 v102, vcc, s27, v106
	s_nop 1
	v_addc_co_u32_e32 v103, vcc, 0, v107, vcc
	v_add_co_u32_e32 v108, vcc, s28, v106
	global_load_dwordx4 v[98:101], v[98:99], off offset:384
	s_nop 0
	global_load_dwordx4 v[102:105], v[102:103], off offset:384
	v_addc_co_u32_e32 v109, vcc, 0, v107, vcc
	v_add_co_u32_e32 v110, vcc, s29, v106
	s_nop 1
	v_addc_co_u32_e32 v111, vcc, 0, v107, vcc
	v_add_co_u32_e32 v118, vcc, s30, v122
	global_load_dwordx4 v[106:109], v[108:109], off offset:384
	s_nop 0
	global_load_dwordx4 v[110:113], v[110:111], off offset:384
	v_addc_co_u32_e32 v119, vcc, 0, v123, vcc
	v_add_co_u32_e32 v126, vcc, s31, v122
	global_load_dwordx4 v[114:117], v[118:119], off offset:-4096
	s_nop 0
	global_load_dwordx4 v[118:121], v[118:119], off
	v_addc_co_u32_e32 v127, vcc, 0, v123, vcc
	global_load_dwordx4 v[122:125], v[126:127], off offset:-4096
	s_nop 0
	global_load_dwordx4 v[126:129], v[126:127], off
;     ...
;   for (int kt = 0; kt < nk; ++kt) {
;     const int kn = (kt + 1 < nk) ? kt + 1 : kt;
;     GM_LOAD2(kn * 64, kn * bkstep)
;     __builtin_amdgcn_sched_barrier(0);
;     const char* As = smem + (kt & 1) * 2 * TILE_B;
;     const char* Bs = As + TILE_B;
;     if constexpr (HOIST) {
;       bf16x8 fa0[4], fa1[4], fb0[4], fb1[4];
; #pragma unroll
;       for (int st = 0; st < 4; ++st) {
;         fa0[st] = *(const bf16x8*)(As + aoff + st * 32);
;         fb0[st] = *(const bf16x8*)(Bs + boff + st * 32);
;         fa1[st] = *(const bf16x8*)(As + aoff + 32 * LSTR + st * 32);
;         fb1[st] = *(const bf16x8*)(Bs + boff + 32 * LSTR + st * 32);
;       }
;       __builtin_amdgcn_sched_barrier(0);
; #pragma unroll
;       for (int st = 0; st < 4; ++st) {
;         acc[0][0] = mfma32(fa0[st], fb0[st], acc[0][0]);
;         acc[0][1] = mfma32(fa0[st], fb1[st], acc[0][1]);
;         acc[1][0] = mfma32(fa1[st], fb0[st], acc[1][0]);
;         acc[1][1] = mfma32(fa1[st], fb1[st], acc[1][1]);
;       }
;     } else {
; #pragma unroll
;       for (int st = 0; st < 4; ++st) {
;         bf16x8 a0 = *(const bf16x8*)(As + aoff + st * 32);
;         bf16x8 a1 = *(const bf16x8*)(As + aoff + 32 * LSTR + st * 32);
;         bf16x8 b0 = *(const bf16x8*)(Bs + boff + st * 32);
;         bf16x8 b1 = *(const bf16x8*)(Bs + boff + 32 * LSTR + st * 32);
;         acc[0][0] = mfma32(a0, b0, acc[0][0]);
;         acc[0][1] = mfma32(a0, b1, acc[0][1]);
;         acc[1][0] = mfma32(a1, b0, acc[1][0]);
;         acc[1][1] = mfma32(a1, b1, acc[1][1]);
;       }
;     }
;     __builtin_amdgcn_sched_barrier(0);
;     {
;       char* Ad = smem + ((kt + 1) & 1) * 2 * TILE_B;
;       GM_STORE(Ad)
;     }
;     __syncthreads();
.LBB0_1121:
	s_and_b32 s14, s15, 2
	s_mulk_i32 s14, 0x4800
	v_add3_u32 v66, s14, v94, v95
	v_add3_u32 v135, s14, v96, v95
	ds_read_b128 v[130:133], v66 offset:0
	ds_read_b128 v[136:139], v135 offset:18432
	ds_read_b128 v[144:147], v66 offset:4608
	ds_read_b128 v[140:143], v135 offset:23040
	s_waitcnt lgkmcnt(2)
	v_mfma_f32_32x32x16_bf16 v[50:65], v[130:133], v[136:139], v[50:65]
	ds_read_b128 v[148:151], v66 offset:32
	s_waitcnt lgkmcnt(2)
	v_mfma_f32_32x32x16_bf16 v[2:17], v[144:147], v[136:139], v[2:17]
	ds_read_b128 v[136:139], v135 offset:18464
	s_waitcnt lgkmcnt(2)
	v_mfma_f32_32x32x16_bf16 v[18:33], v[130:133], v[140:143], v[18:33]
	ds_read_b128 v[130:133], v66 offset:4640
	v_mfma_f32_32x32x16_bf16 v[34:49], v[144:147], v[140:143], v[34:49]
	ds_read_b128 v[140:143], v135 offset:23072
	s_waitcnt lgkmcnt(2)
	v_mfma_f32_32x32x16_bf16 v[50:65], v[148:151], v[136:139], v[50:65]
	ds_read_b128 v[144:147], v66 offset:64
	s_waitcnt lgkmcnt(2)
	v_mfma_f32_32x32x16_bf16 v[2:17], v[130:133], v[136:139], v[2:17]
	ds_read_b128 v[136:139], v135 offset:18496
	s_waitcnt lgkmcnt(2)
	v_mfma_f32_32x32x16_bf16 v[18:33], v[148:151], v[140:143], v[18:33]
	ds_read_b128 v[148:151], v66 offset:4672
	v_mfma_f32_32x32x16_bf16 v[34:49], v[130:133], v[140:143], v[34:49]
	ds_read_b128 v[140:143], v135 offset:23104
	s_waitcnt lgkmcnt(2)
	v_mfma_f32_32x32x16_bf16 v[50:65], v[144:147], v[136:139], v[50:65]
	ds_read_b128 v[130:133], v66 offset:96
	s_waitcnt lgkmcnt(2)
	v_mfma_f32_32x32x16_bf16 v[2:17], v[148:151], v[136:139], v[2:17]
	ds_read_b128 v[136:139], v135 offset:18528
	s_waitcnt lgkmcnt(2)
	v_mfma_f32_32x32x16_bf16 v[18:33], v[144:147], v[140:143], v[18:33]
	ds_read_b128 v[144:147], v66 offset:4704
	v_mfma_f32_32x32x16_bf16 v[34:49], v[148:151], v[140:143], v[34:49]
	ds_read_b128 v[140:143], v135 offset:23136
	s_waitcnt lgkmcnt(2)
	v_mfma_f32_32x32x16_bf16 v[50:65], v[130:133], v[136:139], v[50:65]
	s_waitcnt lgkmcnt(1)
	v_mfma_f32_32x32x16_bf16 v[2:17], v[144:147], v[136:139], v[2:17]
	s_waitcnt lgkmcnt(0)
	v_mfma_f32_32x32x16_bf16 v[18:33], v[130:133], v[140:143], v[18:33]
	v_mfma_f32_32x32x16_bf16 v[34:49], v[144:147], v[140:143], v[34:49]
	s_add_i32 s15, s15, 2
	s_and_b32 s14, s15, 2
	s_mulk_i32 s14, 0x4800
	v_add_u32_e32 v66, s14, v1
	v_lshl_add_u64 v[90:91], v[90:91], 0, s[4:5]
	v_lshl_add_u64 v[92:93], v[92:93], 0, s[10:11]
	s_cmp_lg_u32 s15, 60
	s_waitcnt vmcnt(7)
	ds_write_b128 v66, v[98:101]
	v_lshl_add_u64 v[98:99], v[92:93], 0, v[68:69]
	v_add_co_u32_e32 v98, vcc, s26, v98
	s_nop 1
	v_addc_co_u32_e32 v99, vcc, 0, v99, vcc
	global_load_dwordx4 v[98:101], v[98:99], off offset:384
	s_waitcnt vmcnt(7)
	ds_write_b128 v66, v[102:105] offset:4608
	v_lshl_add_u64 v[102:103], v[92:93], 0, v[68:69]
	v_add_co_u32_e32 v102, vcc, s27, v102
	s_nop 1
	v_addc_co_u32_e32 v103, vcc, 0, v103, vcc
	global_load_dwordx4 v[102:105], v[102:103], off offset:384
	s_waitcnt vmcnt(7)
	ds_write_b128 v66, v[106:109] offset:9216
	v_lshl_add_u64 v[106:107], v[92:93], 0, v[68:69]
	v_add_co_u32_e32 v106, vcc, s28, v106
	s_nop 1
	v_addc_co_u32_e32 v107, vcc, 0, v107, vcc
	global_load_dwordx4 v[106:109], v[106:107], off offset:384
	s_waitcnt vmcnt(7)
	ds_write_b128 v66, v[110:113] offset:13824
	v_lshl_add_u64 v[110:111], v[92:93], 0, v[68:69]
	v_add_co_u32_e32 v110, vcc, s29, v110
	s_nop 1
	v_addc_co_u32_e32 v111, vcc, 0, v111, vcc
	global_load_dwordx4 v[110:113], v[110:111], off offset:384
	s_waitcnt vmcnt(7)
	ds_write_b128 v66, v[114:117] offset:18432
	v_lshl_add_u64 v[114:115], v[90:91], 0, v[68:69]
	v_add_co_u32_e32 v114, vcc, s30, v114
	s_nop 1
	v_addc_co_u32_e32 v115, vcc, 0, v115, vcc
	global_load_dwordx4 v[114:117], v[114:115], off offset:-4096
	s_waitcnt vmcnt(7)
	ds_write_b128 v66, v[118:121] offset:23040
	v_lshl_add_u64 v[118:119], v[90:91], 0, v[68:69]
	v_add_co_u32_e32 v118, vcc, s30, v118
	s_nop 1
	v_addc_co_u32_e32 v119, vcc, 0, v119, vcc
	global_load_dwordx4 v[118:121], v[118:119], off
	s_waitcnt vmcnt(7)
	ds_write_b128 v66, v[122:125] offset:27648
	v_lshl_add_u64 v[122:123], v[90:91], 0, v[68:69]
	v_add_co_u32_e32 v122, vcc, s31, v122
	s_nop 1
	v_addc_co_u32_e32 v123, vcc, 0, v123, vcc
	global_load_dwordx4 v[122:125], v[122:123], off offset:-4096
	s_waitcnt vmcnt(7)
	ds_write_b128 v66, v[126:129] offset:32256
	v_lshl_add_u64 v[126:127], v[90:91], 0, v[68:69]
	v_add_co_u32_e32 v126, vcc, s31, v126
	s_nop 1
	v_addc_co_u32_e32 v127, vcc, 0, v127, vcc
	global_load_dwordx4 v[126:129], v[126:127], off
	s_waitcnt lgkmcnt(0)
	s_barrier
	s_cbranch_scc1 .LBB0_1121
;     ...
;   for (int kt = 0; kt < nk; ++kt) {
;     const int kn = (kt + 1 < nk) ? kt + 1 : kt;
;     GM_LOAD2(kn * 64, kn * bkstep)
;     __builtin_amdgcn_sched_barrier(0);
;     const char* As = smem + (kt & 1) * 2 * TILE_B;
;     const char* Bs = As + TILE_B;
;     if constexpr (HOIST) {
;       bf16x8 fa0[4], fa1[4], fb0[4], fb1[4];
; #pragma unroll
;       for (int st = 0; st < 4; ++st) {
;         fa0[st] = *(const bf16x8*)(As + aoff + st * 32);
;         fb0[st] = *(const bf16x8*)(Bs + boff + st * 32);
;         fa1[st] = *(const bf16x8*)(As + aoff + 32 * LSTR + st * 32);
;         fb1[st] = *(const bf16x8*)(Bs + boff + 32 * LSTR + st * 32);
;       }
;       __builtin_amdgcn_sched_barrier(0);
; #pragma unroll
;       for (int st = 0; st < 4; ++st) {
;         acc[0][0] = mfma32(fa0[st], fb0[st], acc[0][0]);
;         acc[0][1] = mfma32(fa0[st], fb1[st], acc[0][1]);
;         acc[1][0] = mfma32(fa1[st], fb0[st], acc[1][0]);
;         acc[1][1] = mfma32(fa1[st], fb1[st], acc[1][1]);
;       }
;     } else {
; #pragma unroll
;       for (int st = 0; st < 4; ++st) {
;         bf16x8 a0 = *(const bf16x8*)(As + aoff + st * 32);
;         bf16x8 a1 = *(const bf16x8*)(As + aoff + 32 * LSTR + st * 32);
;         bf16x8 b0 = *(const bf16x8*)(Bs + boff + st * 32);
;         bf16x8 b1 = *(const bf16x8*)(Bs + boff + 32 * LSTR + st * 32);
;         acc[0][0] = mfma32(a0, b0, acc[0][0]);
;         acc[0][1] = mfma32(a0, b1, acc[0][1]);
;         acc[1][0] = mfma32(a1, b0, acc[1][0]);
;         acc[1][1] = mfma32(a1, b1, acc[1][1]);
;       }
;     }
;     __builtin_amdgcn_sched_barrier(0);
;     {
;       char* Ad = smem + ((kt + 1) & 1) * 2 * TILE_B;
;       GM_STORE(Ad)
;     }
;     __syncthreads();
	s_and_b32 s14, s15, 2
	s_mulk_i32 s14, 0x4800
	v_add3_u32 v66, s14, v94, v95
	v_add3_u32 v135, s14, v96, v95
	ds_read_b128 v[130:133], v66 offset:0
	ds_read_b128 v[136:139], v135 offset:18432
	ds_read_b128 v[144:147], v66 offset:4608
	ds_read_b128 v[140:143], v135 offset:23040
	s_waitcnt lgkmcnt(2)
	v_mfma_f32_32x32x16_bf16 v[50:65], v[130:133], v[136:139], v[50:65]
	ds_read_b128 v[148:151], v66 offset:32
	s_waitcnt lgkmcnt(2)
	v_mfma_f32_32x32x16_bf16 v[2:17], v[144:147], v[136:139], v[2:17]
	ds_read_b128 v[136:139], v135 offset:18464
	s_waitcnt lgkmcnt(2)
	v_mfma_f32_32x32x16_bf16 v[18:33], v[130:133], v[140:143], v[18:33]
	ds_read_b128 v[130:133], v66 offset:4640
	v_mfma_f32_32x32x16_bf16 v[34:49], v[144:147], v[140:143], v[34:49]
	ds_read_b128 v[140:143], v135 offset:23072
	s_waitcnt lgkmcnt(2)
	v_mfma_f32_32x32x16_bf16 v[50:65], v[148:151], v[136:139], v[50:65]
	ds_read_b128 v[144:147], v66 offset:64
	s_waitcnt lgkmcnt(2)
	v_mfma_f32_32x32x16_bf16 v[2:17], v[130:133], v[136:139], v[2:17]
	ds_read_b128 v[136:139], v135 offset:18496
	s_waitcnt lgkmcnt(2)
	v_mfma_f32_32x32x16_bf16 v[18:33], v[148:151], v[140:143], v[18:33]
	ds_read_b128 v[148:151], v66 offset:4672
	v_mfma_f32_32x32x16_bf16 v[34:49], v[130:133], v[140:143], v[34:49]
	ds_read_b128 v[140:143], v135 offset:23104
	s_waitcnt lgkmcnt(2)
	v_mfma_f32_32x32x16_bf16 v[50:65], v[144:147], v[136:139], v[50:65]
	ds_read_b128 v[130:133], v66 offset:96
	s_waitcnt lgkmcnt(2)
	v_mfma_f32_32x32x16_bf16 v[2:17], v[148:151], v[136:139], v[2:17]
	ds_read_b128 v[136:139], v135 offset:18528
	s_waitcnt lgkmcnt(2)
	v_mfma_f32_32x32x16_bf16 v[18:33], v[144:147], v[140:143], v[18:33]
	ds_read_b128 v[144:147], v66 offset:4704
	v_mfma_f32_32x32x16_bf16 v[34:49], v[148:151], v[140:143], v[34:49]
	ds_read_b128 v[140:143], v135 offset:23136
	s_waitcnt lgkmcnt(2)
	v_mfma_f32_32x32x16_bf16 v[50:65], v[130:133], v[136:139], v[50:65]
	s_waitcnt lgkmcnt(1)
	v_mfma_f32_32x32x16_bf16 v[2:17], v[144:147], v[136:139], v[2:17]
	s_waitcnt lgkmcnt(0)
	v_mfma_f32_32x32x16_bf16 v[18:33], v[130:133], v[140:143], v[18:33]
	v_mfma_f32_32x32x16_bf16 v[34:49], v[144:147], v[140:143], v[34:49]
	s_add_i32 s15, s15, 2
	s_and_b32 s14, s15, 2
	s_mulk_i32 s14, 0x4800
	v_add_u32_e32 v66, s14, v1
	v_lshl_add_u64 v[90:91], v[90:91], 0, s[4:5]
	v_lshl_add_u64 v[92:93], v[92:93], 0, s[10:11]
	s_waitcnt vmcnt(7)
	ds_write_b128 v66, v[98:101]
	s_waitcnt vmcnt(6)
	ds_write_b128 v66, v[102:105] offset:4608
	s_waitcnt vmcnt(5)
	ds_write_b128 v66, v[106:109] offset:9216
	s_waitcnt vmcnt(4)
	ds_write_b128 v66, v[110:113] offset:13824
	s_waitcnt vmcnt(3)
	ds_write_b128 v66, v[114:117] offset:18432
	s_waitcnt vmcnt(2)
	ds_write_b128 v66, v[118:121] offset:23040
	s_waitcnt vmcnt(1)
	ds_write_b128 v66, v[122:125] offset:27648
	s_waitcnt vmcnt(0)
	ds_write_b128 v66, v[126:129] offset:32256
	s_waitcnt lgkmcnt(0)
	s_barrier
	v_add_co_u32_e32 v102, vcc, 0x3e0000, v80
	s_nop 0
	s_nop 0
	s_nop 0
	v_addc_co_u32_e32 v103, vcc, 0, v81, vcc
	v_add_co_u32_e32 v106, vcc, 0x3e1000, v80
	s_nop 1
	v_addc_co_u32_e32 v107, vcc, 0, v81, vcc
	v_add_co_u32_e32 v110, vcc, 0x3e2000, v80
	s_nop 0
	v_addc_co_u32_e32 v111, vcc, 0, v81, vcc
	v_add_co_u32_e32 v80, vcc, 0x3e3000, v80
	s_nop 1
	v_addc_co_u32_e32 v81, vcc, 0, v81, vcc
	s_nop 0
	v_add_u32_e32 v66, v94, v95
	v_add_u32_e32 v80, v96, v95
	ds_read_b128 v[118:121], v66 offset:36864
	ds_read_b128 v[122:125], v80 offset:55296
	ds_read_b128 v[130:133], v66 offset:41472
	ds_read_b128 v[126:129], v80 offset:59904
	s_waitcnt lgkmcnt(2)
	v_mfma_f32_32x32x16_bf16 v[50:65], v[118:121], v[122:125], v[50:65]
	ds_read_b128 v[136:139], v66 offset:36896
	s_waitcnt lgkmcnt(2)
	v_mfma_f32_32x32x16_bf16 v[2:17], v[130:133], v[122:125], v[2:17]
	ds_read_b128 v[122:125], v80 offset:55328
	s_waitcnt lgkmcnt(2)
	v_mfma_f32_32x32x16_bf16 v[18:33], v[118:121], v[126:129], v[18:33]
	ds_read_b128 v[118:121], v66 offset:41504
	v_mfma_f32_32x32x16_bf16 v[34:49], v[130:133], v[126:129], v[34:49]
	ds_read_b128 v[126:129], v80 offset:59936
	s_waitcnt lgkmcnt(2)
	v_mfma_f32_32x32x16_bf16 v[50:65], v[136:139], v[122:125], v[50:65]
	ds_read_b128 v[130:133], v66 offset:36928
	s_waitcnt lgkmcnt(2)
	v_mfma_f32_32x32x16_bf16 v[2:17], v[118:121], v[122:125], v[2:17]
	ds_read_b128 v[122:125], v80 offset:55360
	s_waitcnt lgkmcnt(2)
	v_mfma_f32_32x32x16_bf16 v[18:33], v[136:139], v[126:129], v[18:33]
	ds_read_b128 v[136:139], v66 offset:41536
	v_mfma_f32_32x32x16_bf16 v[34:49], v[118:121], v[126:129], v[34:49]
	ds_read_b128 v[126:129], v80 offset:59968
	s_waitcnt lgkmcnt(2)
	v_mfma_f32_32x32x16_bf16 v[50:65], v[130:133], v[122:125], v[50:65]
	ds_read_b128 v[118:121], v66 offset:36960
	s_waitcnt lgkmcnt(2)
	v_mfma_f32_32x32x16_bf16 v[2:17], v[136:139], v[122:125], v[2:17]
	ds_read_b128 v[122:125], v80 offset:55392
	s_waitcnt lgkmcnt(2)
	v_mfma_f32_32x32x16_bf16 v[18:33], v[130:133], v[126:129], v[18:33]
	ds_read_b128 v[130:133], v66 offset:41568
	v_mfma_f32_32x32x16_bf16 v[34:49], v[136:139], v[126:129], v[34:49]
	ds_read_b128 v[126:129], v80 offset:60000
	s_waitcnt lgkmcnt(2)
	v_mfma_f32_32x32x16_bf16 v[50:65], v[118:121], v[122:125], v[50:65]
	s_waitcnt lgkmcnt(1)
	v_mfma_f32_32x32x16_bf16 v[2:17], v[130:133], v[122:125], v[2:17]
	s_waitcnt lgkmcnt(0)
	v_mfma_f32_32x32x16_bf16 v[18:33], v[118:121], v[126:129], v[18:33]
	v_mfma_f32_32x32x16_bf16 v[34:49], v[130:133], v[126:129], v[34:49]
	s_waitcnt lgkmcnt(0)
	s_barrier
; __device__ __forceinline__ void acc_to_lds(const f32x16 (&acc)[2][2], float* cs) {
;   const int tid = threadIdx.x, lane = tid & 63, wave = tid >> 6;
;   const int wm = wave >> 1, wn = wave & 1;
; #pragma unroll
;   for (int i = 0; i < 2; ++i)
; #pragma unroll
;     for (int j = 0; j < 2; ++j)
; #pragma unroll
;       for (int r = 0; r < 16; ++r) {
;         int row = wm * 64 + i * 32 + (r & 3) + 8 * (r >> 2) + 4 * (lane >> 5);
;         int col = wn * 64 + j * 32 + (lane & 31);
;         cs[row * CSTR + col] = acc[i][j][r];
;       }
;   __syncthreads();
; __device__ __forceinline__ void epi_plain(const float* cs, u16* out, size_t ld, size_t row0, int col0) {
;   int tid_ = threadIdx.x;
;   asm volatile("" : "+v"(tid_));
;   const int lane = tid_ & 63, wave = tid_ >> 6;
;   const int r = 32 * wave + (lane & 31), half = lane >> 5;
;   const float* src = cs + r * CSTR + half * 64;
;   u16* dst = out + (row0 + r) * ld + col0 + half * 64;
; #pragma unroll
;   for (int q = 0; q < 8; ++q) {
;     float4 a = *(const float4*)(src + q * 8);
;     float4 b = *(const float4*)(src + q * 8 + 4);
;     uint4 o;
;     o.x = pack2(a.x, a.y); o.y = pack2(a.z, a.w); o.z = pack2(b.x, b.y); o.w = pack2(b.z, b.w);
;     *(uint4*)(dst + q * 8) = o;
;   }
; }
	ds_write2_b32 v97, v50, v18 offset1:32
	ds_write2_b32 v97, v51, v19 offset0:132 offset1:164
	v_add_u32_e32 v18, 0x400, v97
	ds_write2_b32 v18, v52, v20 offset0:8 offset1:40
	ds_write2_b32 v18, v53, v21 offset0:140 offset1:172
	v_add_u32_e32 v18, 0x1000, v97
	ds_write2_b32 v18, v54, v22 offset0:32 offset1:64
	ds_write2_b32 v18, v55, v23 offset0:164 offset1:196
	v_add_u32_e32 v18, 0x1400, v97
	ds_write2_b32 v18, v56, v24 offset0:40 offset1:72
	ds_write2_b32 v18, v57, v25 offset0:172 offset1:204
	v_add_u32_e32 v18, 0x2000, v97
	ds_write2_b32 v18, v58, v26 offset0:64 offset1:96
	ds_write2_b32 v18, v59, v27 offset0:196 offset1:228
	v_add_u32_e32 v18, 0x2400, v97
	ds_write2_b32 v18, v60, v28 offset0:72 offset1:104
	ds_write2_b32 v18, v61, v29 offset0:204 offset1:236
	v_add_u32_e32 v18, 0x3000, v97
	ds_write2_b32 v18, v62, v30 offset0:96 offset1:128
	v_add_u32_e32 v18, 0x3200, v97
	ds_write2_b32 v18, v63, v31 offset0:100 offset1:132
	v_add_u32_e32 v18, 0x3400, v97
	ds_write2_b32 v18, v64, v32 offset0:104 offset1:136
	v_add_u32_e32 v18, 0x3600, v97
	ds_write2_b32 v18, v65, v33 offset0:108 offset1:140
	v_add_u32_e32 v18, 0x4000, v97
	ds_write2_b32 v18, v2, v34 offset0:128 offset1:160
	v_add_u32_e32 v2, 0x4400, v97
	ds_write2_b32 v2, v3, v35 offset0:4 offset1:36
	ds_write2_b32 v2, v4, v36 offset0:136 offset1:168
	v_add_u32_e32 v2, 0x4800, v97
	ds_write2_b32 v2, v5, v37 offset0:12 offset1:44
	v_add_u32_e32 v2, 0x5000, v97
	ds_write2_b32 v2, v6, v38 offset0:160 offset1:192
	v_add_u32_e32 v2, 0x5400, v97
	ds_write2_b32 v2, v7, v39 offset0:36 offset1:68
	ds_write2_b32 v2, v8, v40 offset0:168 offset1:200
	v_add_u32_e32 v2, 0x5800, v97
	ds_write2_b32 v2, v9, v41 offset0:44 offset1:76
	v_add_u32_e32 v2, 0x6000, v97
	ds_write2_b32 v2, v10, v42 offset0:192 offset1:224
	v_add_u32_e32 v2, 0x6400, v97
	ds_write2_b32 v2, v11, v43 offset0:68 offset1:100
	ds_write2_b32 v2, v12, v44 offset0:200 offset1:232
	v_add_u32_e32 v2, 0x6800, v97
	ds_write2_b32 v2, v13, v45 offset0:76 offset1:108
	v_add_u32_e32 v2, 0x7200, v97
	ds_write2_b32 v2, v14, v46 offset0:96 offset1:128
	v_add_u32_e32 v2, 0x7400, v97
	ds_write2_b32 v2, v15, v47 offset0:100 offset1:132
	v_add_u32_e32 v2, 0x7600, v97
	ds_write2_b32 v2, v16, v48 offset0:104 offset1:136
	v_add_u32_e32 v2, 0x7800, v97
	v_mov_b32_e32 v3, v134
	ds_write2_b32 v2, v17, v49 offset0:108 offset1:140
	s_waitcnt lgkmcnt(0)
	s_barrier
	s_lshl_b32 s2, s2, 8
	v_ashrrev_i32_e32 v2, 1, v3
	v_bfi_b32 v2, s33, v2, v3
	v_lshlrev_b32_e32 v3, 1, v3
	v_and_b32_e32 v5, 64, v3
	v_ashrrev_i32_e32 v3, 31, v2
	v_mul_lo_u32 v4, v2, s16
	v_lshl_add_u64 v[2:3], s[12:13], 0, v[2:3]
	v_lshlrev_b64 v[2:3], 11, v[2:3]
	v_lshl_add_u64 v[2:3], s[0:1], 0, v[2:3]
	v_lshl_add_u32 v20, v5, 2, v4
	v_lshl_add_u64 v[6:7], v[2:3], 0, s[2:3]
	v_lshlrev_b32_e32 v66, 1, v5
	ds_read_b128 v[2:5], v20
	v_lshl_add_u64 v[18:19], v[6:7], 0, v[66:67]
	ds_read_b128 v[6:9], v20 offset:16
	ds_read_b128 v[10:13], v20 offset:32
	ds_read_b128 v[14:17], v20 offset:48
	s_waitcnt lgkmcnt(3)
	v_cvt_pk_bf16_f32 v2, v2, v3
	v_cvt_pk_bf16_f32 v3, v4, v5
	s_waitcnt lgkmcnt(2)
	v_cvt_pk_bf16_f32 v4, v6, v7
	v_cvt_pk_bf16_f32 v5, v8, v9
	global_store_dwordx4 v[18:19], v[2:5], off
	ds_read_b128 v[6:9], v20 offset:64
	s_add_i32 s35, s35, s94
	s_waitcnt lgkmcnt(2)
	v_cvt_pk_bf16_f32 v2, v10, v11
	v_cvt_pk_bf16_f32 v3, v12, v13
	s_waitcnt lgkmcnt(1)
	v_cvt_pk_bf16_f32 v4, v14, v15
	v_cvt_pk_bf16_f32 v5, v16, v17
	ds_read_b128 v[10:13], v20 offset:80
	global_store_dwordx4 v[18:19], v[2:5], off offset:16
	s_add_i32 s34, s34, s94
	s_add_i32 s19, s19, s20
	s_waitcnt lgkmcnt(1)
	v_cvt_pk_bf16_f32 v2, v6, v7
	v_cvt_pk_bf16_f32 v3, v8, v9
	s_waitcnt lgkmcnt(0)
	v_cvt_pk_bf16_f32 v4, v10, v11
	v_cvt_pk_bf16_f32 v5, v12, v13
	ds_read_b128 v[6:9], v20 offset:96
	ds_read_b128 v[10:13], v20 offset:112
	global_store_dwordx4 v[18:19], v[2:5], off offset:32
	s_cmpk_lt_i32 s35, 0x100
	ds_read_b128 v[14:17], v20 offset:240
	s_waitcnt lgkmcnt(2)
	v_cvt_pk_bf16_f32 v2, v6, v7
	v_cvt_pk_bf16_f32 v3, v8, v9
	s_waitcnt lgkmcnt(1)
	v_cvt_pk_bf16_f32 v4, v10, v11
	v_cvt_pk_bf16_f32 v5, v12, v13
	ds_read_b128 v[6:9], v20 offset:128
	ds_read_b128 v[10:13], v20 offset:144
	global_store_dwordx4 v[18:19], v[2:5], off offset:48
	s_waitcnt lgkmcnt(1)
	s_nop 0
	v_cvt_pk_bf16_f32 v2, v6, v7
	v_cvt_pk_bf16_f32 v3, v8, v9
	s_waitcnt lgkmcnt(0)
	v_cvt_pk_bf16_f32 v4, v10, v11
	v_cvt_pk_bf16_f32 v5, v12, v13
	ds_read_b128 v[6:9], v20 offset:160
	ds_read_b128 v[10:13], v20 offset:176
	global_store_dwordx4 v[18:19], v[2:5], off offset:64
	s_waitcnt lgkmcnt(1)
	s_nop 0
	v_cvt_pk_bf16_f32 v2, v6, v7
	v_cvt_pk_bf16_f32 v3, v8, v9
	s_waitcnt lgkmcnt(0)
	v_cvt_pk_bf16_f32 v4, v10, v11
	v_cvt_pk_bf16_f32 v5, v12, v13
	ds_read_b128 v[6:9], v20 offset:192
	ds_read_b128 v[10:13], v20 offset:208
	global_store_dwordx4 v[18:19], v[2:5], off offset:80
	s_waitcnt lgkmcnt(1)
	s_nop 0
	v_cvt_pk_bf16_f32 v2, v6, v7
	v_cvt_pk_bf16_f32 v3, v8, v9
	s_waitcnt lgkmcnt(0)
	v_cvt_pk_bf16_f32 v4, v10, v11
	v_cvt_pk_bf16_f32 v5, v12, v13
	ds_read_b128 v[6:9], v20 offset:224
	global_store_dwordx4 v[18:19], v[2:5], off offset:96
	s_waitcnt lgkmcnt(0)
	s_nop 0
	v_cvt_pk_bf16_f32 v2, v6, v7
	v_cvt_pk_bf16_f32 v3, v8, v9
	v_cvt_pk_bf16_f32 v4, v14, v15
	v_cvt_pk_bf16_f32 v5, v16, v17
	global_store_dwordx4 v[18:19], v[2:5], off offset:112
	s_barrier
	s_cbranch_scc1 .LBB0_1120

; #define GM_LOAD(KOFF) GM_LOAD2(KOFF, 0)
;     ...
;   const u16* ap0 = arow(lr) + kc * 8;
;   const u16* ap1 = arow(lr + 32) + kc * 8;
;   const u16* ap2 = arow(lr + 64) + kc * 8;
;   const u16* ap3 = arow(lr + 96) + kc * 8;
;   const u16* bp0 = Bt + (size_t)lr * ldb + kc * 8;
;   const size_t bstep = 32 * ldb;
;   const int so = lr * LSTR + kc * 16;
;   uint4 ra0, ra1, ra2, ra3, rb0, rb1, rb2, rb3;
;     ...
;   GM_LOAD(0)
;   GM_STORE(smem)
;   __syncthreads();
; __device__ __forceinline__ void fourier_half_tile(const Params& P, bool isctx, int b, int mt, int nt, char* smem) {
;   const int lane = threadIdx.x & 63, wave = threadIdx.x >> 6;
;   const int r = 32 * wave + (lane & 31), half = lane >> 5;
;   float* cs = (float*)smem;
;   const int N = isctx ? CTXL : SEQ;
;   const size_t ld = isctx ? 512 : 8192;
;   const u16* Abase = (isctx ? WSP(u16, OFF_DMATC) : WSP(u16, OFF_DMAT)) + (size_t)mt * 128 * ld;
;   const u16* Bbase = isctx ? (WSP(u16, OFF_FTTC) + ((size_t)b * 256 + nt * 128) * 512)
;                            : (WSP(u16, OFF_FTT) + ((size_t)b * 256 + nt * 128) * 8192);
;   const int k = mt * 128 + r;
;   const size_t rowbase = isctx ? (size_t)NLAT + b * CTXL : (size_t)b * SEQ;
;   float pacc[64];
; #pragma unroll 1
;   for (int br = 0; br < 2; ++br) {
;     f32x16 acc[2][2];
;     zero_acc(acc);
;     const u16* A = Abase + br * N;
;     const u16* Bt = Bbase + br * N;
;     gemm_main<false>([&](int rr) { return A + (size_t)rr * ld; }, Bt, ld, N, smem, acc);
.LBB0_1400:
	s_lshl_b64 s[26:27], s[10:11], 1
	v_lshl_add_u64 v[2:3], v[152:153], 0, s[26:27]
	v_lshl_add_u64 v[2:3], v[2:3], 0, v[142:143]
	v_add_co_u32_e32 v6, vcc, s15, v2
	v_lshl_add_u64 v[4:5], v[146:147], 0, s[26:27]
	s_nop 0
	v_addc_co_u32_e32 v7, vcc, 0, v3, vcc
	v_add_co_u32_e32 v8, vcc, s16, v2
	s_xor_b64 s[8:9], s[8:9], -1
	s_nop 0
	v_addc_co_u32_e32 v9, vcc, 0, v3, vcc
	global_load_dwordx4 v[34:37], v[6:7], off
	global_load_dwordx4 v[38:41], v[8:9], off
	v_add_co_u32_e32 v6, vcc, s17, v2
	global_load_dwordx4 v[42:45], v[2:3], off
	global_load_dwordx4 v[46:49], v[4:5], off
	v_addc_co_u32_e32 v7, vcc, 0, v3, vcc
	v_add_co_u32_e32 v2, vcc, s16, v4
	s_mov_b32 s6, 0
	s_nop 0
	v_addc_co_u32_e32 v3, vcc, 0, v5, vcc
	v_add_co_u32_e32 v8, vcc, s17, v4
	s_mov_b64 s[10:11], 0
	s_nop 0
	v_addc_co_u32_e32 v9, vcc, 0, v5, vcc
	global_load_dwordx4 v[52:55], v[2:3], off
	global_load_dwordx4 v[56:59], v[8:9], off
	v_add_co_u32_e32 v2, vcc, s15, v4
	v_lshl_add_u64 v[158:159], v[154:155], 0, s[26:27]
	s_nop 0
	v_addc_co_u32_e32 v3, vcc, 0, v5, vcc
	global_load_dwordx4 v[60:63], v[6:7], off
	global_load_dwordx4 v[170:173], v[2:3], off
	v_mov_b32_e32 v2, 0
	v_lshl_add_u64 v[160:161], v[156:157], 0, s[26:27]
	v_mov_b32_e32 v3, v2
	v_mov_b32_e32 v4, v2
	v_mov_b32_e32 v5, v2
	v_mov_b32_e32 v6, v2
	v_mov_b32_e32 v7, v2
	v_mov_b32_e32 v8, v2
	v_mov_b32_e32 v9, v2
	v_mov_b32_e32 v10, v2
	v_mov_b32_e32 v11, v2
	v_mov_b32_e32 v12, v2
	v_mov_b32_e32 v13, v2
	v_mov_b32_e32 v14, v2
	v_mov_b32_e32 v15, v2
	v_mov_b32_e32 v16, v2
	v_mov_b32_e32 v17, v2
	v_mov_b32_e32 v18, v2
	v_mov_b32_e32 v19, v2
	v_mov_b32_e32 v20, v2
	v_mov_b32_e32 v21, v2
	v_mov_b32_e32 v22, v2
	v_mov_b32_e32 v23, v2
	v_mov_b32_e32 v24, v2
	v_mov_b32_e32 v25, v2
	v_mov_b32_e32 v26, v2
	v_mov_b32_e32 v27, v2
	v_mov_b32_e32 v28, v2
	v_mov_b32_e32 v29, v2
	v_mov_b32_e32 v30, v2
	v_mov_b32_e32 v31, v2
	v_mov_b32_e32 v32, v2
	v_mov_b32_e32 v33, v2
	v_mov_b32_e32 v50, v2
	v_mov_b32_e32 v51, v2
	v_mov_b32_e32 v64, v2
	v_mov_b32_e32 v65, v2
	s_waitcnt vmcnt(5)
	ds_write_b128 v137, v[42:45]
	s_waitcnt vmcnt(4)
	ds_write_b128 v137, v[46:49] offset:18432
	s_waitcnt vmcnt(3)
	ds_write_b128 v137, v[52:55] offset:27648
	s_waitcnt vmcnt(2)
	ds_write_b128 v137, v[56:59] offset:32256
	ds_write_b128 v137, v[34:37] offset:4608
	ds_write_b128 v137, v[38:41] offset:9216
	s_waitcnt vmcnt(1)
	ds_write_b128 v137, v[60:63] offset:13824
	s_waitcnt vmcnt(0)
	ds_write_b128 v137, v[170:173] offset:23040
	v_mov_b32_e32 v52, v2
	v_mov_b32_e32 v53, v2
	v_mov_b32_e32 v54, v2
	v_mov_b32_e32 v55, v2
	v_mov_b32_e32 v56, v2
	v_mov_b32_e32 v57, v2
	v_mov_b32_e32 v58, v2
	v_mov_b32_e32 v59, v2
	v_mov_b32_e32 v60, v2
	v_mov_b32_e32 v61, v2
	v_mov_b32_e32 v62, v2
	v_mov_b32_e32 v63, v2
	v_mov_b32_e32 v34, v2
	v_mov_b32_e32 v35, v2
	v_mov_b32_e32 v36, v2
	v_mov_b32_e32 v37, v2
	v_mov_b32_e32 v38, v2
	v_mov_b32_e32 v39, v2
	v_mov_b32_e32 v40, v2
	v_mov_b32_e32 v41, v2
	v_mov_b32_e32 v42, v2
	v_mov_b32_e32 v43, v2
	v_mov_b32_e32 v44, v2
	v_mov_b32_e32 v45, v2
	v_mov_b32_e32 v46, v2
	v_mov_b32_e32 v47, v2
	v_mov_b32_e32 v48, v2
	v_mov_b32_e32 v49, v2
	s_waitcnt lgkmcnt(0)
	s_barrier
	v_lshl_add_u64 v[178:179], v[158:159], 0, s[10:11]
	v_add_co_u32_e32 v170, vcc, s18, v178
	v_lshl_add_u64 v[194:195], v[160:161], 0, s[10:11]
	s_nop 0
	v_addc_co_u32_e32 v171, vcc, 0, v179, vcc
	v_add_co_u32_e32 v174, vcc, s19, v178
	s_nop 1
	v_addc_co_u32_e32 v175, vcc, 0, v179, vcc
	v_add_co_u32_e32 v180, vcc, s20, v178
	global_load_dwordx4 v[170:173], v[170:171], off offset:128
	s_nop 0
	global_load_dwordx4 v[174:177], v[174:175], off offset:128
	v_addc_co_u32_e32 v181, vcc, 0, v179, vcc
	v_add_co_u32_e32 v182, vcc, s21, v178
	s_nop 1
	v_addc_co_u32_e32 v183, vcc, 0, v179, vcc
	v_add_co_u32_e32 v186, vcc, s22, v194
	global_load_dwordx4 v[178:181], v[180:181], off offset:128
	s_nop 0
	global_load_dwordx4 v[182:185], v[182:183], off offset:128
	v_addc_co_u32_e32 v187, vcc, 0, v195, vcc
	v_add_co_u32_e32 v190, vcc, s23, v194
	s_nop 1
	v_addc_co_u32_e32 v191, vcc, 0, v195, vcc
	v_add_co_u32_e32 v196, vcc, s24, v194
	global_load_dwordx4 v[186:189], v[186:187], off offset:384
	s_nop 0
	global_load_dwordx4 v[190:193], v[190:191], off offset:384
	v_addc_co_u32_e32 v197, vcc, 0, v195, vcc
	v_add_co_u32_e32 v198, vcc, s25, v194
	s_nop 1
	v_addc_co_u32_e32 v199, vcc, 0, v195, vcc
	global_load_dwordx4 v[194:197], v[196:197], off offset:384
	s_nop 0
	global_load_dwordx4 v[198:201], v[198:199], off offset:384
;     ...
;   for (int kt = 0; kt < nk; ++kt) {
;     const int kn = (kt + 1 < nk) ? kt + 1 : kt;
;     GM_LOAD2(kn * 64, kn * bkstep)
;     __builtin_amdgcn_sched_barrier(0);
;     const char* As = smem + (kt & 1) * 2 * TILE_B;
;     const char* Bs = As + TILE_B;
;     if constexpr (HOIST) {
;       bf16x8 fa0[4], fa1[4], fb0[4], fb1[4];
; #pragma unroll
;       for (int st = 0; st < 4; ++st) {
;         fa0[st] = *(const bf16x8*)(As + aoff + st * 32);
;         fb0[st] = *(const bf16x8*)(Bs + boff + st * 32);
;         fa1[st] = *(const bf16x8*)(As + aoff + 32 * LSTR + st * 32);
;         fb1[st] = *(const bf16x8*)(Bs + boff + 32 * LSTR + st * 32);
;       }
;       __builtin_amdgcn_sched_barrier(0);
; #pragma unroll
;       for (int st = 0; st < 4; ++st) {
;         acc[0][0] = mfma32(fa0[st], fb0[st], acc[0][0]);
;         acc[0][1] = mfma32(fa0[st], fb1[st], acc[0][1]);
;         acc[1][0] = mfma32(fa1[st], fb0[st], acc[1][0]);
;         acc[1][1] = mfma32(fa1[st], fb1[st], acc[1][1]);
;       }
;     } else {
; #pragma unroll
;       for (int st = 0; st < 4; ++st) {
;         bf16x8 a0 = *(const bf16x8*)(As + aoff + st * 32);
;         bf16x8 a1 = *(const bf16x8*)(As + aoff + 32 * LSTR + st * 32);
;         bf16x8 b0 = *(const bf16x8*)(Bs + boff + st * 32);
;         bf16x8 b1 = *(const bf16x8*)(Bs + boff + 32 * LSTR + st * 32);
;         acc[0][0] = mfma32(a0, b0, acc[0][0]);
;         acc[0][1] = mfma32(a0, b1, acc[0][1]);
;         acc[1][0] = mfma32(a1, b0, acc[1][0]);
;         acc[1][1] = mfma32(a1, b1, acc[1][1]);
;       }
;     }
;     __builtin_amdgcn_sched_barrier(0);
;     {
;       char* Ad = smem + ((kt + 1) & 1) * 2 * TILE_B;
;       GM_STORE(Ad)
;     }
;     __syncthreads();
.LBB0_1401:
	s_and_b32 s26, s6, 2
	s_mulk_i32 s26, 0x4800
	v_add3_u32 v130, s26, v163, v164
	v_add3_u32 v169, s26, v165, v164
	ds_read_b128 v[202:205], v130 offset:0
	ds_read_b128 v[206:209], v169 offset:18432
	ds_read_b128 v[214:217], v130 offset:4608
	ds_read_b128 v[210:213], v169 offset:23040
	s_waitcnt lgkmcnt(2)
	v_mfma_f32_32x32x16_bf16 v[50:65], v[202:205], v[206:209], v[50:65]
	ds_read_b128 v[218:221], v130 offset:32
	s_waitcnt lgkmcnt(2)
	v_mfma_f32_32x32x16_bf16 v[2:17], v[214:217], v[206:209], v[2:17]
	ds_read_b128 v[206:209], v169 offset:18464
	s_waitcnt lgkmcnt(2)
	v_mfma_f32_32x32x16_bf16 v[18:33], v[202:205], v[210:213], v[18:33]
	ds_read_b128 v[202:205], v130 offset:4640
	v_mfma_f32_32x32x16_bf16 v[34:49], v[214:217], v[210:213], v[34:49]
	ds_read_b128 v[210:213], v169 offset:23072
	s_waitcnt lgkmcnt(2)
	v_mfma_f32_32x32x16_bf16 v[50:65], v[218:221], v[206:209], v[50:65]
	ds_read_b128 v[214:217], v130 offset:64
	s_waitcnt lgkmcnt(2)
	v_mfma_f32_32x32x16_bf16 v[2:17], v[202:205], v[206:209], v[2:17]
	ds_read_b128 v[206:209], v169 offset:18496
	s_waitcnt lgkmcnt(2)
	v_mfma_f32_32x32x16_bf16 v[18:33], v[218:221], v[210:213], v[18:33]
	ds_read_b128 v[218:221], v130 offset:4672
	v_mfma_f32_32x32x16_bf16 v[34:49], v[202:205], v[210:213], v[34:49]
	ds_read_b128 v[210:213], v169 offset:23104
	s_waitcnt lgkmcnt(2)
	v_mfma_f32_32x32x16_bf16 v[50:65], v[214:217], v[206:209], v[50:65]
	ds_read_b128 v[202:205], v130 offset:96
	s_waitcnt lgkmcnt(2)
	v_mfma_f32_32x32x16_bf16 v[2:17], v[218:221], v[206:209], v[2:17]
	ds_read_b128 v[206:209], v169 offset:18528
	s_waitcnt lgkmcnt(2)
	v_mfma_f32_32x32x16_bf16 v[18:33], v[214:217], v[210:213], v[18:33]
	ds_read_b128 v[214:217], v130 offset:4704
	v_mfma_f32_32x32x16_bf16 v[34:49], v[218:221], v[210:213], v[34:49]
	ds_read_b128 v[210:213], v169 offset:23136
	s_waitcnt lgkmcnt(2)
	v_mfma_f32_32x32x16_bf16 v[50:65], v[202:205], v[206:209], v[50:65]
	s_waitcnt lgkmcnt(1)
	v_mfma_f32_32x32x16_bf16 v[2:17], v[214:217], v[206:209], v[2:17]
	s_waitcnt lgkmcnt(0)
	v_mfma_f32_32x32x16_bf16 v[18:33], v[202:205], v[210:213], v[18:33]
	v_mfma_f32_32x32x16_bf16 v[34:49], v[214:217], v[210:213], v[34:49]
	s_add_i32 s6, s6, 2
	s_and_b32 s26, s6, 2
	s_add_u32 s10, s10, 0x80
	s_mulk_i32 s26, 0x4800
	s_addc_u32 s11, s11, 0
	v_add_u32_e32 v130, s26, v137
	s_cmpk_lg_i32 s10, 0x1f00
	s_waitcnt vmcnt(7)
	ds_write_b128 v130, v[170:173]
	v_lshl_add_u64 v[170:171], v[158:159], 0, s[10:11]
	v_add_co_u32_e32 v170, vcc, s18, v170
	s_nop 1
	v_addc_co_u32_e32 v171, vcc, 0, v171, vcc
	global_load_dwordx4 v[170:173], v[170:171], off offset:128
	s_waitcnt vmcnt(7)
	ds_write_b128 v130, v[174:177] offset:4608
	v_lshl_add_u64 v[174:175], v[158:159], 0, s[10:11]
	v_add_co_u32_e32 v174, vcc, s19, v174
	s_nop 1
	v_addc_co_u32_e32 v175, vcc, 0, v175, vcc
	global_load_dwordx4 v[174:177], v[174:175], off offset:128
	s_waitcnt vmcnt(7)
	ds_write_b128 v130, v[178:181] offset:9216
	v_lshl_add_u64 v[178:179], v[158:159], 0, s[10:11]
	v_add_co_u32_e32 v178, vcc, s20, v178
	s_nop 1
	v_addc_co_u32_e32 v179, vcc, 0, v179, vcc
	global_load_dwordx4 v[178:181], v[178:179], off offset:128
	s_waitcnt vmcnt(7)
	ds_write_b128 v130, v[182:185] offset:13824
	v_lshl_add_u64 v[182:183], v[158:159], 0, s[10:11]
	v_add_co_u32_e32 v182, vcc, s21, v182
	s_nop 1
	v_addc_co_u32_e32 v183, vcc, 0, v183, vcc
	global_load_dwordx4 v[182:185], v[182:183], off offset:128
	s_waitcnt vmcnt(7)
	ds_write_b128 v130, v[186:189] offset:18432
	v_lshl_add_u64 v[186:187], v[160:161], 0, s[10:11]
	v_add_co_u32_e32 v186, vcc, s22, v186
	s_nop 1
	v_addc_co_u32_e32 v187, vcc, 0, v187, vcc
	global_load_dwordx4 v[186:189], v[186:187], off offset:384
	s_waitcnt vmcnt(7)
	ds_write_b128 v130, v[190:193] offset:23040
	v_lshl_add_u64 v[190:191], v[160:161], 0, s[10:11]
	v_add_co_u32_e32 v190, vcc, s23, v190
	s_nop 1
	v_addc_co_u32_e32 v191, vcc, 0, v191, vcc
	global_load_dwordx4 v[190:193], v[190:191], off offset:384
	s_waitcnt vmcnt(7)
	ds_write_b128 v130, v[194:197] offset:27648
	v_lshl_add_u64 v[194:195], v[160:161], 0, s[10:11]
	v_add_co_u32_e32 v194, vcc, s24, v194
	s_nop 1
	v_addc_co_u32_e32 v195, vcc, 0, v195, vcc
	global_load_dwordx4 v[194:197], v[194:195], off offset:384
	s_waitcnt vmcnt(7)
	ds_write_b128 v130, v[198:201] offset:32256
	v_lshl_add_u64 v[198:199], v[160:161], 0, s[10:11]
	v_add_co_u32_e32 v198, vcc, s25, v198
	s_nop 1
	v_addc_co_u32_e32 v199, vcc, 0, v199, vcc
	global_load_dwordx4 v[198:201], v[198:199], off offset:384
	s_waitcnt lgkmcnt(0)
	s_barrier
	s_cbranch_scc1 .LBB0_1401
;     ...
;   for (int kt = 0; kt < nk; ++kt) {
;     const int kn = (kt + 1 < nk) ? kt + 1 : kt;
;     GM_LOAD2(kn * 64, kn * bkstep)
;     __builtin_amdgcn_sched_barrier(0);
;     const char* As = smem + (kt & 1) * 2 * TILE_B;
;     const char* Bs = As + TILE_B;
;     if constexpr (HOIST) {
;       bf16x8 fa0[4], fa1[4], fb0[4], fb1[4];
; #pragma unroll
;       for (int st = 0; st < 4; ++st) {
;         fa0[st] = *(const bf16x8*)(As + aoff + st * 32);
;         fb0[st] = *(const bf16x8*)(Bs + boff + st * 32);
;         fa1[st] = *(const bf16x8*)(As + aoff + 32 * LSTR + st * 32);
;         fb1[st] = *(const bf16x8*)(Bs + boff + 32 * LSTR + st * 32);
;       }
;       __builtin_amdgcn_sched_barrier(0);
; #pragma unroll
;       for (int st = 0; st < 4; ++st) {
;         acc[0][0] = mfma32(fa0[st], fb0[st], acc[0][0]);
;         acc[0][1] = mfma32(fa0[st], fb1[st], acc[0][1]);
;         acc[1][0] = mfma32(fa1[st], fb0[st], acc[1][0]);
;         acc[1][1] = mfma32(fa1[st], fb1[st], acc[1][1]);
;       }
;     } else {
; #pragma unroll
;       for (int st = 0; st < 4; ++st) {
;         bf16x8 a0 = *(const bf16x8*)(As + aoff + st * 32);
;         bf16x8 a1 = *(const bf16x8*)(As + aoff + 32 * LSTR + st * 32);
;         bf16x8 b0 = *(const bf16x8*)(Bs + boff + st * 32);
;         bf16x8 b1 = *(const bf16x8*)(Bs + boff + 32 * LSTR + st * 32);
;         acc[0][0] = mfma32(a0, b0, acc[0][0]);
;         acc[0][1] = mfma32(a0, b1, acc[0][1]);
;         acc[1][0] = mfma32(a1, b0, acc[1][0]);
;         acc[1][1] = mfma32(a1, b1, acc[1][1]);
;       }
;     }
;     __builtin_amdgcn_sched_barrier(0);
;     {
;       char* Ad = smem + ((kt + 1) & 1) * 2 * TILE_B;
;       GM_STORE(Ad)
;     }
;     __syncthreads();
	s_and_b32 s26, s6, 2
	s_mulk_i32 s26, 0x4800
	v_add3_u32 v130, s26, v163, v164
	v_add3_u32 v169, s26, v165, v164
	ds_read_b128 v[202:205], v130 offset:0
	ds_read_b128 v[206:209], v169 offset:18432
	ds_read_b128 v[214:217], v130 offset:4608
	ds_read_b128 v[210:213], v169 offset:23040
	s_waitcnt lgkmcnt(2)
	v_mfma_f32_32x32x16_bf16 v[50:65], v[202:205], v[206:209], v[50:65]
	ds_read_b128 v[218:221], v130 offset:32
	s_waitcnt lgkmcnt(2)
	v_mfma_f32_32x32x16_bf16 v[2:17], v[214:217], v[206:209], v[2:17]
	ds_read_b128 v[206:209], v169 offset:18464
	s_waitcnt lgkmcnt(2)
	v_mfma_f32_32x32x16_bf16 v[18:33], v[202:205], v[210:213], v[18:33]
	ds_read_b128 v[202:205], v130 offset:4640
	v_mfma_f32_32x32x16_bf16 v[34:49], v[214:217], v[210:213], v[34:49]
	ds_read_b128 v[210:213], v169 offset:23072
	s_waitcnt lgkmcnt(2)
	v_mfma_f32_32x32x16_bf16 v[50:65], v[218:221], v[206:209], v[50:65]
	ds_read_b128 v[214:217], v130 offset:64
	s_waitcnt lgkmcnt(2)
	v_mfma_f32_32x32x16_bf16 v[2:17], v[202:205], v[206:209], v[2:17]
	ds_read_b128 v[206:209], v169 offset:18496
	s_waitcnt lgkmcnt(2)
	v_mfma_f32_32x32x16_bf16 v[18:33], v[218:221], v[210:213], v[18:33]
	ds_read_b128 v[218:221], v130 offset:4672
	v_mfma_f32_32x32x16_bf16 v[34:49], v[202:205], v[210:213], v[34:49]
	ds_read_b128 v[210:213], v169 offset:23104
	s_waitcnt lgkmcnt(2)
	v_mfma_f32_32x32x16_bf16 v[50:65], v[214:217], v[206:209], v[50:65]
	ds_read_b128 v[202:205], v130 offset:96
	s_waitcnt lgkmcnt(2)
	v_mfma_f32_32x32x16_bf16 v[2:17], v[218:221], v[206:209], v[2:17]
	ds_read_b128 v[206:209], v169 offset:18528
	s_waitcnt lgkmcnt(2)
	v_mfma_f32_32x32x16_bf16 v[18:33], v[214:217], v[210:213], v[18:33]
	ds_read_b128 v[214:217], v130 offset:4704
	v_mfma_f32_32x32x16_bf16 v[34:49], v[218:221], v[210:213], v[34:49]
	ds_read_b128 v[210:213], v169 offset:23136
	s_waitcnt lgkmcnt(2)
	v_mfma_f32_32x32x16_bf16 v[50:65], v[202:205], v[206:209], v[50:65]
	s_waitcnt lgkmcnt(1)
	v_mfma_f32_32x32x16_bf16 v[2:17], v[214:217], v[206:209], v[2:17]
	s_waitcnt lgkmcnt(0)
	v_mfma_f32_32x32x16_bf16 v[18:33], v[202:205], v[210:213], v[18:33]
	v_mfma_f32_32x32x16_bf16 v[34:49], v[214:217], v[210:213], v[34:49]
	s_add_i32 s6, s6, 2
	s_and_b32 s26, s6, 2
	s_add_u32 s10, s10, 0x80
	s_mulk_i32 s26, 0x4800
	s_addc_u32 s11, s11, 0
	v_add_u32_e32 v130, s26, v137
	s_waitcnt vmcnt(7)
	ds_write_b128 v130, v[170:173]
	s_waitcnt vmcnt(6)
	ds_write_b128 v130, v[174:177] offset:4608
	s_waitcnt vmcnt(5)
	ds_write_b128 v130, v[178:181] offset:9216
	s_waitcnt vmcnt(4)
	ds_write_b128 v130, v[182:185] offset:13824
	s_waitcnt vmcnt(3)
	ds_write_b128 v130, v[186:189] offset:18432
	s_waitcnt vmcnt(2)
	ds_write_b128 v130, v[190:193] offset:23040
	s_waitcnt vmcnt(1)
	ds_write_b128 v130, v[194:197] offset:27648
	s_waitcnt vmcnt(0)
	ds_write_b128 v130, v[198:201] offset:32256
	s_waitcnt lgkmcnt(0)
	s_barrier
	v_lshl_add_u64 v[174:175], v[158:159], 0, s[10:11]
	v_add_co_u32_e32 v158, vcc, 0xdf00000, v174
	v_lshl_add_u64 v[190:191], v[160:161], 0, s[10:11]
	s_nop 0
	v_addc_co_u32_e32 v159, vcc, 0, v175, vcc
	v_add_co_u32_e32 v170, vcc, 0xdf80000, v174
	s_nop 1
	v_addc_co_u32_e32 v171, vcc, 0, v175, vcc
	v_add_co_u32_e32 v176, vcc, 0xe000000, v174
	s_nop 0
	v_addc_co_u32_e32 v177, vcc, 0, v175, vcc
	v_add_co_u32_e32 v178, vcc, 0xe080000, v174
	s_nop 1
	v_addc_co_u32_e32 v179, vcc, 0, v175, vcc
	v_add_co_u32_e32 v182, vcc, 0x35d31000, v190
	s_nop 0
	v_addc_co_u32_e32 v183, vcc, 0, v191, vcc
	v_add_co_u32_e32 v186, vcc, 0x35db1000, v190
	s_nop 1
	v_addc_co_u32_e32 v187, vcc, 0, v191, vcc
	v_add_co_u32_e32 v192, vcc, 0x35e31000, v190
	s_nop 0
	v_addc_co_u32_e32 v193, vcc, 0, v191, vcc
	v_add_co_u32_e32 v194, vcc, 0x35eb1000, v190
	s_nop 1
	v_addc_co_u32_e32 v195, vcc, 0, v191, vcc
	s_nop 0
	v_add3_u32 v130, s26, v163, v164
	v_add3_u32 v169, s26, v165, v164
	ds_read_b128 v[198:201], v130 offset:0
	ds_read_b128 v[202:205], v169 offset:18432
	ds_read_b128 v[210:213], v130 offset:4608
	ds_read_b128 v[206:209], v169 offset:23040
	s_waitcnt lgkmcnt(2)
	v_mfma_f32_32x32x16_bf16 v[50:65], v[198:201], v[202:205], v[50:65]
	ds_read_b128 v[214:217], v130 offset:32
	s_waitcnt lgkmcnt(2)
	v_mfma_f32_32x32x16_bf16 v[2:17], v[210:213], v[202:205], v[2:17]
	ds_read_b128 v[202:205], v169 offset:18464
	s_waitcnt lgkmcnt(2)
	v_mfma_f32_32x32x16_bf16 v[18:33], v[198:201], v[206:209], v[18:33]
	ds_read_b128 v[198:201], v130 offset:4640
	v_mfma_f32_32x32x16_bf16 v[34:49], v[210:213], v[206:209], v[34:49]
	ds_read_b128 v[206:209], v169 offset:23072
	s_waitcnt lgkmcnt(2)
	v_mfma_f32_32x32x16_bf16 v[50:65], v[214:217], v[202:205], v[50:65]
	ds_read_b128 v[210:213], v130 offset:64
	s_waitcnt lgkmcnt(2)
	v_mfma_f32_32x32x16_bf16 v[2:17], v[198:201], v[202:205], v[2:17]
	ds_read_b128 v[202:205], v169 offset:18496
	s_waitcnt lgkmcnt(2)
	v_mfma_f32_32x32x16_bf16 v[18:33], v[214:217], v[206:209], v[18:33]
	ds_read_b128 v[214:217], v130 offset:4672
	v_mfma_f32_32x32x16_bf16 v[34:49], v[198:201], v[206:209], v[34:49]
	ds_read_b128 v[206:209], v169 offset:23104
	s_waitcnt lgkmcnt(2)
	v_mfma_f32_32x32x16_bf16 v[50:65], v[210:213], v[202:205], v[50:65]
	ds_read_b128 v[198:201], v130 offset:96
	s_waitcnt lgkmcnt(2)
	v_mfma_f32_32x32x16_bf16 v[2:17], v[214:217], v[202:205], v[2:17]
	ds_read_b128 v[202:205], v169 offset:18528
	s_waitcnt lgkmcnt(2)
	v_mfma_f32_32x32x16_bf16 v[18:33], v[210:213], v[206:209], v[18:33]
	ds_read_b128 v[210:213], v130 offset:4704
	v_mfma_f32_32x32x16_bf16 v[34:49], v[214:217], v[206:209], v[34:49]
	ds_read_b128 v[206:209], v169 offset:23136
	s_waitcnt lgkmcnt(2)
	v_mfma_f32_32x32x16_bf16 v[50:65], v[198:201], v[202:205], v[50:65]
	s_waitcnt lgkmcnt(1)
	v_mfma_f32_32x32x16_bf16 v[2:17], v[210:213], v[202:205], v[2:17]
	s_waitcnt lgkmcnt(0)
	v_mfma_f32_32x32x16_bf16 v[18:33], v[198:201], v[206:209], v[18:33]
	v_mfma_f32_32x32x16_bf16 v[34:49], v[210:213], v[206:209], v[34:49]
	s_waitcnt lgkmcnt(0)
	s_barrier
; __device__ __forceinline__ void fourier_half_tile(const Params& P, bool isctx, int b, int mt, int nt, char* smem) {
;     ...
;     acc_to_lds(acc, cs);
;     if (br == 0) {
; #pragma unroll
;       for (int q = 0; q < 16; ++q) {
;         float4 a = *(const float4*)(cs + r * CSTR + half * 64 + q * 4);
;         pacc[q * 4 + 0] = a.x; pacc[q * 4 + 1] = a.y; pacc[q * 4 + 2] = a.z; pacc[q * 4 + 3] = a.w;
;       }
;     } else {
;       u16* d1 = WSP(u16, OFF_FTO) + (rowbase + k) * 256 + nt * 128 + half * 64;
;       u16* d2 = WSP(u16, OFF_FTO) + (rowbase + (k > 0 ? N - k : 0)) * 256 + nt * 128 + half * 64;
; #pragma unroll
;       for (int q = 0; q < 8; ++q) {
;         float4 a = *(const float4*)(cs + r * CSTR + half * 64 + q * 8);
;         float4 c = *(const float4*)(cs + r * CSTR + half * 64 + q * 8 + 4);
;         uint4 o1, o2;
;         o1.x = pack2(pacc[q * 8 + 0] + a.x, pacc[q * 8 + 1] + a.y); o1.y = pack2(pacc[q * 8 + 2] + a.z, pacc[q * 8 + 3] + a.w);
;         o1.z = pack2(pacc[q * 8 + 4] + c.x, pacc[q * 8 + 5] + c.y); o1.w = pack2(pacc[q * 8 + 6] + c.z, pacc[q * 8 + 7] + c.w);
;         o2.x = pack2(pacc[q * 8 + 0] - a.x, pacc[q * 8 + 1] - a.y); o2.y = pack2(pacc[q * 8 + 2] - a.z, pacc[q * 8 + 3] - a.w);
;         o2.z = pack2(pacc[q * 8 + 4] - c.x, pacc[q * 8 + 5] - c.y); o2.w = pack2(pacc[q * 8 + 6] - c.z, pacc[q * 8 + 7] - c.w);
;         *(uint4*)(d1 + q * 8) = o1;
;         if (k > 0) *(uint4*)(d2 + q * 8) = o2;
;       }
;     }
	ds_write2_b32 v166, v50, v18 offset1:32
	ds_write2_b32 v166, v51, v19 offset0:132 offset1:164
	v_add_u32_e32 v18, 0x400, v166
	ds_write2_b32 v18, v52, v20 offset0:8 offset1:40
	ds_write2_b32 v18, v53, v21 offset0:140 offset1:172
	v_add_u32_e32 v18, 0x1000, v166
	ds_write2_b32 v18, v54, v22 offset0:32 offset1:64
	ds_write2_b32 v18, v55, v23 offset0:164 offset1:196
	v_add_u32_e32 v18, 0x1400, v166
	ds_write2_b32 v18, v56, v24 offset0:40 offset1:72
	ds_write2_b32 v18, v57, v25 offset0:172 offset1:204
	v_add_u32_e32 v18, 0x2000, v166
	ds_write2_b32 v18, v58, v26 offset0:64 offset1:96
	ds_write2_b32 v18, v59, v27 offset0:196 offset1:228
	v_add_u32_e32 v18, 0x2400, v166
	ds_write2_b32 v18, v60, v28 offset0:72 offset1:104
	ds_write2_b32 v18, v61, v29 offset0:204 offset1:236
	v_add_u32_e32 v18, 0x3000, v166
	ds_write2_b32 v18, v62, v30 offset0:96 offset1:128
	v_add_u32_e32 v18, 0x3200, v166
	ds_write2_b32 v18, v63, v31 offset0:100 offset1:132
	v_add_u32_e32 v18, 0x3400, v166
	ds_write2_b32 v18, v64, v32 offset0:104 offset1:136
	v_add_u32_e32 v18, 0x3600, v166
	ds_write2_b32 v18, v65, v33 offset0:108 offset1:140
	v_add_u32_e32 v18, 0x4000, v166
	ds_write2_b32 v18, v2, v34 offset0:128 offset1:160
	v_add_u32_e32 v2, 0x4400, v166
	ds_write2_b32 v2, v3, v35 offset0:4 offset1:36
	ds_write2_b32 v2, v4, v36 offset0:136 offset1:168
	v_add_u32_e32 v2, 0x4800, v166
	ds_write2_b32 v2, v5, v37 offset0:12 offset1:44
	v_add_u32_e32 v2, 0x5000, v166
	ds_write2_b32 v2, v6, v38 offset0:160 offset1:192
	v_add_u32_e32 v2, 0x5400, v166
	ds_write2_b32 v2, v7, v39 offset0:36 offset1:68
	ds_write2_b32 v2, v8, v40 offset0:168 offset1:200
	v_add_u32_e32 v2, 0x5800, v166
	ds_write2_b32 v2, v9, v41 offset0:44 offset1:76
	v_add_u32_e32 v2, 0x6000, v166
	ds_write2_b32 v2, v10, v42 offset0:192 offset1:224
	v_add_u32_e32 v2, 0x6400, v166
	ds_write2_b32 v2, v11, v43 offset0:68 offset1:100
	ds_write2_b32 v2, v12, v44 offset0:200 offset1:232
	v_add_u32_e32 v2, 0x6800, v166
	ds_write2_b32 v2, v13, v45 offset0:76 offset1:108
	v_add_u32_e32 v2, 0x7200, v166
	ds_write2_b32 v2, v14, v46 offset0:96 offset1:128
	v_add_u32_e32 v2, 0x7400, v166
	ds_write2_b32 v2, v15, v47 offset0:100 offset1:132
	v_add_u32_e32 v2, 0x7600, v166
	ds_write2_b32 v2, v16, v48 offset0:104 offset1:136
	v_add_u32_e32 v2, 0x7800, v166
	s_mov_b64 s[10:11], -1
	s_and_b64 vcc, exec, s[8:9]
	ds_write2_b32 v2, v17, v49 offset0:108 offset1:140
	s_waitcnt lgkmcnt(0)
	s_barrier
	s_cbranch_vccz .LBB0_1420
	ds_read_b128 v[2:5], v167
	ds_read_b128 v[6:9], v167 offset:16
	s_waitcnt lgkmcnt(1)
	v_add_f32_e32 v10, v78, v2
	v_add_f32_e32 v11, v79, v3
	v_sub_f32_e32 v2, v78, v2
	v_sub_f32_e32 v3, v79, v3
	v_add_f32_e32 v12, v80, v4
	v_add_f32_e32 v13, v81, v5
	v_cvt_pk_bf16_f32 v2, v2, v3
	v_sub_f32_e32 v3, v80, v4
	v_sub_f32_e32 v4, v81, v5
	v_cvt_pk_bf16_f32 v10, v10, v11
	v_cvt_pk_bf16_f32 v11, v12, v13
	s_waitcnt lgkmcnt(0)
	v_add_f32_e32 v12, v74, v6
	v_add_f32_e32 v13, v75, v7
	v_cvt_pk_bf16_f32 v3, v3, v4
	v_sub_f32_e32 v4, v74, v6
	v_sub_f32_e32 v5, v75, v7
	v_cvt_pk_bf16_f32 v12, v12, v13
	v_add_f32_e32 v13, v76, v8
	v_cvt_pk_bf16_f32 v4, v4, v5
	v_sub_f32_e32 v5, v76, v8
	v_add_f32_e32 v14, v77, v9
	v_cvt_pk_bf16_f32 v13, v13, v14
	v_sub_f32_e32 v6, v77, v9
	v_cvt_pk_bf16_f32 v5, v5, v6
	global_store_dwordx4 v[148:149], v[10:13], off
	s_and_saveexec_b64 s[10:11], s[2:3]
	s_cbranch_execz .LBB0_1405
	global_store_dwordx4 v[150:151], v[2:5], off

; #define GM_LOAD(KOFF) GM_LOAD2(KOFF, 0)
;     ...
;   const u16* ap0 = arow(lr) + kc * 8;
;   const u16* ap1 = arow(lr + 32) + kc * 8;
;   const u16* ap2 = arow(lr + 64) + kc * 8;
;   const u16* ap3 = arow(lr + 96) + kc * 8;
;   const u16* bp0 = Bt + (size_t)lr * ldb + kc * 8;
;   const size_t bstep = 32 * ldb;
;   const int so = lr * LSTR + kc * 16;
;   uint4 ra0, ra1, ra2, ra3, rb0, rb1, rb2, rb3;
;     ...
;   GM_LOAD(0)
;   GM_STORE(smem)
;   __syncthreads();
; __device__ __forceinline__ void merge_tile(const Params& P, int l, int mt, int nt, char* smem) {
;     ...
;   for (int br = 0; br < 3; ++br) {
;     f32x16 acc[2][2];
;     zero_acc(acc);
;     const int K = (br == 0) ? 256 : 384;
;     const u16* A = WSP(u16, br == 0 ? OFF_FTO : (br == 1 ? OFF_ONA : OFF_ODF)) + (size_t)mt * 128 * K;
;     const u16* Bt = WSP(u16, br == 0 ? OFF_WFT : (br == 1 ? OFF_WNA : OFF_WDF)) + ((size_t)l * DM + nt * 128) * K;
;     gemm_main<false>([&](int rr) { return A + (size_t)rr * K; }, Bt, K, K, smem, acc);
.LBB0_1639:
	s_cmp_eq_u32 s38, 1
	s_cselect_b32 s6, s21, 0x1cdb1100
	s_cselect_b32 s39, s22, 0x1980000
	s_cmp_eq_u32 s38, 0
	s_cselect_b32 s44, s23, 0x180
	s_cselect_b32 s45, 0x1e731100, s6
	s_mul_hi_u32 s6, s10, s44
	s_mul_i32 s40, s11, s44
	s_cselect_b32 s39, 0x1700000, s39
	s_add_u32 s42, s90, s45
	s_addc_u32 s43, s91, 0
	s_add_i32 s41, s6, s40
	s_mul_i32 s40, s10, s44
	s_lshl_b64 s[40:41], s[40:41], 1
	s_add_u32 s40, s42, s40
	s_addc_u32 s41, s43, s41
	s_add_u32 s6, s90, s39
	s_mul_i32 s42, s15, s44
	s_mul_hi_u32 s43, s14, s44
	s_addc_u32 s46, s91, 0
	s_add_i32 s43, s43, s42
	s_mul_i32 s42, s14, s44
	s_lshl_b64 s[42:43], s[42:43], 1
	v_mul_u32_u24_e32 v2, s44, v1
	s_add_u32 s42, s6, s42
	v_lshlrev_b32_e32 v68, 1, v2
	s_addc_u32 s43, s46, s43
	v_lshl_add_u64 v[2:3], s[40:41], 0, v[68:69]
	s_lshl_b32 s6, s44, 6
	v_lshl_add_u64 v[4:5], v[2:3], 0, v[72:73]
	v_lshl_add_u64 v[2:3], v[2:3], 0, s[6:7]
	v_lshl_add_u64 v[6:7], v[2:3], 0, v[72:73]
	v_lshl_add_u64 v[2:3], v[2:3], 0, s[6:7]
	v_lshl_add_u64 v[10:11], v[2:3], 0, v[72:73]
	v_lshl_add_u64 v[2:3], v[2:3], 0, s[6:7]
	v_lshl_add_u64 v[14:15], v[2:3], 0, v[72:73]
	v_lshl_add_u64 v[2:3], s[42:43], 0, v[68:69]
	v_lshl_add_u64 v[18:19], v[2:3], 0, v[72:73]
	v_lshl_add_u64 v[26:27], v[18:19], 0, s[6:7]
	global_load_dwordx4 v[2:5], v[4:5], off
	s_nop 0
	global_load_dwordx4 v[6:9], v[6:7], off
	s_nop 0
	global_load_dwordx4 v[10:13], v[10:11], off
	s_nop 0
	global_load_dwordx4 v[14:17], v[14:15], off
	s_nop 0
	global_load_dwordx4 v[18:21], v[18:19], off
	s_nop 0
	global_load_dwordx4 v[22:25], v[26:27], off
	v_lshl_add_u64 v[26:27], v[26:27], 0, s[6:7]
	v_lshl_add_u64 v[30:31], v[26:27], 0, s[6:7]
	global_load_dwordx4 v[26:29], v[26:27], off
	s_nop 0
	global_load_dwordx4 v[30:33], v[30:31], off
	s_mul_i32 s6, s17, s44
	s_mul_hi_u32 s40, s16, s44
	s_lshr_b32 s58, s44, 6
	s_mul_i32 s41, s16, s44
	s_add_i32 s59, s40, s6
	s_add_i32 s6, s58, -2
	s_mul_i32 s42, s26, s44
	s_mul_hi_u32 s43, s25, s44
	s_add_u32 s40, s45, s41
	s_mul_i32 s46, s25, s44
	s_addc_u32 s41, 0, s59
	s_add_i32 s43, s43, s42
	s_mul_i32 s47, s28, s44
	s_mul_hi_u32 s48, s27, s44
	v_lshl_add_u64 v[148:149], v[70:71], 0, s[40:41]
	s_add_u32 s40, s45, s46
	s_mul_i32 s49, s27, s44
	s_addc_u32 s41, 0, s43
	s_add_i32 s48, s48, s47
	s_mul_i32 s50, s30, s44
	s_mul_hi_u32 s51, s29, s44
	v_lshl_add_u64 v[150:151], v[70:71], 0, s[40:41]
	s_add_u32 s40, s45, s49
	s_mul_i32 s52, s29, s44
	s_addc_u32 s41, 0, s48
	s_add_i32 s51, s51, s50
	s_mul_i32 s53, s19, s44
	s_mul_hi_u32 s54, s18, s44
	v_lshl_add_u64 v[152:153], v[70:71], 0, s[40:41]
	s_add_u32 s40, s45, s52
	s_mul_i32 s55, s18, s44
	s_addc_u32 s41, 0, s51
	s_add_i32 s54, s54, s53
	v_lshl_add_u64 v[154:155], v[70:71], 0, s[40:41]
	s_add_u32 s40, s39, s55
	s_mul_i32 s56, s33, s44
	s_mul_hi_u32 s57, s31, s44
	s_addc_u32 s41, 0, s54
	v_lshl_add_u64 v[156:157], v[70:71], 0, s[40:41]
	s_add_i32 s57, s57, s56
	s_mul_i32 s40, s31, s44
	s_add_u32 s40, s39, s40
	s_addc_u32 s41, 0, s57
	v_lshl_add_u64 v[158:159], v[70:71], 0, s[40:41]
	s_mul_i32 s40, s35, s44
	s_mul_hi_u32 s41, s34, s44
	s_add_i32 s41, s41, s40
	s_mul_i32 s40, s34, s44
	s_add_u32 s40, s39, s40
	s_addc_u32 s41, 0, s41
	v_lshl_add_u64 v[160:161], v[70:71], 0, s[40:41]
	s_mul_i32 s40, s37, s44
	s_mul_hi_u32 s41, s36, s44
	s_add_i32 s41, s41, s40
	s_mul_i32 s40, s36, s44
	s_add_u32 s40, s39, s40
	s_addc_u32 s41, 0, s41
	s_waitcnt vmcnt(7)
	ds_write_b128 v135, v[2:5]
	s_waitcnt vmcnt(6)
	ds_write_b128 v135, v[6:9] offset:4608
	s_waitcnt vmcnt(3)
	ds_write_b128 v135, v[18:21] offset:18432
	ds_write_b128 v135, v[10:13] offset:9216
	s_waitcnt vmcnt(2)
	ds_write_b128 v135, v[22:25] offset:23040
	ds_write_b128 v135, v[14:17] offset:13824
	s_waitcnt vmcnt(1)
	ds_write_b128 v135, v[26:29] offset:27648
	s_waitcnt vmcnt(0)
	ds_write_b128 v135, v[30:33] offset:32256
	v_lshl_add_u64 v[162:163], v[70:71], 0, s[40:41]
	s_mov_b32 s39, 0
	v_mov_b32_e32 v2, 0
	v_mov_b32_e32 v3, v75
	v_mov_b32_e32 v4, v75
	v_mov_b32_e32 v5, v75
	v_mov_b32_e32 v6, v75
	v_mov_b32_e32 v7, v75
	v_mov_b32_e32 v8, v75
	v_mov_b32_e32 v9, v75
	v_mov_b32_e32 v10, v75
	v_mov_b32_e32 v11, v75
	v_mov_b32_e32 v12, v75
	v_mov_b32_e32 v13, v75
	v_mov_b32_e32 v14, v75
	v_mov_b32_e32 v15, v75
	v_mov_b32_e32 v16, v75
	v_mov_b32_e32 v17, v75
	v_mov_b32_e32 v34, 0
	v_mov_b32_e32 v35, v75
	v_mov_b32_e32 v36, v75
	v_mov_b32_e32 v37, v75
	v_mov_b32_e32 v38, v75
	v_mov_b32_e32 v39, v75
	v_mov_b32_e32 v40, v75
	v_mov_b32_e32 v41, v75
	v_mov_b32_e32 v42, v75
	v_mov_b32_e32 v43, v75
	v_mov_b32_e32 v44, v75
	v_mov_b32_e32 v45, v75
	v_mov_b32_e32 v46, v75
	v_mov_b32_e32 v47, v75
	v_mov_b32_e32 v48, v75
	v_mov_b32_e32 v49, v75
	v_mov_b32_e32 v18, 0
	v_mov_b32_e32 v19, v75
	v_mov_b32_e32 v20, v75
	v_mov_b32_e32 v21, v75
	v_mov_b32_e32 v22, v75
	v_mov_b32_e32 v23, v75
	v_mov_b32_e32 v24, v75
	v_mov_b32_e32 v25, v75
	v_mov_b32_e32 v26, v75
	v_mov_b32_e32 v27, v75
	v_mov_b32_e32 v28, v75
	v_mov_b32_e32 v29, v75
	v_mov_b32_e32 v30, v75
	v_mov_b32_e32 v31, v75
	v_mov_b32_e32 v32, v75
	v_mov_b32_e32 v33, v75
	v_mov_b32_e32 v50, 0
	v_mov_b32_e32 v51, v75
	v_mov_b32_e32 v52, v75
	v_mov_b32_e32 v53, v75
	v_mov_b32_e32 v54, v75
	v_mov_b32_e32 v55, v75
	v_mov_b32_e32 v56, v75
	v_mov_b32_e32 v57, v75
	v_mov_b32_e32 v58, v75
	v_mov_b32_e32 v59, v75
	v_mov_b32_e32 v60, v75
	v_mov_b32_e32 v61, v75
	v_mov_b32_e32 v62, v75
	v_mov_b32_e32 v63, v75
	v_mov_b32_e32 v64, v75
	v_mov_b32_e32 v65, v75
	s_waitcnt lgkmcnt(0)
	s_barrier
	v_lshl_add_u64 v[168:169], v[148:149], 0, v[68:69]
	v_lshl_add_u64 v[172:173], v[150:151], 0, v[68:69]
	v_lshl_add_u64 v[176:177], v[152:153], 0, v[68:69]
	v_lshl_add_u64 v[180:181], v[154:155], 0, v[68:69]
	v_lshl_add_u64 v[184:185], v[156:157], 0, v[68:69]
	v_lshl_add_u64 v[188:189], v[158:159], 0, v[68:69]
	v_lshl_add_u64 v[192:193], v[160:161], 0, v[68:69]
	v_lshl_add_u64 v[196:197], v[162:163], 0, v[68:69]
	global_load_dwordx4 v[168:171], v[168:169], off offset:128
	s_nop 0
	global_load_dwordx4 v[172:175], v[172:173], off offset:128
	s_nop 0
	global_load_dwordx4 v[176:179], v[176:177], off offset:128
	s_nop 0
	global_load_dwordx4 v[180:183], v[180:181], off offset:128
	s_nop 0
	global_load_dwordx4 v[184:187], v[184:185], off offset:128
	s_nop 0
	global_load_dwordx4 v[188:191], v[188:189], off offset:128
	s_nop 0
	global_load_dwordx4 v[192:195], v[192:193], off offset:128
	s_nop 0
	global_load_dwordx4 v[196:199], v[196:197], off offset:128
;     ...
;   for (int kt = 0; kt < nk; ++kt) {
;     const int kn = (kt + 1 < nk) ? kt + 1 : kt;
;     GM_LOAD2(kn * 64, kn * bkstep)
;     __builtin_amdgcn_sched_barrier(0);
;     const char* As = smem + (kt & 1) * 2 * TILE_B;
;     const char* Bs = As + TILE_B;
;     if constexpr (HOIST) {
;       bf16x8 fa0[4], fa1[4], fb0[4], fb1[4];
; #pragma unroll
;       for (int st = 0; st < 4; ++st) {
;         fa0[st] = *(const bf16x8*)(As + aoff + st * 32);
;         fb0[st] = *(const bf16x8*)(Bs + boff + st * 32);
;         fa1[st] = *(const bf16x8*)(As + aoff + 32 * LSTR + st * 32);
;         fb1[st] = *(const bf16x8*)(Bs + boff + 32 * LSTR + st * 32);
;       }
;       __builtin_amdgcn_sched_barrier(0);
; #pragma unroll
;       for (int st = 0; st < 4; ++st) {
;         acc[0][0] = mfma32(fa0[st], fb0[st], acc[0][0]);
;         acc[0][1] = mfma32(fa0[st], fb1[st], acc[0][1]);
;         acc[1][0] = mfma32(fa1[st], fb0[st], acc[1][0]);
;         acc[1][1] = mfma32(fa1[st], fb1[st], acc[1][1]);
;       }
;     } else {
; #pragma unroll
;       for (int st = 0; st < 4; ++st) {
;         bf16x8 a0 = *(const bf16x8*)(As + aoff + st * 32);
;         bf16x8 a1 = *(const bf16x8*)(As + aoff + 32 * LSTR + st * 32);
;         bf16x8 b0 = *(const bf16x8*)(Bs + boff + st * 32);
;         bf16x8 b1 = *(const bf16x8*)(Bs + boff + 32 * LSTR + st * 32);
;         acc[0][0] = mfma32(a0, b0, acc[0][0]);
;         acc[0][1] = mfma32(a0, b1, acc[0][1]);
;         acc[1][0] = mfma32(a1, b0, acc[1][0]);
;         acc[1][1] = mfma32(a1, b1, acc[1][1]);
;       }
;     }
;     __builtin_amdgcn_sched_barrier(0);
;     {
;       char* Ad = smem + ((kt + 1) & 1) * 2 * TILE_B;
;       GM_STORE(Ad)
;     }
;     __syncthreads();
.LBB0_1640:
	s_and_b32 s40, s39, 2
	s_mulk_i32 s40, 0x4800
	v_add3_u32 v220, s40, v137, v164
	v_add3_u32 v221, s40, v165, v164
	ds_read_b128 v[200:203], v220 offset:0
	ds_read_b128 v[204:207], v221 offset:18432
	ds_read_b128 v[212:215], v220 offset:4608
	ds_read_b128 v[208:211], v221 offset:23040
	s_waitcnt lgkmcnt(2)
	v_mfma_f32_32x32x16_bf16 v[34:49], v[200:203], v[204:207], v[34:49]
	ds_read_b128 v[216:219], v220 offset:32
	s_waitcnt lgkmcnt(2)
	v_mfma_f32_32x32x16_bf16 v[18:33], v[212:215], v[204:207], v[18:33]
	ds_read_b128 v[204:207], v221 offset:18464
	s_waitcnt lgkmcnt(2)
	v_mfma_f32_32x32x16_bf16 v[2:17], v[200:203], v[208:211], v[2:17]
	ds_read_b128 v[200:203], v220 offset:4640
	v_mfma_f32_32x32x16_bf16 v[50:65], v[212:215], v[208:211], v[50:65]
	ds_read_b128 v[208:211], v221 offset:23072
	s_waitcnt lgkmcnt(2)
	v_mfma_f32_32x32x16_bf16 v[34:49], v[216:219], v[204:207], v[34:49]
	ds_read_b128 v[212:215], v220 offset:64
	s_waitcnt lgkmcnt(2)
	v_mfma_f32_32x32x16_bf16 v[18:33], v[200:203], v[204:207], v[18:33]
	ds_read_b128 v[204:207], v221 offset:18496
	s_waitcnt lgkmcnt(2)
	v_mfma_f32_32x32x16_bf16 v[2:17], v[216:219], v[208:211], v[2:17]
	ds_read_b128 v[216:219], v220 offset:4672
	v_mfma_f32_32x32x16_bf16 v[50:65], v[200:203], v[208:211], v[50:65]
	ds_read_b128 v[208:211], v221 offset:23104
	s_waitcnt lgkmcnt(2)
	v_mfma_f32_32x32x16_bf16 v[34:49], v[212:215], v[204:207], v[34:49]
	ds_read_b128 v[200:203], v220 offset:96
	s_waitcnt lgkmcnt(2)
	v_mfma_f32_32x32x16_bf16 v[18:33], v[216:219], v[204:207], v[18:33]
	ds_read_b128 v[204:207], v221 offset:18528
	s_waitcnt lgkmcnt(2)
	v_mfma_f32_32x32x16_bf16 v[2:17], v[212:215], v[208:211], v[2:17]
	ds_read_b128 v[212:215], v220 offset:4704
	v_mfma_f32_32x32x16_bf16 v[50:65], v[216:219], v[208:211], v[50:65]
	ds_read_b128 v[208:211], v221 offset:23136
	s_waitcnt lgkmcnt(2)
	v_mfma_f32_32x32x16_bf16 v[34:49], v[200:203], v[204:207], v[34:49]
	s_waitcnt lgkmcnt(1)
	v_mfma_f32_32x32x16_bf16 v[18:33], v[212:215], v[204:207], v[18:33]
	s_waitcnt lgkmcnt(0)
	v_mfma_f32_32x32x16_bf16 v[2:17], v[200:203], v[208:211], v[2:17]
	v_mfma_f32_32x32x16_bf16 v[50:65], v[212:215], v[208:211], v[50:65]
	s_add_i32 s39, s39, 2
	s_and_b32 s40, s39, 2
	s_mulk_i32 s40, 0x4800
	s_add_i32 s6, s6, -1
	v_add_u32_e32 v200, s40, v135
	v_lshl_add_u64 v[148:149], v[148:149], 0, s[8:9]
	v_lshl_add_u64 v[150:151], v[150:151], 0, s[8:9]
	v_lshl_add_u64 v[152:153], v[152:153], 0, s[8:9]
	v_lshl_add_u64 v[154:155], v[154:155], 0, s[8:9]
	v_lshl_add_u64 v[156:157], v[156:157], 0, s[8:9]
	v_lshl_add_u64 v[158:159], v[158:159], 0, s[8:9]
	v_lshl_add_u64 v[160:161], v[160:161], 0, s[8:9]
	v_lshl_add_u64 v[162:163], v[162:163], 0, s[8:9]
	s_cmp_lg_u32 s6, 0
	s_waitcnt vmcnt(7)
	ds_write_b128 v200, v[168:171]
	v_lshl_add_u64 v[168:169], v[148:149], 0, v[68:69]
	global_load_dwordx4 v[168:171], v[168:169], off offset:128
	s_waitcnt vmcnt(7)
	ds_write_b128 v200, v[172:175] offset:4608
	v_lshl_add_u64 v[172:173], v[150:151], 0, v[68:69]
	global_load_dwordx4 v[172:175], v[172:173], off offset:128
	s_waitcnt vmcnt(7)
	ds_write_b128 v200, v[176:179] offset:9216
	v_lshl_add_u64 v[176:177], v[152:153], 0, v[68:69]
	global_load_dwordx4 v[176:179], v[176:177], off offset:128
	s_waitcnt vmcnt(7)
	ds_write_b128 v200, v[180:183] offset:13824
	v_lshl_add_u64 v[180:181], v[154:155], 0, v[68:69]
	global_load_dwordx4 v[180:183], v[180:181], off offset:128
	s_waitcnt vmcnt(7)
	ds_write_b128 v200, v[184:187] offset:18432
	v_lshl_add_u64 v[184:185], v[156:157], 0, v[68:69]
	global_load_dwordx4 v[184:187], v[184:185], off offset:128
	s_waitcnt vmcnt(7)
	ds_write_b128 v200, v[188:191] offset:23040
	v_lshl_add_u64 v[188:189], v[158:159], 0, v[68:69]
	global_load_dwordx4 v[188:191], v[188:189], off offset:128
	s_waitcnt vmcnt(7)
	ds_write_b128 v200, v[192:195] offset:27648
	v_lshl_add_u64 v[192:193], v[160:161], 0, v[68:69]
	global_load_dwordx4 v[192:195], v[192:193], off offset:128
	s_waitcnt vmcnt(7)
	ds_write_b128 v200, v[196:199] offset:32256
	v_lshl_add_u64 v[196:197], v[162:163], 0, v[68:69]
	global_load_dwordx4 v[196:199], v[196:197], off offset:128
	s_waitcnt lgkmcnt(0)
	s_barrier
	s_cbranch_scc1 .LBB0_1640
	s_and_b32 s40, s39, 2
	s_mulk_i32 s40, 0x4800
	v_add3_u32 v220, s40, v137, v164
	v_add3_u32 v221, s40, v165, v164
	ds_read_b128 v[200:203], v220 offset:0
	ds_read_b128 v[204:207], v221 offset:18432
	ds_read_b128 v[212:215], v220 offset:4608
	ds_read_b128 v[208:211], v221 offset:23040
	s_waitcnt lgkmcnt(2)
	v_mfma_f32_32x32x16_bf16 v[34:49], v[200:203], v[204:207], v[34:49]
	ds_read_b128 v[216:219], v220 offset:32
	s_waitcnt lgkmcnt(2)
	v_mfma_f32_32x32x16_bf16 v[18:33], v[212:215], v[204:207], v[18:33]
	ds_read_b128 v[204:207], v221 offset:18464
	s_waitcnt lgkmcnt(2)
	v_mfma_f32_32x32x16_bf16 v[2:17], v[200:203], v[208:211], v[2:17]
	ds_read_b128 v[200:203], v220 offset:4640
	v_mfma_f32_32x32x16_bf16 v[50:65], v[212:215], v[208:211], v[50:65]
	ds_read_b128 v[208:211], v221 offset:23072
	s_waitcnt lgkmcnt(2)
	v_mfma_f32_32x32x16_bf16 v[34:49], v[216:219], v[204:207], v[34:49]
	ds_read_b128 v[212:215], v220 offset:64
	s_waitcnt lgkmcnt(2)
	v_mfma_f32_32x32x16_bf16 v[18:33], v[200:203], v[204:207], v[18:33]
	ds_read_b128 v[204:207], v221 offset:18496
	s_waitcnt lgkmcnt(2)
	v_mfma_f32_32x32x16_bf16 v[2:17], v[216:219], v[208:211], v[2:17]
	ds_read_b128 v[216:219], v220 offset:4672
	v_mfma_f32_32x32x16_bf16 v[50:65], v[200:203], v[208:211], v[50:65]
	ds_read_b128 v[208:211], v221 offset:23104
	s_waitcnt lgkmcnt(2)
	v_mfma_f32_32x32x16_bf16 v[34:49], v[212:215], v[204:207], v[34:49]
	ds_read_b128 v[200:203], v220 offset:96
	s_waitcnt lgkmcnt(2)
;     ...
;   for (int kt = 0; kt < nk; ++kt) {
;     const int kn = (kt + 1 < nk) ? kt + 1 : kt;
;     GM_LOAD2(kn * 64, kn * bkstep)
;     __builtin_amdgcn_sched_barrier(0);
;     const char* As = smem + (kt & 1) * 2 * TILE_B;
;     const char* Bs = As + TILE_B;
;     if constexpr (HOIST) {
;       bf16x8 fa0[4], fa1[4], fb0[4], fb1[4];
; #pragma unroll
;       for (int st = 0; st < 4; ++st) {
;         fa0[st] = *(const bf16x8*)(As + aoff + st * 32);
;         fb0[st] = *(const bf16x8*)(Bs + boff + st * 32);
;         fa1[st] = *(const bf16x8*)(As + aoff + 32 * LSTR + st * 32);
;         fb1[st] = *(const bf16x8*)(Bs + boff + 32 * LSTR + st * 32);
;       }
;       __builtin_amdgcn_sched_barrier(0);
; #pragma unroll
;       for (int st = 0; st < 4; ++st) {
;         acc[0][0] = mfma32(fa0[st], fb0[st], acc[0][0]);
;         acc[0][1] = mfma32(fa0[st], fb1[st], acc[0][1]);
;         acc[1][0] = mfma32(fa1[st], fb0[st], acc[1][0]);
;         acc[1][1] = mfma32(fa1[st], fb1[st], acc[1][1]);
;       }
;     } else {
; #pragma unroll
;       for (int st = 0; st < 4; ++st) {
;         bf16x8 a0 = *(const bf16x8*)(As + aoff + st * 32);
;         bf16x8 a1 = *(const bf16x8*)(As + aoff + 32 * LSTR + st * 32);
;         bf16x8 b0 = *(const bf16x8*)(Bs + boff + st * 32);
;         bf16x8 b1 = *(const bf16x8*)(Bs + boff + 32 * LSTR + st * 32);
;         acc[0][0] = mfma32(a0, b0, acc[0][0]);
;         acc[0][1] = mfma32(a0, b1, acc[0][1]);
;         acc[1][0] = mfma32(a1, b0, acc[1][0]);
;         acc[1][1] = mfma32(a1, b1, acc[1][1]);
;       }
;     }
;     __builtin_amdgcn_sched_barrier(0);
;     {
;       char* Ad = smem + ((kt + 1) & 1) * 2 * TILE_B;
;       GM_STORE(Ad)
;     }
;     __syncthreads();
; __device__ __forceinline__ void acc_to_lds(const f32x16 (&acc)[2][2], float* cs) {
;   const int tid = threadIdx.x, lane = tid & 63, wave = tid >> 6;
;   const int wm = wave >> 1, wn = wave & 1;
; #pragma unroll
;   for (int i = 0; i < 2; ++i)
; #pragma unroll
;     for (int j = 0; j < 2; ++j)
; #pragma unroll
;       for (int r = 0; r < 16; ++r) {
;         int row = wm * 64 + i * 32 + (r & 3) + 8 * (r >> 2) + 4 * (lane >> 5);
;         int col = wn * 64 + j * 32 + (lane & 31);
;         cs[row * CSTR + col] = acc[i][j][r];
;       }
;   __syncthreads();
	v_mfma_f32_32x32x16_bf16 v[18:33], v[216:219], v[204:207], v[18:33]
	ds_read_b128 v[204:207], v221 offset:18528
	s_waitcnt lgkmcnt(2)
	v_mfma_f32_32x32x16_bf16 v[2:17], v[212:215], v[208:211], v[2:17]
	ds_read_b128 v[212:215], v220 offset:4704
	v_mfma_f32_32x32x16_bf16 v[50:65], v[216:219], v[208:211], v[50:65]
	ds_read_b128 v[208:211], v221 offset:23136
	s_waitcnt lgkmcnt(2)
	v_mfma_f32_32x32x16_bf16 v[34:49], v[200:203], v[204:207], v[34:49]
	s_waitcnt lgkmcnt(1)
	v_mfma_f32_32x32x16_bf16 v[18:33], v[212:215], v[204:207], v[18:33]
	s_waitcnt lgkmcnt(0)
	v_mfma_f32_32x32x16_bf16 v[2:17], v[200:203], v[208:211], v[2:17]
	v_mfma_f32_32x32x16_bf16 v[50:65], v[212:215], v[208:211], v[50:65]
	s_add_i32 s39, s39, 2
	s_and_b32 s40, s39, 2
	s_mulk_i32 s40, 0x4800
	v_add_u32_e32 v200, s40, v135
	v_lshl_add_u64 v[148:149], v[148:149], 0, s[8:9]
	v_lshl_add_u64 v[150:151], v[150:151], 0, s[8:9]
	v_lshl_add_u64 v[152:153], v[152:153], 0, s[8:9]
	v_lshl_add_u64 v[154:155], v[154:155], 0, s[8:9]
	v_lshl_add_u64 v[156:157], v[156:157], 0, s[8:9]
	v_lshl_add_u64 v[158:159], v[158:159], 0, s[8:9]
	v_lshl_add_u64 v[160:161], v[160:161], 0, s[8:9]
	v_lshl_add_u64 v[162:163], v[162:163], 0, s[8:9]
	s_waitcnt vmcnt(7)
	ds_write_b128 v200, v[168:171]
	s_waitcnt vmcnt(6)
	ds_write_b128 v200, v[172:175] offset:4608
	s_waitcnt vmcnt(5)
	ds_write_b128 v200, v[176:179] offset:9216
	s_waitcnt vmcnt(4)
	ds_write_b128 v200, v[180:183] offset:13824
	s_waitcnt vmcnt(3)
	ds_write_b128 v200, v[184:187] offset:18432
	s_waitcnt vmcnt(2)
	ds_write_b128 v200, v[188:191] offset:23040
	s_waitcnt vmcnt(1)
	ds_write_b128 v200, v[192:195] offset:27648
	s_waitcnt vmcnt(0)
	ds_write_b128 v200, v[196:199] offset:32256
	s_waitcnt lgkmcnt(0)
	s_barrier
	v_lshl_add_u64 v[180:181], v[162:163], 0, v[68:69]
	v_lshl_add_u64 v[176:177], v[160:161], 0, v[68:69]
	v_lshl_add_u64 v[172:173], v[158:159], 0, v[68:69]
	v_lshl_add_u64 v[168:169], v[156:157], 0, v[68:69]
	v_lshl_add_u64 v[160:161], v[154:155], 0, v[68:69]
	v_lshl_add_u64 v[156:157], v[152:153], 0, v[68:69]
	v_lshl_add_u64 v[152:153], v[150:151], 0, v[68:69]
	v_lshl_add_u64 v[148:149], v[148:149], 0, v[68:69]
	s_nop 0
	s_nop 0
	s_nop 0
	s_nop 0
	s_nop 0
	s_nop 0
	s_nop 0
	v_add3_u32 v68, s40, v137, v164
	v_add3_u32 v212, s40, v165, v164
	ds_read_b128 v[184:187], v68 offset:0
	ds_read_b128 v[188:191], v212 offset:18432
	ds_read_b128 v[196:199], v68 offset:4608
	ds_read_b128 v[192:195], v212 offset:23040
	s_waitcnt lgkmcnt(2)
	v_mfma_f32_32x32x16_bf16 v[34:49], v[184:187], v[188:191], v[34:49]
	ds_read_b128 v[200:203], v68 offset:32
	s_waitcnt lgkmcnt(2)
	v_mfma_f32_32x32x16_bf16 v[18:33], v[196:199], v[188:191], v[18:33]
	ds_read_b128 v[188:191], v212 offset:18464
	s_waitcnt lgkmcnt(2)
	v_mfma_f32_32x32x16_bf16 v[2:17], v[184:187], v[192:195], v[2:17]
	ds_read_b128 v[184:187], v68 offset:4640
	v_mfma_f32_32x32x16_bf16 v[50:65], v[196:199], v[192:195], v[50:65]
	ds_read_b128 v[192:195], v212 offset:23072
	s_waitcnt lgkmcnt(2)
	v_mfma_f32_32x32x16_bf16 v[34:49], v[200:203], v[188:191], v[34:49]
	ds_read_b128 v[196:199], v68 offset:64
	s_waitcnt lgkmcnt(2)
	v_mfma_f32_32x32x16_bf16 v[18:33], v[184:187], v[188:191], v[18:33]
	ds_read_b128 v[188:191], v212 offset:18496
	s_waitcnt lgkmcnt(2)
	v_mfma_f32_32x32x16_bf16 v[2:17], v[200:203], v[192:195], v[2:17]
	ds_read_b128 v[200:203], v68 offset:4672
	v_mfma_f32_32x32x16_bf16 v[50:65], v[184:187], v[192:195], v[50:65]
	ds_read_b128 v[192:195], v212 offset:23104
	s_waitcnt lgkmcnt(2)
	v_mfma_f32_32x32x16_bf16 v[34:49], v[196:199], v[188:191], v[34:49]
	ds_read_b128 v[184:187], v68 offset:96
	s_waitcnt lgkmcnt(2)
	v_mfma_f32_32x32x16_bf16 v[18:33], v[200:203], v[188:191], v[18:33]
	ds_read_b128 v[188:191], v212 offset:18528
	s_waitcnt lgkmcnt(2)
	v_mfma_f32_32x32x16_bf16 v[2:17], v[196:199], v[192:195], v[2:17]
	ds_read_b128 v[196:199], v68 offset:4704
	v_mfma_f32_32x32x16_bf16 v[50:65], v[200:203], v[192:195], v[50:65]
	ds_read_b128 v[192:195], v212 offset:23136
	s_waitcnt lgkmcnt(2)
	v_mfma_f32_32x32x16_bf16 v[34:49], v[184:187], v[188:191], v[34:49]
	s_waitcnt lgkmcnt(1)
	v_mfma_f32_32x32x16_bf16 v[18:33], v[196:199], v[188:191], v[18:33]
	s_waitcnt lgkmcnt(0)
	v_mfma_f32_32x32x16_bf16 v[2:17], v[184:187], v[192:195], v[2:17]
	v_mfma_f32_32x32x16_bf16 v[50:65], v[196:199], v[192:195], v[50:65]
	s_waitcnt lgkmcnt(0)
	s_barrier
	ds_write2_b32 v166, v34, v2 offset1:32
	ds_write2_b32 v166, v35, v3 offset0:132 offset1:164
	v_add_u32_e32 v2, 0x400, v166
	ds_write2_b32 v2, v36, v4 offset0:8 offset1:40
	ds_write2_b32 v2, v37, v5 offset0:140 offset1:172
	v_add_u32_e32 v2, 0x1000, v166
	ds_write2_b32 v2, v38, v6 offset0:32 offset1:64
	ds_write2_b32 v2, v39, v7 offset0:164 offset1:196
	v_add_u32_e32 v2, 0x1400, v166
	ds_write2_b32 v2, v40, v8 offset0:40 offset1:72
	ds_write2_b32 v2, v41, v9 offset0:172 offset1:204
	v_add_u32_e32 v2, 0x2000, v166
	ds_write2_b32 v2, v42, v10 offset0:64 offset1:96
	ds_write2_b32 v2, v43, v11 offset0:196 offset1:228
	v_add_u32_e32 v2, 0x2400, v166
	ds_write2_b32 v2, v44, v12 offset0:72 offset1:104
	ds_write2_b32 v2, v45, v13 offset0:204 offset1:236
	v_add_u32_e32 v2, 0x3000, v166
	ds_write2_b32 v2, v46, v14 offset0:96 offset1:128
	v_add_u32_e32 v2, 0x3200, v166
	ds_write2_b32 v2, v47, v15 offset0:100 offset1:132
	v_add_u32_e32 v2, 0x3400, v166
	ds_write2_b32 v2, v48, v16 offset0:104 offset1:136
	v_add_u32_e32 v2, 0x3600, v166
	ds_write2_b32 v2, v49, v17 offset0:108 offset1:140
	v_add_u32_e32 v2, 0x4000, v166
	ds_write2_b32 v2, v18, v50 offset0:128 offset1:160
	v_add_u32_e32 v2, 0x4400, v166
	ds_write2_b32 v2, v19, v51 offset0:4 offset1:36
	ds_write2_b32 v2, v20, v52 offset0:136 offset1:168
	v_add_u32_e32 v2, 0x4800, v166
	ds_write2_b32 v2, v21, v53 offset0:12 offset1:44
	v_add_u32_e32 v2, 0x5000, v166
	ds_write2_b32 v2, v22, v54 offset0:160 offset1:192
	v_add_u32_e32 v2, 0x5400, v166
	ds_write2_b32 v2, v23, v55 offset0:36 offset1:68
	ds_write2_b32 v2, v24, v56 offset0:168 offset1:200
	v_add_u32_e32 v2, 0x5800, v166
	ds_write2_b32 v2, v25, v57 offset0:44 offset1:76
	v_add_u32_e32 v2, 0x6000, v166
	ds_write2_b32 v2, v26, v58 offset0:192 offset1:224
	v_add_u32_e32 v2, 0x6400, v166
	ds_write2_b32 v2, v27, v59 offset0:68 offset1:100
	ds_write2_b32 v2, v28, v60 offset0:200 offset1:232
	v_add_u32_e32 v2, 0x6800, v166
	ds_write2_b32 v2, v29, v61 offset0:76 offset1:108
	v_add_u32_e32 v2, 0x7200, v166
	ds_write2_b32 v2, v30, v62 offset0:96 offset1:128
	v_add_u32_e32 v2, 0x7400, v166
	ds_write2_b32 v2, v31, v63 offset0:100 offset1:132
	v_add_u32_e32 v2, 0x7600, v166
	s_lshl_b32 s6, s38, 11
	ds_write2_b32 v2, v32, v64 offset0:104 offset1:136
	v_add_u32_e32 v2, 0x7800, v166
	v_lshl_add_u64 v[46:47], v[118:119], 0, s[6:7]
	ds_write2_b32 v2, v33, v65 offset0:108 offset1:140
	s_waitcnt lgkmcnt(0)
	s_barrier
; __device__ __forceinline__ void merge_tile(const Params& P, int l, int mt, int nt, char* smem) {
;     ...
;     const u16* gp = WSP(u16, OFF_G) + grow * 3072 + br * 1024 + nt * 128 + half * 64;
; #pragma unroll
;     for (int q = 0; q < 8; ++q) {
;       uint4 gq = *(const uint4*)(gp + q * 8);
;       float4 a = *(const float4*)(cs + r * CSTR + half * 64 + q * 8);
;       float4 c = *(const float4*)(cs + r * CSTR + half * 64 + q * 8 + 4);
;       macc[q * 8 + 0] += __uint_as_float(gq.x << 16) * a.x;
;       macc[q * 8 + 1] += __uint_as_float(gq.x & 0xffff0000u) * a.y;
;       macc[q * 8 + 2] += __uint_as_float(gq.y << 16) * a.z;
;       macc[q * 8 + 3] += __uint_as_float(gq.y & 0xffff0000u) * a.w;
;       macc[q * 8 + 4] += __uint_as_float(gq.z << 16) * c.x;
;       macc[q * 8 + 5] += __uint_as_float(gq.z & 0xffff0000u) * c.y;
;       macc[q * 8 + 6] += __uint_as_float(gq.w << 16) * c.z;
;       macc[q * 8 + 7] += __uint_as_float(gq.w & 0xffff0000u) * c.w;
;     }
	global_load_dwordx4 v[2:5], v[46:47], off
	global_load_dwordx4 v[6:9], v[46:47], off offset:16
	global_load_dwordx4 v[10:13], v[46:47], off offset:32
	global_load_dwordx4 v[14:17], v[46:47], off offset:48
	global_load_dwordx4 v[18:21], v[46:47], off offset:64
	global_load_dwordx4 v[22:25], v[46:47], off offset:80
	ds_read_b128 v[26:29], v167
	ds_read_b128 v[30:33], v167 offset:16
	ds_read_b128 v[34:37], v167 offset:32
	ds_read_b128 v[38:41], v167 offset:48
	global_load_dwordx4 v[42:45], v[46:47], off offset:112
	s_nop 0
	global_load_dwordx4 v[46:49], v[46:47], off offset:96
	s_add_i32 s38, s38, 1
	s_cmp_lg_u32 s38, 3
	s_waitcnt vmcnt(7)
	v_lshlrev_b32_e32 v50, 16, v2
	v_and_b32_e32 v51, 0xffff0000, v2
	v_lshlrev_b32_e32 v2, 16, v3
	v_and_b32_e32 v3, 0xffff0000, v3
	s_waitcnt lgkmcnt(3)
	v_pk_fma_f32 v[144:145], v[28:29], v[2:3], v[144:145]
	v_lshlrev_b32_e32 v2, 16, v4
	v_and_b32_e32 v3, 0xffff0000, v4
	s_waitcnt lgkmcnt(2)
	v_pk_fma_f32 v[142:143], v[30:31], v[2:3], v[142:143]
	v_lshlrev_b32_e32 v2, 16, v5
	v_and_b32_e32 v3, 0xffff0000, v5
	v_pk_fma_f32 v[140:141], v[32:33], v[2:3], v[140:141]
	s_waitcnt vmcnt(6)
	v_lshlrev_b32_e32 v2, 16, v6
	v_and_b32_e32 v3, 0xffff0000, v6
	s_waitcnt lgkmcnt(1)
	v_pk_fma_f32 v[138:139], v[34:35], v[2:3], v[138:139]
	v_lshlrev_b32_e32 v2, 16, v7
	v_and_b32_e32 v3, 0xffff0000, v7
	v_pk_fma_f32 v[132:133], v[36:37], v[2:3], v[132:133]
	v_lshlrev_b32_e32 v2, 16, v8
	v_and_b32_e32 v3, 0xffff0000, v8
	s_waitcnt lgkmcnt(0)
	v_pk_fma_f32 v[130:131], v[38:39], v[2:3], v[130:131]
	ds_read_b128 v[2:5], v167 offset:64
	v_lshlrev_b32_e32 v6, 16, v9
	v_and_b32_e32 v7, 0xffff0000, v9
	v_pk_fma_f32 v[128:129], v[40:41], v[6:7], v[128:129]
	ds_read_b128 v[6:9], v167 offset:80
	v_pk_fma_f32 v[146:147], v[26:27], v[50:51], v[146:147]
	s_waitcnt vmcnt(5)
	v_lshlrev_b32_e32 v26, 16, v10
	v_and_b32_e32 v27, 0xffff0000, v10
	s_waitcnt lgkmcnt(1)
	v_pk_fma_f32 v[126:127], v[2:3], v[26:27], v[126:127]
	v_lshlrev_b32_e32 v2, 16, v11
	v_and_b32_e32 v3, 0xffff0000, v11
	v_pk_fma_f32 v[124:125], v[4:5], v[2:3], v[124:125]
	v_lshlrev_b32_e32 v2, 16, v12
	v_and_b32_e32 v3, 0xffff0000, v12
	s_waitcnt lgkmcnt(0)
	v_pk_fma_f32 v[122:123], v[6:7], v[2:3], v[122:123]
	ds_read_b128 v[2:5], v167 offset:96
	v_lshlrev_b32_e32 v6, 16, v13
	v_and_b32_e32 v7, 0xffff0000, v13
	v_pk_fma_f32 v[120:121], v[8:9], v[6:7], v[120:121]
	ds_read_b128 v[6:9], v167 offset:112
	s_waitcnt vmcnt(4)
	v_lshlrev_b32_e32 v10, 16, v14
	v_and_b32_e32 v11, 0xffff0000, v14
	s_waitcnt lgkmcnt(1)
	v_pk_fma_f32 v[116:117], v[2:3], v[10:11], v[116:117]
	v_lshlrev_b32_e32 v2, 16, v15
	v_and_b32_e32 v3, 0xffff0000, v15
	v_pk_fma_f32 v[114:115], v[4:5], v[2:3], v[114:115]
	v_lshlrev_b32_e32 v2, 16, v16
	v_and_b32_e32 v3, 0xffff0000, v16
	s_waitcnt lgkmcnt(0)
	v_pk_fma_f32 v[112:113], v[6:7], v[2:3], v[112:113]
	ds_read_b128 v[2:5], v167 offset:128
	v_lshlrev_b32_e32 v6, 16, v17
	v_and_b32_e32 v7, 0xffff0000, v17
	v_pk_fma_f32 v[110:111], v[8:9], v[6:7], v[110:111]
	ds_read_b128 v[6:9], v167 offset:144
	s_waitcnt vmcnt(3)
	v_lshlrev_b32_e32 v10, 16, v18
	v_and_b32_e32 v11, 0xffff0000, v18
	s_waitcnt lgkmcnt(1)
	v_pk_fma_f32 v[106:107], v[2:3], v[10:11], v[106:107]
	v_lshlrev_b32_e32 v2, 16, v19
	v_and_b32_e32 v3, 0xffff0000, v19
	v_pk_fma_f32 v[104:105], v[4:5], v[2:3], v[104:105]
	v_lshlrev_b32_e32 v2, 16, v20
	v_and_b32_e32 v3, 0xffff0000, v20
	s_waitcnt lgkmcnt(0)
	v_pk_fma_f32 v[102:103], v[6:7], v[2:3], v[102:103]
	ds_read_b128 v[2:5], v167 offset:160
	v_lshlrev_b32_e32 v6, 16, v21
	v_and_b32_e32 v7, 0xffff0000, v21
	v_pk_fma_f32 v[100:101], v[8:9], v[6:7], v[100:101]
	ds_read_b128 v[6:9], v167 offset:176
	s_waitcnt vmcnt(2)
	v_lshlrev_b32_e32 v10, 16, v22
	v_and_b32_e32 v11, 0xffff0000, v22
	s_waitcnt lgkmcnt(1)
	v_pk_fma_f32 v[98:99], v[2:3], v[10:11], v[98:99]
	v_lshlrev_b32_e32 v2, 16, v23
	v_and_b32_e32 v3, 0xffff0000, v23
	v_pk_fma_f32 v[96:97], v[4:5], v[2:3], v[96:97]
	v_lshlrev_b32_e32 v2, 16, v24
	v_and_b32_e32 v3, 0xffff0000, v24
	s_waitcnt lgkmcnt(0)
	v_pk_fma_f32 v[94:95], v[6:7], v[2:3], v[94:95]
	ds_read_b128 v[2:5], v167 offset:192
	v_lshlrev_b32_e32 v6, 16, v25
	v_and_b32_e32 v7, 0xffff0000, v25
	v_pk_fma_f32 v[92:93], v[8:9], v[6:7], v[92:93]
	ds_read_b128 v[6:9], v167 offset:208
	s_waitcnt vmcnt(0)
	v_lshlrev_b32_e32 v10, 16, v46
	v_and_b32_e32 v11, 0xffff0000, v46
	s_waitcnt lgkmcnt(1)
	v_pk_fma_f32 v[90:91], v[2:3], v[10:11], v[90:91]
	v_lshlrev_b32_e32 v2, 16, v47
	v_and_b32_e32 v3, 0xffff0000, v47
	v_pk_fma_f32 v[88:89], v[4:5], v[2:3], v[88:89]
	v_lshlrev_b32_e32 v2, 16, v48
	v_and_b32_e32 v3, 0xffff0000, v48
	s_waitcnt lgkmcnt(0)
	v_pk_fma_f32 v[86:87], v[6:7], v[2:3], v[86:87]
	ds_read_b128 v[2:5], v167 offset:224
	v_lshlrev_b32_e32 v6, 16, v49
	v_and_b32_e32 v7, 0xffff0000, v49
	v_pk_fma_f32 v[84:85], v[8:9], v[6:7], v[84:85]
	ds_read_b128 v[6:9], v167 offset:240
	v_lshlrev_b32_e32 v10, 16, v42
	v_and_b32_e32 v11, 0xffff0000, v42
	s_waitcnt lgkmcnt(1)
	v_pk_fma_f32 v[82:83], v[2:3], v[10:11], v[82:83]
	v_lshlrev_b32_e32 v2, 16, v43
	v_and_b32_e32 v3, 0xffff0000, v43
	v_pk_fma_f32 v[80:81], v[4:5], v[2:3], v[80:81]
	v_lshlrev_b32_e32 v2, 16, v44
	v_and_b32_e32 v3, 0xffff0000, v44
	s_waitcnt lgkmcnt(0)
	v_pk_fma_f32 v[78:79], v[6:7], v[2:3], v[78:79]
	v_lshlrev_b32_e32 v2, 16, v45
	v_and_b32_e32 v3, 0xffff0000, v45
	v_pk_fma_f32 v[76:77], v[8:9], v[2:3], v[76:77]
	s_barrier
; __device__ __forceinline__ void store_row64_bf16(const float* v, u16* dst) {
; #pragma unroll
;   for (int q = 0; q < 8; ++q) {
;     uint4 o;
;     o.x = pack2(v[q * 8 + 0], v[q * 8 + 1]);
;     o.y = pack2(v[q * 8 + 2], v[q * 8 + 3]);
;     o.z = pack2(v[q * 8 + 4], v[q * 8 + 5]);
;     o.w = pack2(v[q * 8 + 6], v[q * 8 + 7]);
;     *(uint4*)(dst + q * 8) = o;
;   }
; }
; __device__ __forceinline__ void merge_tile(const Params& P, int l, int mt, int nt, char* smem) {
;     ...
;   }
;   store_row64_bf16(macc, WSP(u16, OFF_M) + grow * DM + nt * 128 + half * 64);
	s_cbranch_scc1 .LBB0_1639
	v_lshlrev_b64 v[2:3], 11, v[108:109]
	v_lshl_add_u64 v[2:3], s[4:5], 0, v[2:3]
	v_lshl_add_u64 v[2:3], s[12:13], 1, v[2:3]
	v_mov_b32_e32 v75, v69
	v_lshl_add_u64 v[6:7], v[2:3], 0, v[74:75]
	v_cvt_pk_bf16_f32 v2, v146, v147
	v_cvt_pk_bf16_f32 v3, v144, v145
	v_cvt_pk_bf16_f32 v4, v142, v143
	v_cvt_pk_bf16_f32 v5, v140, v141
	global_store_dwordx4 v[6:7], v[2:5], off
	v_readlane_b32 s40, v253, 37
	v_readlane_b32 s48, v253, 45
	v_cvt_pk_bf16_f32 v2, v138, v139
	v_cvt_pk_bf16_f32 v3, v132, v133
	v_cvt_pk_bf16_f32 v4, v130, v131
	v_cvt_pk_bf16_f32 v5, v128, v129
	global_store_dwordx4 v[6:7], v[2:5], off offset:16
	v_readlane_b32 s49, v253, 46
	v_readlane_b32 s41, v253, 38
	v_cvt_pk_bf16_f32 v2, v126, v127
	v_cvt_pk_bf16_f32 v3, v124, v125
	v_cvt_pk_bf16_f32 v4, v122, v123
	v_cvt_pk_bf16_f32 v5, v120, v121
	global_store_dwordx4 v[6:7], v[2:5], off offset:32
	v_readlane_b32 s42, v253, 39
	v_readlane_b32 s43, v253, 40
	v_cvt_pk_bf16_f32 v2, v116, v117
	v_cvt_pk_bf16_f32 v3, v114, v115
	v_cvt_pk_bf16_f32 v4, v112, v113
	v_cvt_pk_bf16_f32 v5, v110, v111
	global_store_dwordx4 v[6:7], v[2:5], off offset:48
	v_readlane_b32 s44, v253, 41
	v_readlane_b32 s45, v253, 42
	v_cvt_pk_bf16_f32 v2, v106, v107
	v_cvt_pk_bf16_f32 v3, v104, v105
	v_cvt_pk_bf16_f32 v4, v102, v103
	v_cvt_pk_bf16_f32 v5, v100, v101
	global_store_dwordx4 v[6:7], v[2:5], off offset:64
	v_readlane_b32 s46, v253, 43
	v_readlane_b32 s47, v253, 44
	v_cvt_pk_bf16_f32 v2, v98, v99
	v_cvt_pk_bf16_f32 v3, v96, v97
	v_cvt_pk_bf16_f32 v4, v94, v95
	v_cvt_pk_bf16_f32 v5, v92, v93
	global_store_dwordx4 v[6:7], v[2:5], off offset:80
	v_readlane_b32 s50, v253, 47
	v_readlane_b32 s51, v253, 48
	v_cvt_pk_bf16_f32 v2, v90, v91
	v_cvt_pk_bf16_f32 v3, v88, v89
	v_cvt_pk_bf16_f32 v4, v86, v87
	v_cvt_pk_bf16_f32 v5, v84, v85
	global_store_dwordx4 v[6:7], v[2:5], off offset:96
	v_readlane_b32 s52, v253, 49
	v_readlane_b32 s53, v253, 50
	v_cvt_pk_bf16_f32 v2, v82, v83
	v_cvt_pk_bf16_f32 v3, v80, v81
	v_cvt_pk_bf16_f32 v4, v78, v79
	v_cvt_pk_bf16_f32 v5, v76, v77
	global_store_dwordx4 v[6:7], v[2:5], off offset:112
	v_readlane_b32 s54, v253, 51
	v_readlane_b32 s55, v253, 52
	s_branch .LBB0_1636
